# speedup vs baseline: 1.0003x; 1.0003x over previous
; #define PG8_STAGE(bufoff, gbase, voff) do { _Pragma("unroll") for (int _i = 0; _i < 2; ++_i) \
;     __builtin_amdgcn_global_load_lds((const unsigned*)((const char*)(gbase) + (voff)[_i]), (LAS unsigned*)(lds + (bufoff) + ldsw + _i * 8192), 16, 0, 0); } while (0)
; #define PG8_LDA(dst, b, h) do { _Pragma("unroll") for (int m = 0; m < 4; ++m) _Pragma("unroll") for (int k = 0; k < 2; ++k) dst[m][k] = *(const LAS bf16x8*)(lds + PG8_SA(b, h) + aoff + m * 2048 + k * 1024); } while (0)
; #define PG8_LDB(dst, b, h) do { _Pragma("unroll") for (int n = 0; n < 2; ++n) _Pragma("unroll") for (int k = 0; k < 2; ++k) dst[n][k] = *(const LAS bf16x8*)(lds + PG8_SB(b, h) + boff + n * 2048 + k * 1024); } while (0)
; #define PG8_MMA(ai, bj, At, Bt) do { __builtin_amdgcn_s_setprio(1); _Pragma("unroll") for (int m = 0; m < 4; ++m) _Pragma("unroll") for (int n = 0; n < 2; ++n) _Pragma("unroll") for (int k = 0; k < 2; ++k) \
;     acc[ai][bj][m][n] = __builtin_amdgcn_mfma_f32_16x16x32_bf16(Bt[n][k], At[m][k], acc[ai][bj][m][n], 0, 0, 0); __builtin_amdgcn_s_setprio(0); } while (0)
; #define PG8_WAIT_L(n) asm volatile("s_waitcnt lgkmcnt(" #n ")" ::: "memory")
; #define PG8_BAR __builtin_amdgcn_s_barrier()
; #define PG8_SCHED __builtin_amdgcn_sched_barrier(0)
; template <class Epi, bool SPLITA = false>
; __device__ __forceinline__ void gemm_phase(const int tid, LAS unsigned char* lds, const Gemm g, const Order& S, const Epi& E) {
;     ...
;   Acc acc;
; #pragma unroll
;   for (int a = 0; a < 2; ++a)
; #pragma unroll
;     for (int b = 0; b < 2; ++b)
; #pragma unroll
;       for (int m = 0; m < 4; ++m)
; #pragma unroll
;         for (int n = 0; n < 2; ++n) acc[a][b][m][n] = (f32x4){0.f, 0.f, 0.f, 0.f};
;     ...
;       PG8_LDB(B0, 0, 0); PG8_SCHED; PG8_LDA(At, 0, 0); PG8_STAGE(PG8_SA(1, 1), a1 + hstepA, voffA);
;       PG8_WAIT_L(8); PG8_BAR; PG8_WAIT_L(0); PG8_MMA(0, 0, At, B0); PG8_BAR; PG8_SCHED;
;       PG8_LDB(B1, 0, 1); PG8_STAGE(PG8_SB(0, 0), b2, voffB);
;       PG8_BAR; PG8_WAIT_L(0); PG8_MMA(0, 1, At, B1); PG8_BAR;
;       PG8_LDA(At, 0, 1); PG8_STAGE(PG8_SA(0, 0), a2, voffA);
;       PG8_BAR; PG8_WAIT_L(0); PG8_MMA(1, 0, At, B0); PG8_BAR; PG8_SCHED;
;       PG8_STAGE(PG8_SB(0, 1), b2 + hstepB, voffB);
.LBB0_56:
	s_add_u32 s6, s0, 0x80
	s_addc_u32 s7, s1, 0
	s_add_u32 s53, s16, 0x100
	s_addc_u32 s54, s17, 0
	s_add_u32 s16, s12, 0x160080
	s_addc_u32 s17, s13, 0
	v_mov_b32_e32 v2, 0
	v_lshl_add_u64 v[130:131], s[16:17], 0, v[156:157]
	v_lshl_add_u64 v[132:133], s[16:17], 0, v[158:159]
	s_mov_b32 s29, -2
	s_mov_b64 s[16:17], 0
	s_add_u32 s8, s12, s16
	s_addc_u32 s9, s13, s17
	s_add_u32 s20, s8, 0x100
	s_addc_u32 s21, s9, 0
	s_add_u32 s18, s53, s16
	s_addc_u32 s19, s54, s17
	s_add_u32 s8, s8, 0x180
	s_addc_u32 s9, s9, 0
	s_add_i32 s55, 0, 0x10000
	v_add_u32_e32 v146, s55, v172
	ds_read_b128 v[134:137], v146
	ds_read_b128 v[138:141], v146 offset:1024
	ds_read_b128 v[142:145], v146 offset:2048
	ds_read_b128 v[146:149], v146 offset:3072
	s_cmpk_eq_i32 s16, 0x2b00
	s_cselect_b32 s23, s7, s9
	s_cselect_b32 s22, s6, s8
	s_cselect_b32 s19, s11, s19
	s_cselect_b32 s18, s10, s18
	s_cselect_b32 s41, s1, s21
	s_cselect_b32 s40, s0, s20
	v_lshl_add_u64 v[168:169], v[130:131], 0, s[16:17]
	s_add_i32 m0, s4, 0xc000
	ds_read_b128 v[160:163], v173
	ds_read_b128 v[164:167], v173 offset:1024
	ds_read_b128 v[174:177], v173 offset:2048
	ds_read_b128 v[178:181], v173 offset:3072
	ds_read_b128 v[182:185], v173 offset:4096
	ds_read_b128 v[186:189], v173 offset:5120
	ds_read_b128 v[190:193], v173 offset:6144
	ds_read_b128 v[210:213], v173 offset:7168
	global_load_lds_dwordx4 v[168:169], off
	v_lshl_add_u64 v[168:169], v[132:133], 0, s[16:17]
	s_add_i32 m0, s4, 0xe000
	s_nop 0
	global_load_lds_dwordx4 v[168:169], off
	s_waitcnt lgkmcnt(8)
	s_barrier
	s_waitcnt lgkmcnt(0)
	s_setprio 1
	s_waitcnt lgkmcnt(0)
	v_mfma_f32_16x16x32_bf16 v[126:129], v[134:137], v[160:163], 0
	v_mfma_f32_16x16x32_bf16 v[122:125], v[142:145], v[160:163], 0
	v_mfma_f32_16x16x32_bf16 v[118:121], v[134:137], v[174:177], 0
	v_mfma_f32_16x16x32_bf16 v[114:117], v[142:145], v[174:177], 0
	v_mfma_f32_16x16x32_bf16 v[98:101], v[134:137], v[182:185], 0
	v_mfma_f32_16x16x32_bf16 v[90:93], v[142:145], v[182:185], 0
	v_mfma_f32_16x16x32_bf16 v[82:85], v[134:137], v[190:193], 0
	v_mfma_f32_16x16x32_bf16 v[74:77], v[142:145], v[190:193], 0
	v_mfma_f32_16x16x32_bf16 v[126:129], v[138:141], v[164:167], v[126:129]
	v_mfma_f32_16x16x32_bf16 v[122:125], v[146:149], v[164:167], v[122:125]
	v_mfma_f32_16x16x32_bf16 v[118:121], v[138:141], v[178:181], v[118:121]
	v_mfma_f32_16x16x32_bf16 v[114:117], v[146:149], v[178:181], v[114:117]
	v_mfma_f32_16x16x32_bf16 v[98:101], v[138:141], v[186:189], v[98:101]
	v_mfma_f32_16x16x32_bf16 v[90:93], v[146:149], v[186:189], v[90:93]
	v_mfma_f32_16x16x32_bf16 v[82:85], v[138:141], v[210:213], v[82:85]
	v_mfma_f32_16x16x32_bf16 v[74:77], v[146:149], v[210:213], v[74:77]
	s_setprio 0
	s_barrier
	s_add_i32 s8, 0, 0x14000
	v_add_u32_e32 v168, s8, v172
	s_add_i32 s9, s55, s3
	ds_read_b128 v[214:217], v168
	ds_read_b128 v[218:221], v168 offset:1024
	ds_read_b128 v[222:225], v168 offset:2048
	ds_read_b128 v[226:229], v168 offset:3072
	s_mov_b32 m0, s9
	s_nop 0
	global_load_lds_dwordx4 v0, s[18:19]
	s_add_i32 m0, s9, 0x2000
	s_nop 0
	global_load_lds_dwordx4 v150, s[18:19]
	s_barrier
	s_waitcnt lgkmcnt(0)
	s_setprio 1
	s_waitcnt lgkmcnt(0)
	v_mfma_f32_16x16x32_bf16 v[110:113], v[214:217], v[160:163], 0
	v_mfma_f32_16x16x32_bf16 v[106:109], v[222:225], v[160:163], 0
	v_mfma_f32_16x16x32_bf16 v[102:105], v[214:217], v[174:177], 0
	v_mfma_f32_16x16x32_bf16 v[94:97], v[222:225], v[174:177], 0
	v_mfma_f32_16x16x32_bf16 v[86:89], v[214:217], v[182:185], 0
	v_mfma_f32_16x16x32_bf16 v[78:81], v[222:225], v[182:185], 0
	v_mfma_f32_16x16x32_bf16 v[70:73], v[214:217], v[190:193], 0
	v_mfma_f32_16x16x32_bf16 v[66:69], v[222:225], v[190:193], 0
	v_mfma_f32_16x16x32_bf16 v[110:113], v[218:221], v[164:167], v[110:113]
	v_mfma_f32_16x16x32_bf16 v[106:109], v[226:229], v[164:167], v[106:109]
	v_mfma_f32_16x16x32_bf16 v[102:105], v[218:221], v[178:181], v[102:105]
	v_mfma_f32_16x16x32_bf16 v[94:97], v[226:229], v[178:181], v[94:97]
	v_mfma_f32_16x16x32_bf16 v[86:89], v[218:221], v[186:189], v[86:89]
	v_mfma_f32_16x16x32_bf16 v[78:81], v[226:229], v[186:189], v[78:81]
	v_mfma_f32_16x16x32_bf16 v[70:73], v[218:221], v[210:213], v[70:73]
	v_mfma_f32_16x16x32_bf16 v[66:69], v[226:229], v[210:213], v[66:69]
	s_setprio 0
	s_mov_b32 m0, s4
	s_barrier
	ds_read_b128 v[160:163], v173 offset:16384
	ds_read_b128 v[164:167], v173 offset:17408
	ds_read_b128 v[174:177], v173 offset:18432
	ds_read_b128 v[178:181], v173 offset:19456
	ds_read_b128 v[182:185], v173 offset:20480
	ds_read_b128 v[186:189], v173 offset:21504
	ds_read_b128 v[190:193], v173 offset:22528
	ds_read_b128 v[210:213], v173 offset:23552
	global_load_lds_dwordx4 v154, s[40:41]
	s_mov_b32 m0, s28
	s_nop 0
	global_load_lds_dwordx4 v152, s[40:41]
	s_barrier
	s_waitcnt lgkmcnt(0)
	s_setprio 1
	s_waitcnt lgkmcnt(0)
	v_mfma_f32_16x16x32_bf16 v[62:65], v[134:137], v[160:163], 0
	v_mfma_f32_16x16x32_bf16 v[58:61], v[142:145], v[160:163], 0
	v_mfma_f32_16x16x32_bf16 v[50:53], v[134:137], v[174:177], 0
	v_mfma_f32_16x16x32_bf16 v[42:45], v[142:145], v[174:177], 0
	v_mfma_f32_16x16x32_bf16 v[34:37], v[134:137], v[182:185], 0
	v_mfma_f32_16x16x32_bf16 v[26:29], v[142:145], v[182:185], 0
	v_mfma_f32_16x16x32_bf16 v[18:21], v[134:137], v[190:193], 0
	v_mfma_f32_16x16x32_bf16 v[10:13], v[142:145], v[190:193], 0
	v_mfma_f32_16x16x32_bf16 v[62:65], v[138:141], v[164:167], v[62:65]
	v_mfma_f32_16x16x32_bf16 v[58:61], v[146:149], v[164:167], v[58:61]
	v_mfma_f32_16x16x32_bf16 v[50:53], v[138:141], v[178:181], v[50:53]
	v_mfma_f32_16x16x32_bf16 v[42:45], v[146:149], v[178:181], v[42:45]
	v_mfma_f32_16x16x32_bf16 v[34:37], v[138:141], v[186:189], v[34:37]
	v_mfma_f32_16x16x32_bf16 v[26:29], v[146:149], v[186:189], v[26:29]
	v_mfma_f32_16x16x32_bf16 v[18:21], v[138:141], v[210:213], v[18:21]
	v_mfma_f32_16x16x32_bf16 v[10:13], v[146:149], v[210:213], v[10:13]
	s_setprio 0
	s_barrier
; #define PG8_STAGE(bufoff, gbase, voff) do { _Pragma("unroll") for (int _i = 0; _i < 2; ++_i) \
;     __builtin_amdgcn_global_load_lds((const unsigned*)((const char*)(gbase) + (voff)[_i]), (LAS unsigned*)(lds + (bufoff) + ldsw + _i * 8192), 16, 0, 0); } while (0)
; #define PG8_LDA(dst, b, h) do { _Pragma("unroll") for (int m = 0; m < 4; ++m) _Pragma("unroll") for (int k = 0; k < 2; ++k) dst[m][k] = *(const LAS bf16x8*)(lds + PG8_SA(b, h) + aoff + m * 2048 + k * 1024); } while (0)
; #define PG8_LDB(dst, b, h) do { _Pragma("unroll") for (int n = 0; n < 2; ++n) _Pragma("unroll") for (int k = 0; k < 2; ++k) dst[n][k] = *(const LAS bf16x8*)(lds + PG8_SB(b, h) + boff + n * 2048 + k * 1024); } while (0)
; #define PG8_MMA(ai, bj, At, Bt) do { __builtin_amdgcn_s_setprio(1); _Pragma("unroll") for (int m = 0; m < 4; ++m) _Pragma("unroll") for (int n = 0; n < 2; ++n) _Pragma("unroll") for (int k = 0; k < 2; ++k) \
;     acc[ai][bj][m][n] = __builtin_amdgcn_mfma_f32_16x16x32_bf16(Bt[n][k], At[m][k], acc[ai][bj][m][n], 0, 0, 0); __builtin_amdgcn_s_setprio(0); } while (0)
; #define PG8_WAIT_V(n) asm volatile("s_waitcnt vmcnt(" #n ")" ::: "memory")
; #define PG8_WAIT_L(n) asm volatile("s_waitcnt lgkmcnt(" #n ")" ::: "memory")
; #define PG8_BAR __builtin_amdgcn_s_barrier()
; #define PG8_SCHED __builtin_amdgcn_sched_barrier(0)
; template <class Epi, bool SPLITA = false>
; __device__ __forceinline__ void gemm_phase(const int tid, LAS unsigned char* lds, const Gemm g, const Order& S, const Epi& E) {
;     ...
;       PG8_STAGE(PG8_SB(0, 1), b2 + hstepB, voffB);
;       PG8_WAIT_V(6); PG8_BAR; PG8_MMA(1, 1, At, B1); PG8_BAR;
;       PG8_LDB(B0, 1, 0); PG8_SCHED; PG8_LDA(At, 1, 0); PG8_STAGE(PG8_SA(0, 1), a2 + hstepA, voffA);
;       PG8_WAIT_L(8); PG8_BAR; PG8_WAIT_L(0); PG8_MMA(0, 0, At, B0); PG8_BAR; PG8_SCHED;
;       PG8_LDB(B1, 1, 1); PG8_STAGE(PG8_SB(1, 0), b3, voffB);
;       PG8_BAR; PG8_WAIT_L(0); PG8_MMA(0, 1, At, B1); PG8_BAR;
;       PG8_LDA(At, 1, 1); PG8_STAGE(PG8_SA(1, 0), a3, voffA);
	s_add_u32 s20, s18, 0x160000
	s_addc_u32 s21, s19, 0
	s_add_i32 s8, s8, s3
	s_mov_b32 m0, s8
	s_nop 0
	global_load_lds_dwordx4 v0, s[20:21]
	s_add_i32 m0, s8, 0x2000
	s_nop 0
	global_load_lds_dwordx4 v150, s[20:21]
	s_waitcnt vmcnt(6)
	s_barrier
	s_setprio 1
	v_mfma_f32_16x16x32_bf16 v[54:57], v[214:217], v[160:163], 0
	v_mfma_f32_16x16x32_bf16 v[46:49], v[222:225], v[160:163], 0
	v_mfma_f32_16x16x32_bf16 v[38:41], v[214:217], v[174:177], 0
	v_mfma_f32_16x16x32_bf16 v[30:33], v[222:225], v[174:177], 0
	v_mfma_f32_16x16x32_bf16 v[22:25], v[214:217], v[182:185], 0
	v_mfma_f32_16x16x32_bf16 v[14:17], v[222:225], v[182:185], 0
	v_mfma_f32_16x16x32_bf16 v[6:9], v[214:217], v[190:193], 0
	v_mfma_f32_16x16x32_bf16 v[2:5], v[222:225], v[190:193], 0
	v_mfma_f32_16x16x32_bf16 v[54:57], v[218:221], v[164:167], v[54:57]
	v_mfma_f32_16x16x32_bf16 v[46:49], v[226:229], v[164:167], v[46:49]
	v_mfma_f32_16x16x32_bf16 v[38:41], v[218:221], v[178:181], v[38:41]
	v_mfma_f32_16x16x32_bf16 v[30:33], v[226:229], v[178:181], v[30:33]
	v_mfma_f32_16x16x32_bf16 v[22:25], v[218:221], v[186:189], v[22:25]
	v_mfma_f32_16x16x32_bf16 v[14:17], v[226:229], v[186:189], v[14:17]
	v_mfma_f32_16x16x32_bf16 v[6:9], v[218:221], v[210:213], v[6:9]
	v_mfma_f32_16x16x32_bf16 v[2:5], v[226:229], v[210:213], v[2:5]
	s_setprio 0
	s_add_i32 s8, 0, 0x18000
	v_add_u32_e32 v146, s8, v172
	s_barrier
	ds_read_b128 v[134:137], v146
	ds_read_b128 v[138:141], v146 offset:1024
	ds_read_b128 v[142:145], v146 offset:2048
	ds_read_b128 v[146:149], v146 offset:3072
	s_add_u32 s20, s40, 0x160000
	s_addc_u32 s21, s41, 0
	s_mov_b32 m0, s30
	ds_read_b128 v[160:163], v173 offset:32768
	ds_read_b128 v[164:167], v173 offset:33792
	ds_read_b128 v[174:177], v173 offset:34816
	ds_read_b128 v[178:181], v173 offset:35840
	ds_read_b128 v[182:185], v173 offset:36864
	ds_read_b128 v[186:189], v173 offset:37888
	ds_read_b128 v[190:193], v173 offset:38912
	ds_read_b128 v[210:213], v173 offset:39936
	global_load_lds_dwordx4 v154, s[20:21]
	s_mov_b32 m0, s31
	s_nop 0
	global_load_lds_dwordx4 v152, s[20:21]
	s_waitcnt lgkmcnt(8)
	s_barrier
	s_waitcnt lgkmcnt(0)
	s_setprio 1
	s_waitcnt lgkmcnt(0)
	v_mfma_f32_16x16x32_bf16 v[126:129], v[134:137], v[160:163], v[126:129]
	v_mfma_f32_16x16x32_bf16 v[122:125], v[142:145], v[160:163], v[122:125]
	v_mfma_f32_16x16x32_bf16 v[118:121], v[134:137], v[174:177], v[118:121]
	v_mfma_f32_16x16x32_bf16 v[114:117], v[142:145], v[174:177], v[114:117]
	v_mfma_f32_16x16x32_bf16 v[98:101], v[134:137], v[182:185], v[98:101]
	v_mfma_f32_16x16x32_bf16 v[90:93], v[142:145], v[182:185], v[90:93]
	v_mfma_f32_16x16x32_bf16 v[82:85], v[134:137], v[190:193], v[82:85]
	v_mfma_f32_16x16x32_bf16 v[74:77], v[142:145], v[190:193], v[74:77]
	v_mfma_f32_16x16x32_bf16 v[126:129], v[138:141], v[164:167], v[126:129]
	v_mfma_f32_16x16x32_bf16 v[122:125], v[146:149], v[164:167], v[122:125]
	v_mfma_f32_16x16x32_bf16 v[118:121], v[138:141], v[178:181], v[118:121]
	v_mfma_f32_16x16x32_bf16 v[114:117], v[146:149], v[178:181], v[114:117]
	v_mfma_f32_16x16x32_bf16 v[98:101], v[138:141], v[186:189], v[98:101]
	v_mfma_f32_16x16x32_bf16 v[90:93], v[146:149], v[186:189], v[90:93]
	v_mfma_f32_16x16x32_bf16 v[82:85], v[138:141], v[210:213], v[82:85]
	v_mfma_f32_16x16x32_bf16 v[74:77], v[146:149], v[210:213], v[74:77]
	s_setprio 0
	s_barrier
	s_add_i32 s9, 0, 0x1c000
	s_add_i32 s8, s8, s3
	v_add_u32_e32 v195, s9, v172
	s_add_i32 m0, s8, 0xffffff80
	ds_read_b128 v[214:217], v195
	ds_read_b128 v[218:221], v195 offset:1024
	ds_read_b128 v[222:225], v195 offset:2048
	ds_read_b128 v[226:229], v195 offset:3072
	global_load_lds_dwordx4 v0, s[18:19] offset:128
	s_add_i32 m0, s8, 0x1f80
	s_nop 0
	global_load_lds_dwordx4 v150, s[18:19] offset:128
	s_barrier
; #define PG8_STAGE(bufoff, gbase, voff) do { _Pragma("unroll") for (int _i = 0; _i < 2; ++_i) \
;     __builtin_amdgcn_global_load_lds((const unsigned*)((const char*)(gbase) + (voff)[_i]), (LAS unsigned*)(lds + (bufoff) + ldsw + _i * 8192), 16, 0, 0); } while (0)
; #define PG8_LDA(dst, b, h) do { _Pragma("unroll") for (int m = 0; m < 4; ++m) _Pragma("unroll") for (int k = 0; k < 2; ++k) dst[m][k] = *(const LAS bf16x8*)(lds + PG8_SA(b, h) + aoff + m * 2048 + k * 1024); } while (0)
; #define PG8_LDB(dst, b, h) do { _Pragma("unroll") for (int n = 0; n < 2; ++n) _Pragma("unroll") for (int k = 0; k < 2; ++k) dst[n][k] = *(const LAS bf16x8*)(lds + PG8_SB(b, h) + boff + n * 2048 + k * 1024); } while (0)
; #define PG8_MMA(ai, bj, At, Bt) do { __builtin_amdgcn_s_setprio(1); _Pragma("unroll") for (int m = 0; m < 4; ++m) _Pragma("unroll") for (int n = 0; n < 2; ++n) _Pragma("unroll") for (int k = 0; k < 2; ++k) \
;     acc[ai][bj][m][n] = __builtin_amdgcn_mfma_f32_16x16x32_bf16(Bt[n][k], At[m][k], acc[ai][bj][m][n], 0, 0, 0); __builtin_amdgcn_s_setprio(0); } while (0)
; #define PG8_WAIT_V(n) asm volatile("s_waitcnt vmcnt(" #n ")" ::: "memory")
; #define PG8_WAIT_L(n) asm volatile("s_waitcnt lgkmcnt(" #n ")" ::: "memory")
; #define PG8_BAR __builtin_amdgcn_s_barrier()
; #define PG8_SCHED __builtin_amdgcn_sched_barrier(0)
; template <class Epi, bool SPLITA = false>
; __device__ __forceinline__ void gemm_phase(const int tid, LAS unsigned char* lds, const Gemm g, const Order& S, const Epi& E) {
;     ...
;       PG8_LDB(B1, 1, 1); PG8_STAGE(PG8_SB(1, 0), b3, voffB);
;       PG8_BAR; PG8_WAIT_L(0); PG8_MMA(0, 1, At, B1); PG8_BAR;
;       PG8_LDA(At, 1, 1); PG8_STAGE(PG8_SA(1, 0), a3, voffA);
;       PG8_BAR; PG8_WAIT_L(0); PG8_MMA(1, 0, At, B0); PG8_BAR; PG8_SCHED;
;       PG8_STAGE(PG8_SB(1, 1), b3 + hstepB, voffB);
;       PG8_WAIT_V(6); PG8_BAR; PG8_MMA(1, 1, At, B1); PG8_BAR;
	s_waitcnt lgkmcnt(0)
	s_setprio 1
	s_waitcnt lgkmcnt(0)
	v_mfma_f32_16x16x32_bf16 v[110:113], v[214:217], v[160:163], v[110:113]
	v_mfma_f32_16x16x32_bf16 v[106:109], v[222:225], v[160:163], v[106:109]
	v_mfma_f32_16x16x32_bf16 v[102:105], v[214:217], v[174:177], v[102:105]
	v_mfma_f32_16x16x32_bf16 v[94:97], v[222:225], v[174:177], v[94:97]
	v_mfma_f32_16x16x32_bf16 v[86:89], v[214:217], v[182:185], v[86:89]
	v_mfma_f32_16x16x32_bf16 v[78:81], v[222:225], v[182:185], v[78:81]
	v_mfma_f32_16x16x32_bf16 v[70:73], v[214:217], v[190:193], v[70:73]
	v_mfma_f32_16x16x32_bf16 v[66:69], v[222:225], v[190:193], v[66:69]
	v_mfma_f32_16x16x32_bf16 v[110:113], v[218:221], v[164:167], v[110:113]
	v_mfma_f32_16x16x32_bf16 v[106:109], v[226:229], v[164:167], v[106:109]
	v_mfma_f32_16x16x32_bf16 v[102:105], v[218:221], v[178:181], v[102:105]
	v_mfma_f32_16x16x32_bf16 v[94:97], v[226:229], v[178:181], v[94:97]
	v_mfma_f32_16x16x32_bf16 v[86:89], v[218:221], v[186:189], v[86:89]
	v_mfma_f32_16x16x32_bf16 v[78:81], v[226:229], v[186:189], v[78:81]
	v_mfma_f32_16x16x32_bf16 v[70:73], v[218:221], v[210:213], v[70:73]
	v_mfma_f32_16x16x32_bf16 v[66:69], v[226:229], v[210:213], v[66:69]
	s_setprio 0
	s_mov_b32 m0, s44
	s_barrier
	ds_read_b128 v[160:163], v173 offset:49152
	ds_read_b128 v[164:167], v173 offset:50176
	ds_read_b128 v[174:177], v173 offset:51200
	ds_read_b128 v[178:181], v173 offset:52224
	ds_read_b128 v[182:185], v173 offset:53248
	ds_read_b128 v[186:189], v173 offset:54272
	ds_read_b128 v[190:193], v173 offset:55296
	ds_read_b128 v[210:213], v173 offset:56320
	global_load_lds_dwordx4 v154, s[22:23]
	s_mov_b32 m0, s45
	s_nop 0
	global_load_lds_dwordx4 v152, s[22:23]
	s_barrier
	s_waitcnt lgkmcnt(0)
	s_setprio 1
	s_waitcnt lgkmcnt(0)
	v_mfma_f32_16x16x32_bf16 v[62:65], v[134:137], v[160:163], v[62:65]
	v_mfma_f32_16x16x32_bf16 v[58:61], v[142:145], v[160:163], v[58:61]
	v_mfma_f32_16x16x32_bf16 v[50:53], v[134:137], v[174:177], v[50:53]
	v_mfma_f32_16x16x32_bf16 v[42:45], v[142:145], v[174:177], v[42:45]
	v_mfma_f32_16x16x32_bf16 v[34:37], v[134:137], v[182:185], v[34:37]
	v_mfma_f32_16x16x32_bf16 v[26:29], v[142:145], v[182:185], v[26:29]
	v_mfma_f32_16x16x32_bf16 v[18:21], v[134:137], v[190:193], v[18:21]
	v_mfma_f32_16x16x32_bf16 v[10:13], v[142:145], v[190:193], v[10:13]
	v_mfma_f32_16x16x32_bf16 v[62:65], v[138:141], v[164:167], v[62:65]
	v_mfma_f32_16x16x32_bf16 v[58:61], v[146:149], v[164:167], v[58:61]
	v_mfma_f32_16x16x32_bf16 v[50:53], v[138:141], v[178:181], v[50:53]
	v_mfma_f32_16x16x32_bf16 v[42:45], v[146:149], v[178:181], v[42:45]
	v_mfma_f32_16x16x32_bf16 v[34:37], v[138:141], v[186:189], v[34:37]
	v_mfma_f32_16x16x32_bf16 v[26:29], v[146:149], v[186:189], v[26:29]
	v_mfma_f32_16x16x32_bf16 v[18:21], v[138:141], v[210:213], v[18:21]
	v_mfma_f32_16x16x32_bf16 v[10:13], v[146:149], v[210:213], v[10:13]
	s_setprio 0
	s_barrier
	s_add_u32 s18, s18, 0x160080
	s_addc_u32 s19, s19, 0
	s_add_i32 s8, s9, s3
	s_mov_b32 m0, s8
	s_nop 0
	global_load_lds_dwordx4 v0, s[18:19]
	s_add_i32 m0, s8, 0x2000
	s_nop 0
	global_load_lds_dwordx4 v150, s[18:19]
	s_waitcnt vmcnt(6)
	s_barrier
	s_setprio 1
	v_mfma_f32_16x16x32_bf16 v[54:57], v[214:217], v[160:163], v[54:57]
	v_mfma_f32_16x16x32_bf16 v[46:49], v[222:225], v[160:163], v[46:49]
	v_mfma_f32_16x16x32_bf16 v[38:41], v[214:217], v[174:177], v[38:41]
	v_mfma_f32_16x16x32_bf16 v[30:33], v[222:225], v[174:177], v[30:33]
	v_mfma_f32_16x16x32_bf16 v[22:25], v[214:217], v[182:185], v[22:25]
	v_mfma_f32_16x16x32_bf16 v[14:17], v[222:225], v[182:185], v[14:17]
	v_mfma_f32_16x16x32_bf16 v[6:9], v[214:217], v[190:193], v[6:9]
	v_mfma_f32_16x16x32_bf16 v[2:5], v[222:225], v[190:193], v[2:5]
	v_mfma_f32_16x16x32_bf16 v[54:57], v[218:221], v[164:167], v[54:57]
	v_mfma_f32_16x16x32_bf16 v[46:49], v[226:229], v[164:167], v[46:49]
	v_mfma_f32_16x16x32_bf16 v[38:41], v[218:221], v[178:181], v[38:41]
	v_mfma_f32_16x16x32_bf16 v[30:33], v[226:229], v[178:181], v[30:33]
	v_mfma_f32_16x16x32_bf16 v[22:25], v[218:221], v[186:189], v[22:25]
	v_mfma_f32_16x16x32_bf16 v[14:17], v[226:229], v[186:189], v[14:17]
	v_mfma_f32_16x16x32_bf16 v[6:9], v[218:221], v[210:213], v[6:9]
	v_mfma_f32_16x16x32_bf16 v[2:5], v[226:229], v[210:213], v[2:5]
	s_setprio 0
	s_add_i32 s29, s29, 2
	s_add_u32 s16, s16, 0x100
	s_addc_u32 s17, s17, 0
	s_cmpk_gt_u32 s29, 0x55
	s_barrier
	s_cbranch_scc0 .LBB0_57
	s_branch .Lpeel_exit_57

; __device__ __forceinline__ float bflo(unsigned w) { return __uint_as_float(w << 16); }
; __device__ __forceinline__ float bfhi(unsigned w) { return __uint_as_float(w & 0xffff0000u); }
;   __device__ __forceinline__ void operator()(const Acc& acc, const Unit& u, int wr, int wc, int fr_, int fq_) const {
;     int fr = fr_, fq = fq_; asm volatile("" : "+v"(fr), "+v"(fq));
;     const int lane = fq * 16 + fr;
;     const int row0 = u.pm * BM + wr * 64 + fr, col0 = u.pn * BM + wc * 32 + 8 * fq;
; #pragma unroll
;     for (int ai = 0; ai < 2; ++ai) {
;       u32x4 hv[4][2];
; #pragma unroll
;       for (int m = 0; m < 4; ++m)
; #pragma unroll
;         for (int bj = 0; bj < 2; ++bj) hv[m][bj] = *(const u32x4*)(rin + (size_t)(row0 + ai * HALF + m * 16) * DM + col0 + bj * HALF);
; #pragma unroll
;       for (int m = 0; m < 4; ++m) { const size_t ro = (size_t)(row0 + ai * HALF + m * 16) * DM + col0; float ss = 0.f;
; #pragma unroll
;         for (int bj = 0; bj < 2; ++bj) { const u32x4 h = hv[m][bj];
;           f32x4 v0 = acc[ai][bj][m][0], v1 = acc[ai][bj][m][1];
;           v0[0] += bflo(h.x); v0[1] += bfhi(h.x); v0[2] += bflo(h.y); v0[3] += bfhi(h.y);
;           v1[0] += bflo(h.z); v1[1] += bfhi(h.z); v1[2] += bflo(h.w); v1[3] += bfhi(h.w);
;           if (FINAL) { *(f32x4*)(outf + ro + bj * HALF) = v0; *(f32x4*)(outf + ro + bj * HALF + 4) = v1; }
.Lpeel_exit_57:
	s_lshl_b32 s6, s51, 8
	v_mov_b32_e32 v130, v171
	v_mov_b32_e32 v131, v170
	s_add_i32 s6, s6, s42
	v_readlane_b32 s40, v255, 9
	v_add_u32_e32 v160, s6, v130
	s_lshl_b32 s6, s52, 8
	s_or_b32 s6, s6, s43
	v_lshl_add_u32 v186, v131, 3, s6
	v_readlane_b32 s6, v255, 5
	v_ashrrev_i32_e32 v187, 31, v186
	v_readlane_b32 s7, v255, 6
	v_ashrrev_i32_e32 v161, 31, v160
	v_lshlrev_b64 v[130:131], 12, v[160:161]
	v_lshl_add_u64 v[162:163], v[186:187], 1, s[6:7]
	v_lshl_add_u64 v[130:131], v[162:163], 0, v[130:131]
	global_load_dwordx4 v[174:177], v[130:131], off
	global_load_dwordx4 v[178:181], v[130:131], off offset:256
	v_add_u32_e32 v168, 16, v160
	v_ashrrev_i32_e32 v169, 31, v168
	v_lshlrev_b64 v[130:131], 12, v[168:169]
	v_lshl_add_u64 v[130:131], v[162:163], 0, v[130:131]
	global_load_dwordx4 v[182:185], v[130:131], off
	global_load_dwordx4 v[146:149], v[130:131], off offset:256
	v_add_u32_e32 v166, 32, v160
	v_ashrrev_i32_e32 v167, 31, v166
	v_lshlrev_b64 v[130:131], 12, v[166:167]
	v_lshl_add_u64 v[130:131], v[162:163], 0, v[130:131]
	global_load_dwordx4 v[142:145], v[130:131], off
	global_load_dwordx4 v[138:141], v[130:131], off offset:256
	v_add_u32_e32 v164, 48, v160
	v_ashrrev_i32_e32 v165, 31, v164
	v_lshlrev_b64 v[130:131], 12, v[164:165]
	v_lshl_add_u64 v[130:131], v[162:163], 0, v[130:131]
	global_load_dwordx4 v[134:137], v[130:131], off
	s_nop 0
	global_load_dwordx4 v[130:133], v[130:131], off offset:256
	s_and_b64 vcc, exec, s[38:39]
	s_mov_b32 s52, s48
	s_mov_b32 s51, s49
	s_mov_b64 s[16:17], s[10:11]
	s_mov_b64 s[12:13], s[0:1]
	s_mov_b64 s[20:21], s[34:35]
	v_readlane_b32 s41, v255, 10
	s_waitcnt vmcnt(0)
	v_lshlrev_b32_e32 v188, 16, v174
	v_and_b32_e32 v189, 0xffff0000, v174
	v_lshlrev_b32_e32 v174, 16, v175
	v_and_b32_e32 v175, 0xffff0000, v175
	v_pk_add_f32 v[128:129], v[128:129], v[174:175]
	v_lshlrev_b32_e32 v174, 16, v176
	v_and_b32_e32 v175, 0xffff0000, v176
	v_pk_add_f32 v[174:175], v[122:123], v[174:175]
	v_lshlrev_b32_e32 v122, 16, v177
	v_and_b32_e32 v123, 0xffff0000, v177
	v_pk_add_f32 v[176:177], v[124:125], v[122:123]
	v_lshlrev_b64 v[122:123], 13, v[160:161]
	v_lshl_add_u64 v[124:125], s[86:87], 0, v[122:123]
	v_lshlrev_b64 v[122:123], 2, v[186:187]
	v_pk_add_f32 v[126:127], v[126:127], v[188:189]
	v_lshl_add_u64 v[124:125], v[124:125], 0, v[122:123]
	global_store_dwordx4 v[124:125], v[126:129], off
	global_store_dwordx4 v[124:125], v[174:177], off offset:16
	s_nop 0
	v_lshlrev_b32_e32 v126, 16, v178
	v_and_b32_e32 v127, 0xffff0000, v178
	v_pk_add_f32 v[110:111], v[110:111], v[126:127]
	v_lshlrev_b32_e32 v126, 16, v179
	v_and_b32_e32 v127, 0xffff0000, v179
	v_pk_add_f32 v[112:113], v[112:113], v[126:127]
	v_lshlrev_b32_e32 v126, 16, v180
	v_and_b32_e32 v127, 0xffff0000, v180
	v_pk_add_f32 v[106:107], v[106:107], v[126:127]
	v_lshlrev_b32_e32 v126, 16, v181
	v_and_b32_e32 v127, 0xffff0000, v181
	v_pk_add_f32 v[108:109], v[108:109], v[126:127]
	global_store_dwordx4 v[124:125], v[110:113], off offset:512
	global_store_dwordx4 v[124:125], v[106:109], off offset:528
	s_nop 0
	v_lshlrev_b32_e32 v110, 16, v184
	v_and_b32_e32 v111, 0xffff0000, v184
	v_pk_add_f32 v[110:111], v[114:115], v[110:111]
	v_lshlrev_b64 v[114:115], 13, v[168:169]
	v_lshlrev_b32_e32 v106, 16, v182
	v_and_b32_e32 v107, 0xffff0000, v182
	v_lshlrev_b32_e32 v108, 16, v183
	v_and_b32_e32 v109, 0xffff0000, v183
	v_lshl_add_u64 v[114:115], s[86:87], 0, v[114:115]
	v_pk_add_f32 v[106:107], v[118:119], v[106:107]
	v_pk_add_f32 v[108:109], v[120:121], v[108:109]
	v_lshlrev_b32_e32 v112, 16, v185
	v_and_b32_e32 v113, 0xffff0000, v185
	v_lshl_add_u64 v[114:115], v[114:115], 0, v[122:123]
	v_pk_add_f32 v[112:113], v[116:117], v[112:113]
	global_store_dwordx4 v[114:115], v[106:109], off
	global_store_dwordx4 v[114:115], v[110:113], off offset:16
	s_nop 0
	v_lshlrev_b32_e32 v106, 16, v146
	v_and_b32_e32 v107, 0xffff0000, v146
	v_pk_add_f32 v[102:103], v[102:103], v[106:107]
	v_lshlrev_b32_e32 v106, 16, v147
	v_and_b32_e32 v107, 0xffff0000, v147
	v_pk_add_f32 v[104:105], v[104:105], v[106:107]
	v_lshlrev_b32_e32 v106, 16, v148
	v_and_b32_e32 v107, 0xffff0000, v148
	v_pk_add_f32 v[94:95], v[94:95], v[106:107]
	v_lshlrev_b32_e32 v106, 16, v149
	v_and_b32_e32 v107, 0xffff0000, v149
	v_pk_add_f32 v[96:97], v[96:97], v[106:107]
	global_store_dwordx4 v[114:115], v[102:105], off offset:512
	global_store_dwordx4 v[114:115], v[94:97], off offset:528
	s_nop 0
	v_add_u32_e32 v102, 0xa0, v160
	v_lshlrev_b32_e32 v94, 16, v142
	v_and_b32_e32 v95, 0xffff0000, v142
	v_pk_add_f32 v[94:95], v[98:99], v[94:95]
	v_lshlrev_b32_e32 v98, 16, v144
	v_and_b32_e32 v99, 0xffff0000, v144
	v_pk_add_f32 v[90:91], v[90:91], v[98:99]
	v_lshlrev_b32_e32 v98, 16, v145
	v_and_b32_e32 v99, 0xffff0000, v145
	v_pk_add_f32 v[92:93], v[92:93], v[98:99]
	v_lshlrev_b64 v[98:99], 13, v[166:167]
	v_lshlrev_b32_e32 v96, 16, v143
	v_and_b32_e32 v97, 0xffff0000, v143
	v_lshl_add_u64 v[98:99], s[86:87], 0, v[98:99]
	v_pk_add_f32 v[96:97], v[100:101], v[96:97]
	v_lshl_add_u64 v[98:99], v[98:99], 0, v[122:123]
	global_store_dwordx4 v[98:99], v[94:97], off
	global_store_dwordx4 v[98:99], v[90:93], off offset:16
	v_add_u32_e32 v100, 0x90, v160
	v_ashrrev_i32_e32 v101, 31, v100
	v_lshlrev_b32_e32 v90, 16, v138
	v_and_b32_e32 v91, 0xffff0000, v138
	v_pk_add_f32 v[86:87], v[86:87], v[90:91]
	v_lshlrev_b32_e32 v90, 16, v139
	v_and_b32_e32 v91, 0xffff0000, v139
	v_pk_add_f32 v[88:89], v[88:89], v[90:91]
	v_lshlrev_b32_e32 v90, 16, v140
	v_and_b32_e32 v91, 0xffff0000, v140
	v_pk_add_f32 v[78:79], v[78:79], v[90:91]
	v_lshlrev_b32_e32 v90, 16, v141
	v_and_b32_e32 v91, 0xffff0000, v141
; __device__ __forceinline__ float bflo(unsigned w) { return __uint_as_float(w << 16); }
; __device__ __forceinline__ float bfhi(unsigned w) { return __uint_as_float(w & 0xffff0000u); }
;   __device__ __forceinline__ void operator()(const Acc& acc, const Unit& u, int wr, int wc, int fr_, int fq_) const {
;     ...
;         for (int bj = 0; bj < 2; ++bj) hv[m][bj] = *(const u32x4*)(rin + (size_t)(row0 + ai * HALF + m * 16) * DM + col0 + bj * HALF);
; #pragma unroll
;       for (int m = 0; m < 4; ++m) { const size_t ro = (size_t)(row0 + ai * HALF + m * 16) * DM + col0; float ss = 0.f;
; #pragma unroll
;         for (int bj = 0; bj < 2; ++bj) { const u32x4 h = hv[m][bj];
;           f32x4 v0 = acc[ai][bj][m][0], v1 = acc[ai][bj][m][1];
;           v0[0] += bflo(h.x); v0[1] += bfhi(h.x); v0[2] += bflo(h.y); v0[3] += bfhi(h.y);
;           v1[0] += bflo(h.z); v1[1] += bfhi(h.z); v1[2] += bflo(h.w); v1[3] += bfhi(h.w);
;           if (FINAL) { *(f32x4*)(outf + ro + bj * HALF) = v0; *(f32x4*)(outf + ro + bj * HALF + 4) = v1; }
	v_pk_add_f32 v[80:81], v[80:81], v[90:91]
	global_store_dwordx4 v[98:99], v[86:89], off offset:512
	global_store_dwordx4 v[98:99], v[78:81], off offset:528
	v_add_u32_e32 v98, 0x80, v160
	v_ashrrev_i32_e32 v99, 31, v98
	v_lshlrev_b32_e32 v78, 16, v134
	v_and_b32_e32 v79, 0xffff0000, v134
	v_pk_add_f32 v[78:79], v[82:83], v[78:79]
	v_lshlrev_b32_e32 v82, 16, v136
	v_and_b32_e32 v83, 0xffff0000, v136
	v_pk_add_f32 v[74:75], v[74:75], v[82:83]
	v_lshlrev_b32_e32 v82, 16, v137
	v_and_b32_e32 v83, 0xffff0000, v137
	v_pk_add_f32 v[76:77], v[76:77], v[82:83]
	v_lshlrev_b64 v[82:83], 13, v[164:165]
	v_lshlrev_b32_e32 v80, 16, v135
	v_and_b32_e32 v81, 0xffff0000, v135
	v_lshl_add_u64 v[82:83], s[86:87], 0, v[82:83]
	v_pk_add_f32 v[80:81], v[84:85], v[80:81]
	v_lshl_add_u64 v[82:83], v[82:83], 0, v[122:123]
	global_store_dwordx4 v[82:83], v[78:81], off
	global_store_dwordx4 v[82:83], v[74:77], off offset:16
	v_ashrrev_i32_e32 v103, 31, v102
	v_add_u32_e32 v104, 0xb0, v160
	v_lshlrev_b32_e32 v74, 16, v130
	v_and_b32_e32 v75, 0xffff0000, v130
	v_pk_add_f32 v[70:71], v[70:71], v[74:75]
	v_lshlrev_b32_e32 v74, 16, v131
	v_and_b32_e32 v75, 0xffff0000, v131
	v_pk_add_f32 v[72:73], v[72:73], v[74:75]
	v_lshlrev_b32_e32 v74, 16, v132
	v_and_b32_e32 v75, 0xffff0000, v132
	v_pk_add_f32 v[66:67], v[66:67], v[74:75]
	v_lshlrev_b32_e32 v74, 16, v133
	v_and_b32_e32 v75, 0xffff0000, v133
	v_pk_add_f32 v[68:69], v[68:69], v[74:75]
	global_store_dwordx4 v[82:83], v[70:73], off offset:512
	global_store_dwordx4 v[82:83], v[66:69], off offset:528
	v_ashrrev_i32_e32 v105, 31, v104
	s_nop 0
	v_lshlrev_b64 v[66:67], 12, v[98:99]
	v_lshl_add_u64 v[66:67], v[162:163], 0, v[66:67]
	global_load_dwordx4 v[70:73], v[66:67], off
	global_load_dwordx4 v[74:77], v[66:67], off offset:256
	v_lshlrev_b64 v[66:67], 12, v[100:101]
	v_lshl_add_u64 v[66:67], v[162:163], 0, v[66:67]
	global_load_dwordx4 v[78:81], v[66:67], off
	global_load_dwordx4 v[82:85], v[66:67], off offset:256
	v_lshlrev_b64 v[66:67], 12, v[102:103]
	v_lshl_add_u64 v[66:67], v[162:163], 0, v[66:67]
	global_load_dwordx4 v[86:89], v[66:67], off
	global_load_dwordx4 v[90:93], v[66:67], off offset:256
	v_lshlrev_b64 v[66:67], 12, v[104:105]
	v_lshl_add_u64 v[66:67], v[162:163], 0, v[66:67]
	global_load_dwordx4 v[94:97], v[66:67], off
	s_nop 0
	global_load_dwordx4 v[66:69], v[66:67], off offset:256
	s_waitcnt vmcnt(0)
; __device__ __forceinline__ float bflo(unsigned w) { return __uint_as_float(w << 16); }
; __device__ __forceinline__ float bfhi(unsigned w) { return __uint_as_float(w & 0xffff0000u); }
; #define PG8_WAIT_V(n) asm volatile("s_waitcnt vmcnt(" #n ")" ::: "memory")
; #define PG8_BAR __builtin_amdgcn_s_barrier()
; __device__ __forceinline__ u32x4 pack8(const f32x4 v0, const f32x4 v1) { u32x4 w; w.x = cvtpk(v0[0], v0[1]); w.y = cvtpk(v0[2], v0[3]); w.z = cvtpk(v1[0], v1[1]); w.w = cvtpk(v1[2], v1[3]); return w; }
; template <class Epi, bool SPLITA = false>
; __device__ __forceinline__ void gemm_phase(const int tid, LAS unsigned char* lds, const Gemm g, const Order& S, const Epi& E) {
;     ...
;     E(acc, cur, wr, wc, fr, fq);
;     if (!has_next) break;
; #pragma unroll
;     for (int a = 0; a < 2; ++a)
; #pragma unroll
;       for (int b = 0; b < 2; ++b)
; #pragma unroll
;         for (int m = 0; m < 4; ++m)
; #pragma unroll
;           for (int n = 0; n < 2; ++n) acc[a][b][m][n] = (f32x4){0.f, 0.f, 0.f, 0.f};
;     cur = nxt; cA = nA; cA2 = nA2; cB = nB; ++ui;
;   }
;   PG8_WAIT_V(0);
;   if (wr == 0) PG8_BAR;
;   PG8_BAR;
;   __device__ __forceinline__ void operator()(const Acc& acc, const Unit& u, int wr, int wc, int fr_, int fq_) const {
;     ...
;         for (int bj = 0; bj < 2; ++bj) hv[m][bj] = *(const u32x4*)(rin + (size_t)(row0 + ai * HALF + m * 16) * DM + col0 + bj * HALF);
; #pragma unroll
;       for (int m = 0; m < 4; ++m) { const size_t ro = (size_t)(row0 + ai * HALF + m * 16) * DM + col0; float ss = 0.f;
; #pragma unroll
;         for (int bj = 0; bj < 2; ++bj) { const u32x4 h = hv[m][bj];
;           f32x4 v0 = acc[ai][bj][m][0], v1 = acc[ai][bj][m][1];
;           v0[0] += bflo(h.x); v0[1] += bfhi(h.x); v0[2] += bflo(h.y); v0[3] += bfhi(h.y);
;           v1[0] += bflo(h.z); v1[1] += bfhi(h.z); v1[2] += bflo(h.w); v1[3] += bfhi(h.w);
;           if (FINAL) { *(f32x4*)(outf + ro + bj * HALF) = v0; *(f32x4*)(outf + ro + bj * HALF + 4) = v1; }
;           else { ss += v0[0] * v0[0] + v0[1] * v0[1] + v0[2] * v0[2] + v0[3] * v0[3] + v1[0] * v1[0] + v1[1] * v1[1] + v1[2] * v1[2] + v1[3] * v1[3];
;             *(u32x4*)(outb + ro + bj * HALF) = pack8(v0, v1); } }
	v_lshlrev_b32_e32 v106, 16, v70
	v_and_b32_e32 v107, 0xffff0000, v70
	v_lshlrev_b32_e32 v70, 16, v71
	v_and_b32_e32 v71, 0xffff0000, v71
	v_pk_add_f32 v[64:65], v[64:65], v[70:71]
	v_lshlrev_b32_e32 v70, 16, v72
	v_and_b32_e32 v71, 0xffff0000, v72
	v_pk_add_f32 v[58:59], v[58:59], v[70:71]
	v_lshlrev_b32_e32 v70, 16, v73
	v_and_b32_e32 v71, 0xffff0000, v73
	v_pk_add_f32 v[60:61], v[60:61], v[70:71]
	v_lshlrev_b64 v[70:71], 13, v[98:99]
	v_lshl_add_u64 v[70:71], s[86:87], 0, v[70:71]
	v_pk_add_f32 v[62:63], v[62:63], v[106:107]
	v_lshl_add_u64 v[70:71], v[70:71], 0, v[122:123]
	global_store_dwordx4 v[70:71], v[62:65], off
	global_store_dwordx4 v[70:71], v[58:61], off offset:16
	s_nop 1
	v_lshlrev_b32_e32 v58, 16, v74
	v_and_b32_e32 v59, 0xffff0000, v74
	v_pk_add_f32 v[54:55], v[54:55], v[58:59]
	v_lshlrev_b32_e32 v58, 16, v75
	v_and_b32_e32 v59, 0xffff0000, v75
	v_pk_add_f32 v[56:57], v[56:57], v[58:59]
	v_lshlrev_b32_e32 v58, 16, v76
	v_and_b32_e32 v59, 0xffff0000, v76
	v_pk_add_f32 v[46:47], v[46:47], v[58:59]
	v_lshlrev_b32_e32 v58, 16, v77
	v_and_b32_e32 v59, 0xffff0000, v77
	v_pk_add_f32 v[48:49], v[48:49], v[58:59]
	global_store_dwordx4 v[70:71], v[54:57], off offset:512
	global_store_dwordx4 v[70:71], v[46:49], off offset:528
	s_nop 1
	v_lshlrev_b32_e32 v46, 16, v78
	v_and_b32_e32 v47, 0xffff0000, v78
	v_pk_add_f32 v[46:47], v[50:51], v[46:47]
	v_lshlrev_b32_e32 v50, 16, v80
	v_and_b32_e32 v51, 0xffff0000, v80
	v_pk_add_f32 v[42:43], v[42:43], v[50:51]
	v_lshlrev_b32_e32 v50, 16, v81
	v_and_b32_e32 v51, 0xffff0000, v81
	v_pk_add_f32 v[44:45], v[44:45], v[50:51]
	v_lshlrev_b64 v[50:51], 13, v[100:101]
	v_lshlrev_b32_e32 v48, 16, v79
	v_and_b32_e32 v49, 0xffff0000, v79
	v_lshl_add_u64 v[50:51], s[86:87], 0, v[50:51]
	v_pk_add_f32 v[48:49], v[52:53], v[48:49]
	v_lshl_add_u64 v[50:51], v[50:51], 0, v[122:123]
	global_store_dwordx4 v[50:51], v[46:49], off
	global_store_dwordx4 v[50:51], v[42:45], off offset:16
	s_nop 1
	v_lshlrev_b32_e32 v42, 16, v82
	v_and_b32_e32 v43, 0xffff0000, v82
	v_pk_add_f32 v[38:39], v[38:39], v[42:43]
	v_lshlrev_b32_e32 v42, 16, v83
	v_and_b32_e32 v43, 0xffff0000, v83
	v_pk_add_f32 v[40:41], v[40:41], v[42:43]
	v_lshlrev_b32_e32 v42, 16, v84
	v_and_b32_e32 v43, 0xffff0000, v84
	v_pk_add_f32 v[30:31], v[30:31], v[42:43]
	v_lshlrev_b32_e32 v42, 16, v85
	v_and_b32_e32 v43, 0xffff0000, v85
	v_pk_add_f32 v[32:33], v[32:33], v[42:43]
	global_store_dwordx4 v[50:51], v[38:41], off offset:512
	global_store_dwordx4 v[50:51], v[30:33], off offset:528
	s_nop 1
	v_lshlrev_b32_e32 v30, 16, v86
	v_and_b32_e32 v31, 0xffff0000, v86
	v_pk_add_f32 v[30:31], v[34:35], v[30:31]
	v_lshlrev_b32_e32 v34, 16, v88
	v_and_b32_e32 v35, 0xffff0000, v88
	v_pk_add_f32 v[26:27], v[26:27], v[34:35]
	v_lshlrev_b32_e32 v34, 16, v89
	v_and_b32_e32 v35, 0xffff0000, v89
	v_pk_add_f32 v[28:29], v[28:29], v[34:35]
	v_lshlrev_b64 v[34:35], 13, v[102:103]
	v_lshlrev_b32_e32 v32, 16, v87
	v_and_b32_e32 v33, 0xffff0000, v87
	v_lshl_add_u64 v[34:35], s[86:87], 0, v[34:35]
	v_pk_add_f32 v[32:33], v[36:37], v[32:33]
	v_lshl_add_u64 v[34:35], v[34:35], 0, v[122:123]
	global_store_dwordx4 v[34:35], v[30:33], off
	global_store_dwordx4 v[34:35], v[26:29], off offset:16
	s_nop 1
	v_lshlrev_b32_e32 v26, 16, v90
	v_and_b32_e32 v27, 0xffff0000, v90
	v_pk_add_f32 v[22:23], v[22:23], v[26:27]
	v_lshlrev_b32_e32 v26, 16, v91
	v_and_b32_e32 v27, 0xffff0000, v91
	v_pk_add_f32 v[24:25], v[24:25], v[26:27]
	v_lshlrev_b32_e32 v26, 16, v92
	v_and_b32_e32 v27, 0xffff0000, v92
	v_pk_add_f32 v[14:15], v[14:15], v[26:27]
	v_lshlrev_b32_e32 v26, 16, v93
	v_and_b32_e32 v27, 0xffff0000, v93
	v_pk_add_f32 v[16:17], v[16:17], v[26:27]
	global_store_dwordx4 v[34:35], v[22:25], off offset:512
	global_store_dwordx4 v[34:35], v[14:17], off offset:528
	s_nop 1
	v_lshlrev_b32_e32 v14, 16, v94
	v_and_b32_e32 v15, 0xffff0000, v94
	v_pk_add_f32 v[14:15], v[18:19], v[14:15]
	v_lshlrev_b32_e32 v18, 16, v96
	v_and_b32_e32 v19, 0xffff0000, v96
	v_pk_add_f32 v[10:11], v[10:11], v[18:19]
	v_lshlrev_b32_e32 v18, 16, v97
	v_and_b32_e32 v19, 0xffff0000, v97
	v_pk_add_f32 v[12:13], v[12:13], v[18:19]
	v_lshlrev_b64 v[18:19], 13, v[104:105]
	v_lshlrev_b32_e32 v16, 16, v95
	v_and_b32_e32 v17, 0xffff0000, v95
	v_lshl_add_u64 v[18:19], s[86:87], 0, v[18:19]
	v_pk_add_f32 v[16:17], v[20:21], v[16:17]
	v_lshl_add_u64 v[18:19], v[18:19], 0, v[122:123]
	global_store_dwordx4 v[18:19], v[14:17], off
	global_store_dwordx4 v[18:19], v[10:13], off offset:16
	s_nop 1
	v_lshlrev_b32_e32 v10, 16, v66
	v_and_b32_e32 v11, 0xffff0000, v66
	v_pk_add_f32 v[6:7], v[6:7], v[10:11]
	v_lshlrev_b32_e32 v10, 16, v67
	v_and_b32_e32 v11, 0xffff0000, v67
	v_pk_add_f32 v[8:9], v[8:9], v[10:11]
	v_lshlrev_b32_e32 v10, 16, v68
	v_and_b32_e32 v11, 0xffff0000, v68
	v_pk_add_f32 v[2:3], v[2:3], v[10:11]
	v_lshlrev_b32_e32 v10, 16, v69
	v_and_b32_e32 v11, 0xffff0000, v69
	v_pk_add_f32 v[4:5], v[4:5], v[10:11]
	global_store_dwordx4 v[18:19], v[6:9], off offset:512
	global_store_dwordx4 v[18:19], v[2:5], off offset:528
	s_cbranch_vccz .LBB0_46
	s_waitcnt vmcnt(0)
	v_mov_b32_e32 v219, v196
	s_cmpk_gt_u32 s2, 0xff
	s_cbranch_scc1 .LBB0_61
	s_barrier

; #define PG8_STAGE(bufoff, gbase, voff) do { _Pragma("unroll") for (int _i = 0; _i < 2; ++_i) \
;     __builtin_amdgcn_global_load_lds((const unsigned*)((const char*)(gbase) + (voff)[_i]), (LAS unsigned*)(lds + (bufoff) + ldsw + _i * 8192), 16, 0, 0); } while (0)
; #define PG8_LDA(dst, b, h) do { _Pragma("unroll") for (int m = 0; m < 4; ++m) _Pragma("unroll") for (int k = 0; k < 2; ++k) dst[m][k] = *(const LAS bf16x8*)(lds + PG8_SA(b, h) + aoff + m * 2048 + k * 1024); } while (0)
; #define PG8_WAIT_V(n) asm volatile("s_waitcnt vmcnt(" #n ")" ::: "memory")
; #define PG8_WAIT_L(n) asm volatile("s_waitcnt lgkmcnt(" #n ")" ::: "memory")
; template <class Epi, bool SPLITA = false>
; __device__ __forceinline__ void gemm_phase(const int tid, LAS unsigned char* lds, const Gemm g, const Order& S, const Epi& E) {
;     ...
;   Acc acc;
; #pragma unroll
;   for (int a = 0; a < 2; ++a)
; #pragma unroll
;     for (int b = 0; b < 2; ++b)
; #pragma unroll
;       for (int m = 0; m < 4; ++m)
; #pragma unroll
;         for (int n = 0; n < 2; ++n) acc[a][b][m][n] = (f32x4){0.f, 0.f, 0.f, 0.f};
;     ...
;     const bool has_next = S.next(ui + 1, nxt);
;     const char* nA = has_next ? (const char*)g.A + (size_t)nxt.pm * tstepA + (size_t)nxt.pn * apn : cA; const char* nA2 = (SPLITA && has_next) ? (const char*)g.A2 + (size_t)nxt.pm * tstepA : cA2; const char* nB = has_next ? (const char*)g.Bt + (size_t)nxt.pn * tstepB : cB;
;     for (int t = 0; t < nt; t += 2) {
;       const bool last = (t == nt - 2);
;       if constexpr (SPLITA) { if (t == nt1) E.mid(acc, cur, wr, wc, fr, fq); }
;       const char* a1 = PG8_TA(t + 1);
;       const char* a2 = last ? nA : PG8_TA(t + 2); const char* b2 = last ? nB : cB + (size_t)(t + 2) * kstep;
;       const char* a3 = last ? nA + kstep : PG8_TA(t + 3); const char* b3 = b2 + kstep;
;       PG8_LDB(B0, 0, 0); PG8_SCHED; PG8_LDA(At, 0, 0); PG8_STAGE(PG8_SA(1, 1), a1 + hstepA, voffA);
;       PG8_WAIT_L(8); PG8_BAR; PG8_WAIT_L(0); PG8_MMA(0, 0, At, B0); PG8_BAR; PG8_SCHED;
;       PG8_LDB(B1, 0, 1); PG8_STAGE(PG8_SB(0, 0), b2, voffB);
;       PG8_BAR; PG8_WAIT_L(0); PG8_MMA(0, 1, At, B1); PG8_BAR;
;       PG8_LDA(At, 0, 1); PG8_STAGE(PG8_SA(0, 0), a2, voffA);
;       PG8_BAR; PG8_WAIT_L(0); PG8_MMA(1, 0, At, B0); PG8_BAR; PG8_SCHED;
;       PG8_STAGE(PG8_SB(0, 1), b2 + hstepB, voffB);
;       PG8_WAIT_V(6); PG8_BAR; PG8_MMA(1, 1, At, B1); PG8_BAR;
.LBB0_86:
	s_add_u32 s6, s0, 0x80
	s_addc_u32 s7, s1, 0
	s_add_u32 s54, s16, 0x100
	s_addc_u32 s55, s17, 0
	s_add_u32 s16, s12, 0x160080
	s_addc_u32 s17, s13, 0
	v_mov_b32_e32 v2, 0
	v_lshl_add_u64 v[130:131], s[16:17], 0, v[164:165]
	v_lshl_add_u64 v[132:133], s[16:17], 0, v[166:167]
	s_mov_b32 s29, -2
	s_mov_b64 s[16:17], 0
	s_waitcnt lgkmcnt(0)
	s_add_u32 s8, s12, s16
	s_addc_u32 s9, s13, s17
	s_add_u32 s20, s8, 0x100
	s_addc_u32 s21, s9, 0
	s_add_u32 s18, s54, s16
	s_addc_u32 s19, s55, s17
	s_add_u32 s8, s8, 0x180
	s_addc_u32 s9, s9, 0
	s_add_i32 s90, 0, 0x10000
	v_add_u32_e32 v146, s90, v188
	ds_read_b128 v[134:137], v146
	ds_read_b128 v[138:141], v146 offset:1024
	ds_read_b128 v[142:145], v146 offset:2048
	ds_read_b128 v[146:149], v146 offset:3072
	s_cmpk_eq_i32 s16, 0x2b00
	s_cselect_b32 s23, s7, s9
	s_cselect_b32 s22, s6, s8
	s_cselect_b32 s19, s11, s19
	s_cselect_b32 s18, s10, s18
	s_cselect_b32 s41, s1, s21
	s_cselect_b32 s40, s0, s20
	v_lshl_add_u64 v[184:185], v[130:131], 0, s[16:17]
	s_add_i32 m0, s30, 0xc000
	ds_read_b128 v[150:153], v189
	ds_read_b128 v[154:157], v189 offset:1024
	ds_read_b128 v[168:171], v189 offset:2048
	ds_read_b128 v[172:175], v189 offset:3072
	ds_read_b128 v[176:179], v189 offset:4096
	ds_read_b128 v[180:183], v189 offset:5120
	ds_read_b128 v[190:193], v189 offset:6144
	ds_read_b128 v[212:215], v189 offset:7168
	global_load_lds_dwordx4 v[184:185], off
	v_lshl_add_u64 v[184:185], v[132:133], 0, s[16:17]
	s_add_i32 m0, s30, 0xe000
	s_nop 0
	global_load_lds_dwordx4 v[184:185], off
	s_waitcnt lgkmcnt(8)
	s_barrier
	s_waitcnt lgkmcnt(0)
	s_setprio 1
	s_waitcnt lgkmcnt(0)
	v_mfma_f32_16x16x32_bf16 v[126:129], v[134:137], v[150:153], 0
	v_mfma_f32_16x16x32_bf16 v[122:125], v[142:145], v[150:153], 0
	v_mfma_f32_16x16x32_bf16 v[110:113], v[134:137], v[168:171], 0
	v_mfma_f32_16x16x32_bf16 v[106:109], v[142:145], v[168:171], 0
	v_mfma_f32_16x16x32_bf16 v[94:97], v[134:137], v[176:179], 0
	v_mfma_f32_16x16x32_bf16 v[90:93], v[142:145], v[176:179], 0
	v_mfma_f32_16x16x32_bf16 v[78:81], v[134:137], v[190:193], 0
	v_mfma_f32_16x16x32_bf16 v[74:77], v[142:145], v[190:193], 0
	v_mfma_f32_16x16x32_bf16 v[126:129], v[138:141], v[154:157], v[126:129]
	v_mfma_f32_16x16x32_bf16 v[122:125], v[146:149], v[154:157], v[122:125]
	v_mfma_f32_16x16x32_bf16 v[110:113], v[138:141], v[172:175], v[110:113]
	v_mfma_f32_16x16x32_bf16 v[106:109], v[146:149], v[172:175], v[106:109]
	v_mfma_f32_16x16x32_bf16 v[94:97], v[138:141], v[180:183], v[94:97]
	v_mfma_f32_16x16x32_bf16 v[90:93], v[146:149], v[180:183], v[90:93]
	v_mfma_f32_16x16x32_bf16 v[78:81], v[138:141], v[212:215], v[78:81]
	v_mfma_f32_16x16x32_bf16 v[74:77], v[146:149], v[212:215], v[74:77]
	s_setprio 0
	s_barrier
	s_add_i32 s8, 0, 0x14000
	v_add_u32_e32 v184, s8, v188
	s_add_i32 s9, s90, s3
	ds_read_b128 v[216:219], v184
	ds_read_b128 v[220:223], v184 offset:1024
	ds_read_b128 v[224:227], v184 offset:2048
	ds_read_b128 v[228:231], v184 offset:3072
	s_mov_b32 m0, s9
	s_nop 0
	global_load_lds_dwordx4 v0, s[18:19]
	s_add_i32 m0, s9, 0x2000
	s_nop 0
	global_load_lds_dwordx4 v162, s[18:19]
	s_barrier
	s_waitcnt lgkmcnt(0)
	s_setprio 1
	s_waitcnt lgkmcnt(0)
	v_mfma_f32_16x16x32_bf16 v[118:121], v[216:219], v[150:153], 0
	v_mfma_f32_16x16x32_bf16 v[114:117], v[224:227], v[150:153], 0
	v_mfma_f32_16x16x32_bf16 v[102:105], v[216:219], v[168:171], 0
	v_mfma_f32_16x16x32_bf16 v[98:101], v[224:227], v[168:171], 0
	v_mfma_f32_16x16x32_bf16 v[86:89], v[216:219], v[176:179], 0
	v_mfma_f32_16x16x32_bf16 v[82:85], v[224:227], v[176:179], 0
	v_mfma_f32_16x16x32_bf16 v[70:73], v[216:219], v[190:193], 0
	v_mfma_f32_16x16x32_bf16 v[66:69], v[224:227], v[190:193], 0
	v_mfma_f32_16x16x32_bf16 v[118:121], v[220:223], v[154:157], v[118:121]
	v_mfma_f32_16x16x32_bf16 v[114:117], v[228:231], v[154:157], v[114:117]
	v_mfma_f32_16x16x32_bf16 v[102:105], v[220:223], v[172:175], v[102:105]
	v_mfma_f32_16x16x32_bf16 v[98:101], v[228:231], v[172:175], v[98:101]
	v_mfma_f32_16x16x32_bf16 v[86:89], v[220:223], v[180:183], v[86:89]
	v_mfma_f32_16x16x32_bf16 v[82:85], v[228:231], v[180:183], v[82:85]
	v_mfma_f32_16x16x32_bf16 v[70:73], v[220:223], v[212:215], v[70:73]
	v_mfma_f32_16x16x32_bf16 v[66:69], v[228:231], v[212:215], v[66:69]
	s_setprio 0
	s_mov_b32 m0, s30
	s_barrier
	ds_read_b128 v[150:153], v189 offset:16384
	ds_read_b128 v[154:157], v189 offset:17408
	ds_read_b128 v[168:171], v189 offset:18432
	ds_read_b128 v[172:175], v189 offset:19456
	ds_read_b128 v[176:179], v189 offset:20480
	ds_read_b128 v[180:183], v189 offset:21504
	ds_read_b128 v[190:193], v189 offset:22528
	ds_read_b128 v[212:215], v189 offset:23552
	global_load_lds_dwordx4 v158, s[40:41]
	s_mov_b32 m0, s31
	s_nop 0
	global_load_lds_dwordx4 v160, s[40:41]
	s_barrier
	s_waitcnt lgkmcnt(0)
	s_setprio 1
	s_waitcnt lgkmcnt(0)
	v_mfma_f32_16x16x32_bf16 v[62:65], v[134:137], v[150:153], 0
	v_mfma_f32_16x16x32_bf16 v[58:61], v[142:145], v[150:153], 0
	v_mfma_f32_16x16x32_bf16 v[46:49], v[134:137], v[168:171], 0
	v_mfma_f32_16x16x32_bf16 v[42:45], v[142:145], v[168:171], 0
	v_mfma_f32_16x16x32_bf16 v[30:33], v[134:137], v[176:179], 0
	v_mfma_f32_16x16x32_bf16 v[26:29], v[142:145], v[176:179], 0
	v_mfma_f32_16x16x32_bf16 v[14:17], v[134:137], v[190:193], 0
	v_mfma_f32_16x16x32_bf16 v[10:13], v[142:145], v[190:193], 0
	v_mfma_f32_16x16x32_bf16 v[62:65], v[138:141], v[154:157], v[62:65]
	v_mfma_f32_16x16x32_bf16 v[58:61], v[146:149], v[154:157], v[58:61]
	v_mfma_f32_16x16x32_bf16 v[46:49], v[138:141], v[172:175], v[46:49]
	v_mfma_f32_16x16x32_bf16 v[42:45], v[146:149], v[172:175], v[42:45]
	v_mfma_f32_16x16x32_bf16 v[30:33], v[138:141], v[180:183], v[30:33]
	v_mfma_f32_16x16x32_bf16 v[26:29], v[146:149], v[180:183], v[26:29]
	v_mfma_f32_16x16x32_bf16 v[14:17], v[138:141], v[212:215], v[14:17]
	v_mfma_f32_16x16x32_bf16 v[10:13], v[146:149], v[212:215], v[10:13]
	s_setprio 0
	s_barrier
; #define PG8_STAGE(bufoff, gbase, voff) do { _Pragma("unroll") for (int _i = 0; _i < 2; ++_i) \
;     __builtin_amdgcn_global_load_lds((const unsigned*)((const char*)(gbase) + (voff)[_i]), (LAS unsigned*)(lds + (bufoff) + ldsw + _i * 8192), 16, 0, 0); } while (0)
; #define PG8_LDA(dst, b, h) do { _Pragma("unroll") for (int m = 0; m < 4; ++m) _Pragma("unroll") for (int k = 0; k < 2; ++k) dst[m][k] = *(const LAS bf16x8*)(lds + PG8_SA(b, h) + aoff + m * 2048 + k * 1024); } while (0)
; #define PG8_LDB(dst, b, h) do { _Pragma("unroll") for (int n = 0; n < 2; ++n) _Pragma("unroll") for (int k = 0; k < 2; ++k) dst[n][k] = *(const LAS bf16x8*)(lds + PG8_SB(b, h) + boff + n * 2048 + k * 1024); } while (0)
; #define PG8_MMA(ai, bj, At, Bt) do { __builtin_amdgcn_s_setprio(1); _Pragma("unroll") for (int m = 0; m < 4; ++m) _Pragma("unroll") for (int n = 0; n < 2; ++n) _Pragma("unroll") for (int k = 0; k < 2; ++k) \
;     acc[ai][bj][m][n] = __builtin_amdgcn_mfma_f32_16x16x32_bf16(Bt[n][k], At[m][k], acc[ai][bj][m][n], 0, 0, 0); __builtin_amdgcn_s_setprio(0); } while (0)
; #define PG8_WAIT_V(n) asm volatile("s_waitcnt vmcnt(" #n ")" ::: "memory")
; #define PG8_WAIT_L(n) asm volatile("s_waitcnt lgkmcnt(" #n ")" ::: "memory")
; #define PG8_BAR __builtin_amdgcn_s_barrier()
; #define PG8_SCHED __builtin_amdgcn_sched_barrier(0)
; template <class Epi, bool SPLITA = false>
; __device__ __forceinline__ void gemm_phase(const int tid, LAS unsigned char* lds, const Gemm g, const Order& S, const Epi& E) {
;     ...
;       PG8_STAGE(PG8_SB(0, 1), b2 + hstepB, voffB);
;       PG8_WAIT_V(6); PG8_BAR; PG8_MMA(1, 1, At, B1); PG8_BAR;
;       PG8_LDB(B0, 1, 0); PG8_SCHED; PG8_LDA(At, 1, 0); PG8_STAGE(PG8_SA(0, 1), a2 + hstepA, voffA);
;       PG8_WAIT_L(8); PG8_BAR; PG8_WAIT_L(0); PG8_MMA(0, 0, At, B0); PG8_BAR; PG8_SCHED;
;       PG8_LDB(B1, 1, 1); PG8_STAGE(PG8_SB(1, 0), b3, voffB);
;       PG8_BAR; PG8_WAIT_L(0); PG8_MMA(0, 1, At, B1); PG8_BAR;
;       PG8_LDA(At, 1, 1); PG8_STAGE(PG8_SA(1, 0), a3, voffA);
;       PG8_BAR; PG8_WAIT_L(0); PG8_MMA(1, 0, At, B0); PG8_BAR; PG8_SCHED;
	s_add_u32 s20, s18, 0x160000
	s_addc_u32 s21, s19, 0
	s_add_i32 s8, s8, s3
	s_mov_b32 m0, s8
	s_nop 0
	global_load_lds_dwordx4 v0, s[20:21]
	s_add_i32 m0, s8, 0x2000
	s_nop 0
	global_load_lds_dwordx4 v162, s[20:21]
	s_waitcnt vmcnt(6)
	s_barrier
	s_setprio 1
	v_mfma_f32_16x16x32_bf16 v[54:57], v[216:219], v[150:153], 0
	v_mfma_f32_16x16x32_bf16 v[50:53], v[224:227], v[150:153], 0
	v_mfma_f32_16x16x32_bf16 v[38:41], v[216:219], v[168:171], 0
	v_mfma_f32_16x16x32_bf16 v[34:37], v[224:227], v[168:171], 0
	v_mfma_f32_16x16x32_bf16 v[22:25], v[216:219], v[176:179], 0
	v_mfma_f32_16x16x32_bf16 v[18:21], v[224:227], v[176:179], 0
	v_mfma_f32_16x16x32_bf16 v[6:9], v[216:219], v[190:193], 0
	v_mfma_f32_16x16x32_bf16 v[2:5], v[224:227], v[190:193], 0
	v_mfma_f32_16x16x32_bf16 v[54:57], v[220:223], v[154:157], v[54:57]
	v_mfma_f32_16x16x32_bf16 v[50:53], v[228:231], v[154:157], v[50:53]
	v_mfma_f32_16x16x32_bf16 v[38:41], v[220:223], v[172:175], v[38:41]
	v_mfma_f32_16x16x32_bf16 v[34:37], v[228:231], v[172:175], v[34:37]
	v_mfma_f32_16x16x32_bf16 v[22:25], v[220:223], v[180:183], v[22:25]
	v_mfma_f32_16x16x32_bf16 v[18:21], v[228:231], v[180:183], v[18:21]
	v_mfma_f32_16x16x32_bf16 v[6:9], v[220:223], v[212:215], v[6:9]
	v_mfma_f32_16x16x32_bf16 v[2:5], v[228:231], v[212:215], v[2:5]
	s_setprio 0
	s_add_i32 s8, 0, 0x18000
	v_add_u32_e32 v146, s8, v188
	s_barrier
	ds_read_b128 v[134:137], v146
	ds_read_b128 v[138:141], v146 offset:1024
	ds_read_b128 v[142:145], v146 offset:2048
	ds_read_b128 v[146:149], v146 offset:3072
	s_add_u32 s20, s40, 0x160000
	s_addc_u32 s21, s41, 0
	s_mov_b32 m0, s42
	ds_read_b128 v[150:153], v189 offset:32768
	ds_read_b128 v[154:157], v189 offset:33792
	ds_read_b128 v[168:171], v189 offset:34816
	ds_read_b128 v[172:175], v189 offset:35840
	ds_read_b128 v[176:179], v189 offset:36864
	ds_read_b128 v[180:183], v189 offset:37888
	ds_read_b128 v[190:193], v189 offset:38912
	ds_read_b128 v[212:215], v189 offset:39936
	global_load_lds_dwordx4 v158, s[20:21]
	s_mov_b32 m0, s43
	s_nop 0
	global_load_lds_dwordx4 v160, s[20:21]
	s_waitcnt lgkmcnt(8)
	s_barrier
	s_waitcnt lgkmcnt(0)
	s_setprio 1
	s_waitcnt lgkmcnt(0)
	v_mfma_f32_16x16x32_bf16 v[126:129], v[134:137], v[150:153], v[126:129]
	v_mfma_f32_16x16x32_bf16 v[122:125], v[142:145], v[150:153], v[122:125]
	v_mfma_f32_16x16x32_bf16 v[110:113], v[134:137], v[168:171], v[110:113]
	v_mfma_f32_16x16x32_bf16 v[106:109], v[142:145], v[168:171], v[106:109]
	v_mfma_f32_16x16x32_bf16 v[94:97], v[134:137], v[176:179], v[94:97]
	v_mfma_f32_16x16x32_bf16 v[90:93], v[142:145], v[176:179], v[90:93]
	v_mfma_f32_16x16x32_bf16 v[78:81], v[134:137], v[190:193], v[78:81]
	v_mfma_f32_16x16x32_bf16 v[74:77], v[142:145], v[190:193], v[74:77]
	v_mfma_f32_16x16x32_bf16 v[126:129], v[138:141], v[154:157], v[126:129]
	v_mfma_f32_16x16x32_bf16 v[122:125], v[146:149], v[154:157], v[122:125]
	v_mfma_f32_16x16x32_bf16 v[110:113], v[138:141], v[172:175], v[110:113]
	v_mfma_f32_16x16x32_bf16 v[106:109], v[146:149], v[172:175], v[106:109]
	v_mfma_f32_16x16x32_bf16 v[94:97], v[138:141], v[180:183], v[94:97]
	v_mfma_f32_16x16x32_bf16 v[90:93], v[146:149], v[180:183], v[90:93]
	v_mfma_f32_16x16x32_bf16 v[78:81], v[138:141], v[212:215], v[78:81]
	v_mfma_f32_16x16x32_bf16 v[74:77], v[146:149], v[212:215], v[74:77]
	s_setprio 0
	s_barrier
	s_add_i32 s9, 0, 0x1c000
	s_add_i32 s8, s8, s3
	v_add_u32_e32 v195, s9, v188
	s_add_i32 m0, s8, 0xffffff80
	ds_read_b128 v[216:219], v195
	ds_read_b128 v[220:223], v195 offset:1024
	ds_read_b128 v[224:227], v195 offset:2048
	ds_read_b128 v[228:231], v195 offset:3072
	global_load_lds_dwordx4 v0, s[18:19] offset:128
	s_add_i32 m0, s8, 0x1f80
	s_nop 0
	global_load_lds_dwordx4 v162, s[18:19] offset:128
	s_barrier
; #define PG8_STAGE(bufoff, gbase, voff) do { _Pragma("unroll") for (int _i = 0; _i < 2; ++_i) \
;     __builtin_amdgcn_global_load_lds((const unsigned*)((const char*)(gbase) + (voff)[_i]), (LAS unsigned*)(lds + (bufoff) + ldsw + _i * 8192), 16, 0, 0); } while (0)
; #define PG8_LDA(dst, b, h) do { _Pragma("unroll") for (int m = 0; m < 4; ++m) _Pragma("unroll") for (int k = 0; k < 2; ++k) dst[m][k] = *(const LAS bf16x8*)(lds + PG8_SA(b, h) + aoff + m * 2048 + k * 1024); } while (0)
; #define PG8_MMA(ai, bj, At, Bt) do { __builtin_amdgcn_s_setprio(1); _Pragma("unroll") for (int m = 0; m < 4; ++m) _Pragma("unroll") for (int n = 0; n < 2; ++n) _Pragma("unroll") for (int k = 0; k < 2; ++k) \
;     acc[ai][bj][m][n] = __builtin_amdgcn_mfma_f32_16x16x32_bf16(Bt[n][k], At[m][k], acc[ai][bj][m][n], 0, 0, 0); __builtin_amdgcn_s_setprio(0); } while (0)
; #define PG8_WAIT_V(n) asm volatile("s_waitcnt vmcnt(" #n ")" ::: "memory")
; #define PG8_WAIT_L(n) asm volatile("s_waitcnt lgkmcnt(" #n ")" ::: "memory")
; #define PG8_BAR __builtin_amdgcn_s_barrier()
; #define PG8_SCHED __builtin_amdgcn_sched_barrier(0)
; template <class Epi, bool SPLITA = false>
; __device__ __forceinline__ void gemm_phase(const int tid, LAS unsigned char* lds, const Gemm g, const Order& S, const Epi& E) {
;     ...
;       PG8_LDA(At, 1, 1); PG8_STAGE(PG8_SA(1, 0), a3, voffA);
;       PG8_BAR; PG8_WAIT_L(0); PG8_MMA(1, 0, At, B0); PG8_BAR; PG8_SCHED;
;       PG8_STAGE(PG8_SB(1, 1), b3 + hstepB, voffB);
;       PG8_WAIT_V(6); PG8_BAR; PG8_MMA(1, 1, At, B1); PG8_BAR;
;     }
	s_waitcnt lgkmcnt(0)
	s_setprio 1
	s_waitcnt lgkmcnt(0)
	v_mfma_f32_16x16x32_bf16 v[118:121], v[216:219], v[150:153], v[118:121]
	v_mfma_f32_16x16x32_bf16 v[114:117], v[224:227], v[150:153], v[114:117]
	v_mfma_f32_16x16x32_bf16 v[102:105], v[216:219], v[168:171], v[102:105]
	v_mfma_f32_16x16x32_bf16 v[98:101], v[224:227], v[168:171], v[98:101]
	v_mfma_f32_16x16x32_bf16 v[86:89], v[216:219], v[176:179], v[86:89]
	v_mfma_f32_16x16x32_bf16 v[82:85], v[224:227], v[176:179], v[82:85]
	v_mfma_f32_16x16x32_bf16 v[70:73], v[216:219], v[190:193], v[70:73]
	v_mfma_f32_16x16x32_bf16 v[66:69], v[224:227], v[190:193], v[66:69]
	v_mfma_f32_16x16x32_bf16 v[118:121], v[220:223], v[154:157], v[118:121]
	v_mfma_f32_16x16x32_bf16 v[114:117], v[228:231], v[154:157], v[114:117]
	v_mfma_f32_16x16x32_bf16 v[102:105], v[220:223], v[172:175], v[102:105]
	v_mfma_f32_16x16x32_bf16 v[98:101], v[228:231], v[172:175], v[98:101]
	v_mfma_f32_16x16x32_bf16 v[86:89], v[220:223], v[180:183], v[86:89]
	v_mfma_f32_16x16x32_bf16 v[82:85], v[228:231], v[180:183], v[82:85]
	v_mfma_f32_16x16x32_bf16 v[70:73], v[220:223], v[212:215], v[70:73]
	v_mfma_f32_16x16x32_bf16 v[66:69], v[228:231], v[212:215], v[66:69]
	s_setprio 0
	s_mov_b32 m0, s47
	s_barrier
	ds_read_b128 v[150:153], v189 offset:49152
	ds_read_b128 v[154:157], v189 offset:50176
	ds_read_b128 v[168:171], v189 offset:51200
	ds_read_b128 v[172:175], v189 offset:52224
	ds_read_b128 v[176:179], v189 offset:53248
	ds_read_b128 v[180:183], v189 offset:54272
	ds_read_b128 v[190:193], v189 offset:55296
	ds_read_b128 v[212:215], v189 offset:56320
	global_load_lds_dwordx4 v158, s[22:23]
	s_mov_b32 m0, s48
	s_nop 0
	global_load_lds_dwordx4 v160, s[22:23]
	s_barrier
	s_waitcnt lgkmcnt(0)
	s_setprio 1
	s_waitcnt lgkmcnt(0)
	v_mfma_f32_16x16x32_bf16 v[62:65], v[134:137], v[150:153], v[62:65]
	v_mfma_f32_16x16x32_bf16 v[58:61], v[142:145], v[150:153], v[58:61]
	v_mfma_f32_16x16x32_bf16 v[46:49], v[134:137], v[168:171], v[46:49]
	v_mfma_f32_16x16x32_bf16 v[42:45], v[142:145], v[168:171], v[42:45]
	v_mfma_f32_16x16x32_bf16 v[30:33], v[134:137], v[176:179], v[30:33]
	v_mfma_f32_16x16x32_bf16 v[26:29], v[142:145], v[176:179], v[26:29]
	v_mfma_f32_16x16x32_bf16 v[14:17], v[134:137], v[190:193], v[14:17]
	v_mfma_f32_16x16x32_bf16 v[10:13], v[142:145], v[190:193], v[10:13]
	v_mfma_f32_16x16x32_bf16 v[62:65], v[138:141], v[154:157], v[62:65]
	v_mfma_f32_16x16x32_bf16 v[58:61], v[146:149], v[154:157], v[58:61]
	v_mfma_f32_16x16x32_bf16 v[46:49], v[138:141], v[172:175], v[46:49]
	v_mfma_f32_16x16x32_bf16 v[42:45], v[146:149], v[172:175], v[42:45]
	v_mfma_f32_16x16x32_bf16 v[30:33], v[138:141], v[180:183], v[30:33]
	v_mfma_f32_16x16x32_bf16 v[26:29], v[146:149], v[180:183], v[26:29]
	v_mfma_f32_16x16x32_bf16 v[14:17], v[138:141], v[212:215], v[14:17]
	v_mfma_f32_16x16x32_bf16 v[10:13], v[146:149], v[212:215], v[10:13]
	s_setprio 0
	s_barrier
	s_add_u32 s18, s18, 0x160080
	s_addc_u32 s19, s19, 0
	s_add_i32 s8, s9, s3
	s_mov_b32 m0, s8
	s_nop 0
	global_load_lds_dwordx4 v0, s[18:19]
	s_add_i32 m0, s8, 0x2000
	s_nop 0
	global_load_lds_dwordx4 v162, s[18:19]
	s_waitcnt vmcnt(6)
	s_barrier
	s_setprio 1
	v_mfma_f32_16x16x32_bf16 v[54:57], v[216:219], v[150:153], v[54:57]
	v_mfma_f32_16x16x32_bf16 v[50:53], v[224:227], v[150:153], v[50:53]
	v_mfma_f32_16x16x32_bf16 v[38:41], v[216:219], v[168:171], v[38:41]
	v_mfma_f32_16x16x32_bf16 v[34:37], v[224:227], v[168:171], v[34:37]
	v_mfma_f32_16x16x32_bf16 v[22:25], v[216:219], v[176:179], v[22:25]
	v_mfma_f32_16x16x32_bf16 v[18:21], v[224:227], v[176:179], v[18:21]
	v_mfma_f32_16x16x32_bf16 v[6:9], v[216:219], v[190:193], v[6:9]
	v_mfma_f32_16x16x32_bf16 v[2:5], v[224:227], v[190:193], v[2:5]
	v_mfma_f32_16x16x32_bf16 v[54:57], v[220:223], v[154:157], v[54:57]
	v_mfma_f32_16x16x32_bf16 v[50:53], v[228:231], v[154:157], v[50:53]
	v_mfma_f32_16x16x32_bf16 v[38:41], v[220:223], v[172:175], v[38:41]
	v_mfma_f32_16x16x32_bf16 v[34:37], v[228:231], v[172:175], v[34:37]
	v_mfma_f32_16x16x32_bf16 v[22:25], v[220:223], v[180:183], v[22:25]
	v_mfma_f32_16x16x32_bf16 v[18:21], v[228:231], v[180:183], v[18:21]
	v_mfma_f32_16x16x32_bf16 v[6:9], v[220:223], v[212:215], v[6:9]
	v_mfma_f32_16x16x32_bf16 v[2:5], v[228:231], v[212:215], v[2:5]
	s_setprio 0
	s_add_i32 s29, s29, 2
	s_add_u32 s16, s16, 0x100
	s_addc_u32 s17, s17, 0
	s_cmpk_gt_u32 s29, 0x55
	s_barrier
	s_cbranch_scc0 .LBB0_87
	s_branch .Lpeel_exit_87

; __device__ __forceinline__ float bflo(unsigned w) { return __uint_as_float(w << 16); }
; __device__ __forceinline__ float bfhi(unsigned w) { return __uint_as_float(w & 0xffff0000u); }
; __device__ __forceinline__ float lane_read(float v, int src) { return __int_as_float(__builtin_amdgcn_ds_bpermute(src << 2, __float_as_int(v))); }
; __device__ __forceinline__ u32x4 pack8(const f32x4 v0, const f32x4 v1) { u32x4 w; w.x = cvtpk(v0[0], v0[1]); w.y = cvtpk(v0[2], v0[3]); w.z = cvtpk(v1[0], v1[1]); w.w = cvtpk(v1[2], v1[3]); return w; }
;   __device__ __forceinline__ void operator()(const Acc& acc, const Unit& u, int wr, int wc, int fr_, int fq_) const {
;     int fr = fr_, fq = fq_; asm volatile("" : "+v"(fr), "+v"(fq));
;     const int lane = fq * 16 + fr;
;     const int row0 = u.pm * BM + wr * 64 + fr, col0 = u.pn * BM + wc * 32 + 8 * fq;
; #pragma unroll
;     for (int ai = 0; ai < 2; ++ai) {
;       u32x4 hv[4][2];
; #pragma unroll
;       for (int m = 0; m < 4; ++m)
; #pragma unroll
;         for (int bj = 0; bj < 2; ++bj) hv[m][bj] = *(const u32x4*)(rin + (size_t)(row0 + ai * HALF + m * 16) * DM + col0 + bj * HALF);
; #pragma unroll
;       for (int m = 0; m < 4; ++m) { const size_t ro = (size_t)(row0 + ai * HALF + m * 16) * DM + col0; float ss = 0.f;
; #pragma unroll
;         for (int bj = 0; bj < 2; ++bj) { const u32x4 h = hv[m][bj];
;           f32x4 v0 = acc[ai][bj][m][0], v1 = acc[ai][bj][m][1];
;           v0[0] += bflo(h.x); v0[1] += bfhi(h.x); v0[2] += bflo(h.y); v0[3] += bfhi(h.y);
;           v1[0] += bflo(h.z); v1[1] += bfhi(h.z); v1[2] += bflo(h.w); v1[3] += bfhi(h.w);
;           if (FINAL) { *(f32x4*)(outf + ro + bj * HALF) = v0; *(f32x4*)(outf + ro + bj * HALF + 4) = v1; }
;           else { ss += v0[0] * v0[0] + v0[1] * v0[1] + v0[2] * v0[2] + v0[3] * v0[3] + v1[0] * v1[0] + v1[1] * v1[1] + v1[2] * v1[2] + v1[3] * v1[3];
;             *(u32x4*)(outb + ro + bj * HALF) = pack8(v0, v1); } }
;         if (!FINAL) { ss += lane_read(ss, lane ^ 16); ss += lane_read(ss, lane ^ 32);
;           if (fq == 0) rss[(size_t)(row0 + ai * HALF + m * 16) * 32 + u.pn * 4 + wc] = ss; } }
.Lpeel_exit_87:
	s_lshl_b32 s6, s53, 8
	v_mov_b32_e32 v130, v187
	v_mov_b32_e32 v131, v186
	s_add_i32 s6, s6, s45
	s_lshl_b32 s12, s4, 2
	v_add_u32_e32 v170, s6, v130
	s_lshl_b32 s6, s4, 8
	s_or_b32 s6, s6, s46
	v_lshl_add_u32 v168, v131, 3, s6
	v_ashrrev_i32_e32 v169, 31, v168
	v_lshlrev_b32_e32 v130, 2, v130
	v_lshlrev_b64 v[192:193], 1, v[168:169]
	v_ashrrev_i32_e32 v171, 31, v170
	v_lshl_add_u32 v130, v131, 6, v130
	v_lshl_add_u64 v[172:173], s[86:87], 0, v[192:193]
	v_lshlrev_b64 v[198:199], 12, v[170:171]
	v_xor_b32_e32 v191, 64, v130
	v_xor_b32_e32 v190, 0x80, v130
	v_cmp_eq_u32_e32 vcc, 0, v131
	v_lshl_add_u64 v[130:131], v[172:173], 0, v[198:199]
	global_load_dwordx4 v[212:215], v[130:131], off
	global_load_dwordx4 v[154:157], v[130:131], off offset:256
	v_add_u32_e32 v182, 16, v170
	v_ashrrev_i32_e32 v183, 31, v182
	v_add_u32_e32 v178, 32, v170
	v_lshlrev_b64 v[184:185], 12, v[182:183]
	v_ashrrev_i32_e32 v179, 31, v178
	v_add_u32_e32 v174, 48, v170
	v_lshl_add_u64 v[130:131], v[172:173], 0, v[184:185]
	v_lshlrev_b64 v[180:181], 12, v[178:179]
	v_ashrrev_i32_e32 v175, 31, v174
	global_load_dwordx4 v[150:153], v[130:131], off
	global_load_dwordx4 v[146:149], v[130:131], off offset:256
	v_lshl_add_u64 v[130:131], v[172:173], 0, v[180:181]
	v_lshlrev_b64 v[176:177], 12, v[174:175]
	global_load_dwordx4 v[142:145], v[130:131], off
	global_load_dwordx4 v[138:141], v[130:131], off offset:256
	v_lshl_add_u64 v[130:131], v[172:173], 0, v[176:177]
	global_load_dwordx4 v[134:137], v[130:131], off
	s_nop 0
	global_load_dwordx4 v[130:133], v[130:131], off offset:256
	s_ashr_i32 s13, s12, 31
	s_waitcnt vmcnt(0)
	v_lshlrev_b32_e32 v200, 16, v212
	v_and_b32_e32 v201, 0xffff0000, v212
	v_pk_add_f32 v[126:127], v[126:127], v[200:201]
	v_lshlrev_b32_e32 v200, 16, v213
	v_and_b32_e32 v201, 0xffff0000, v213
	v_pk_add_f32 v[128:129], v[128:129], v[200:201]
	v_lshlrev_b32_e32 v200, 16, v214
	v_and_b32_e32 v201, 0xffff0000, v214
	v_pk_add_f32 v[200:201], v[122:123], v[200:201]
	v_lshlrev_b32_e32 v122, 16, v215
	v_and_b32_e32 v123, 0xffff0000, v215
	v_pk_add_f32 v[202:203], v[124:125], v[122:123]
	v_pk_mul_f32 v[204:205], v[126:127], v[126:127]
	v_cvt_pk_bf16_f32 v122, v126, v127
	v_lshl_add_u64 v[126:127], s[86:87], 0, v[198:199]
	v_cvt_pk_bf16_f32 v123, v128, v129
	v_cvt_pk_bf16_f32 v124, v200, v201
	v_cvt_pk_bf16_f32 v125, v202, v203
	v_lshl_add_u64 v[126:127], v[126:127], 0, v[192:193]
	global_store_dwordx4 v[126:127], v[122:125], off
	v_pk_mul_f32 v[206:207], v[128:129], v[128:129]
	v_pk_mul_f32 v[212:213], v[200:201], v[200:201]
	v_lshlrev_b32_e32 v122, 16, v154
	v_and_b32_e32 v123, 0xffff0000, v154
	v_pk_add_f32 v[118:119], v[118:119], v[122:123]
	v_lshlrev_b32_e32 v122, 16, v155
	v_and_b32_e32 v123, 0xffff0000, v155
	v_pk_add_f32 v[120:121], v[120:121], v[122:123]
	v_lshlrev_b32_e32 v122, 16, v156
	v_and_b32_e32 v123, 0xffff0000, v156
	v_pk_add_f32 v[122:123], v[114:115], v[122:123]
	v_lshlrev_b32_e32 v114, 16, v157
	v_and_b32_e32 v115, 0xffff0000, v157
	v_pk_add_f32 v[124:125], v[116:117], v[114:115]
	v_pk_mul_f32 v[114:115], v[118:119], v[118:119]
	v_pk_mul_f32 v[116:117], v[120:121], v[120:121]
	v_add_f32_e32 v114, v114, v115
	v_add_f32_e32 v115, v204, v205
	v_add_f32_e32 v114, v116, v114
	v_add_f32_e32 v115, v206, v115
	v_pk_mul_f32 v[128:129], v[122:123], v[122:123]
	v_add_f32_e32 v114, v117, v114
	v_add_f32_e32 v115, v207, v115
	v_add_f32_e32 v114, v128, v114
	v_add_f32_e32 v115, v212, v115
	v_pk_mul_f32 v[214:215], v[202:203], v[202:203]
	v_pk_mul_f32 v[154:155], v[124:125], v[124:125]
	v_add_f32_e32 v114, v129, v114
	v_add_f32_e32 v115, v213, v115
	v_add_f32_e32 v114, v154, v114
	v_add_f32_e32 v115, v214, v115
	v_add_f32_e32 v114, v155, v114
	v_add_f32_e32 v115, v215, v115
	v_add_f32_e32 v128, v115, v114
	v_cvt_pk_bf16_f32 v114, v118, v119
	v_cvt_pk_bf16_f32 v115, v120, v121
	v_cvt_pk_bf16_f32 v116, v122, v123
	v_cvt_pk_bf16_f32 v117, v124, v125
	global_store_dwordx4 v[126:127], v[114:117], off offset:256
	ds_bpermute_b32 v114, v191, v128
	s_waitcnt lgkmcnt(0)
	v_add_f32_e32 v114, v128, v114
	ds_bpermute_b32 v115, v190, v114
	s_and_saveexec_b64 s[6:7], vcc
	s_cbranch_execz .LBB0_90
	v_readlane_b32 s8, v255, 1
	v_lshlrev_b64 v[116:117], 7, v[170:171]
	v_readlane_b32 s9, v255, 2
	s_lshl_b32 s4, s44, 2
	s_waitcnt lgkmcnt(0)
	v_add_f32_e32 v114, v114, v115
	v_lshl_add_u64 v[116:117], s[8:9], 0, v[116:117]
	v_lshl_add_u64 v[116:117], s[12:13], 2, v[116:117]
	v_lshl_add_u64 v[116:117], v[116:117], 0, s[4:5]
	global_store_dword v[116:117], v114, off

; #define PG8_STAGE(bufoff, gbase, voff) do { _Pragma("unroll") for (int _i = 0; _i < 2; ++_i) \
;     __builtin_amdgcn_global_load_lds((const unsigned*)((const char*)(gbase) + (voff)[_i]), (LAS unsigned*)(lds + (bufoff) + ldsw + _i * 8192), 16, 0, 0); } while (0)
; #define PG8_LDA(dst, b, h) do { _Pragma("unroll") for (int m = 0; m < 4; ++m) _Pragma("unroll") for (int k = 0; k < 2; ++k) dst[m][k] = *(const LAS bf16x8*)(lds + PG8_SA(b, h) + aoff + m * 2048 + k * 1024); } while (0)
; #define PG8_LDB(dst, b, h) do { _Pragma("unroll") for (int n = 0; n < 2; ++n) _Pragma("unroll") for (int k = 0; k < 2; ++k) dst[n][k] = *(const LAS bf16x8*)(lds + PG8_SB(b, h) + boff + n * 2048 + k * 1024); } while (0)
; #define PG8_WAIT_L(n) asm volatile("s_waitcnt lgkmcnt(" #n ")" ::: "memory")
; #define PG8_BAR __builtin_amdgcn_s_barrier()
; #define PG8_SCHED __builtin_amdgcn_sched_barrier(0)
; template <class Epi, bool SPLITA = false>
; __device__ __forceinline__ void gemm_phase(const int tid, LAS unsigned char* lds, const Gemm g, const Order& S, const Epi& E) {
;     ...
;     const bool has_next = S.next(ui + 1, nxt);
;     const char* nA = has_next ? (const char*)g.A + (size_t)nxt.pm * tstepA + (size_t)nxt.pn * apn : cA; const char* nA2 = (SPLITA && has_next) ? (const char*)g.A2 + (size_t)nxt.pm * tstepA : cA2; const char* nB = has_next ? (const char*)g.Bt + (size_t)nxt.pn * tstepB : cB;
;     for (int t = 0; t < nt; t += 2) {
;       const bool last = (t == nt - 2);
;       if constexpr (SPLITA) { if (t == nt1) E.mid(acc, cur, wr, wc, fr, fq); }
;       const char* a1 = PG8_TA(t + 1);
;       const char* a2 = last ? nA : PG8_TA(t + 2); const char* b2 = last ? nB : cB + (size_t)(t + 2) * kstep;
;       const char* a3 = last ? nA + kstep : PG8_TA(t + 3); const char* b3 = b2 + kstep;
;       PG8_LDB(B0, 0, 0); PG8_SCHED; PG8_LDA(At, 0, 0); PG8_STAGE(PG8_SA(1, 1), a1 + hstepA, voffA);
;       PG8_WAIT_L(8); PG8_BAR; PG8_WAIT_L(0); PG8_MMA(0, 0, At, B0); PG8_BAR; PG8_SCHED;
;       PG8_LDB(B1, 0, 1); PG8_STAGE(PG8_SB(0, 0), b2, voffB);
;       PG8_BAR; PG8_WAIT_L(0); PG8_MMA(0, 1, At, B1); PG8_BAR;
;       PG8_LDA(At, 0, 1); PG8_STAGE(PG8_SA(0, 0), a2, voffA);
;       PG8_BAR; PG8_WAIT_L(0); PG8_MMA(1, 0, At, B0); PG8_BAR; PG8_SCHED;
.LBB0_191:
	s_ashr_i32 s13, s12, 31
	s_lshl_b64 s[6:7], s[12:13], 20
	v_readlane_b32 s8, v255, 31
	v_cmp_lt_i64_e32 vcc, s[14:15], v[242:243]
	v_readlane_b32 s9, v255, 32
	s_add_u32 s14, s8, s6
	s_addc_u32 s15, s9, s7
	s_and_b64 s[6:7], vcc, exec
	s_cselect_b32 s4, s15, s41
	s_cselect_b32 s6, s14, s40
	s_ashr_i32 s11, s10, 31
	s_lshl_b64 s[16:17], s[10:11], 20
	s_add_u32 s16, s30, s16
	s_addc_u32 s17, s31, s17
	s_and_b64 s[44:45], vcc, exec
	s_cselect_b32 s7, s17, s43
	s_cselect_b32 s11, s16, s42
	s_add_u32 s13, s6, 0x80
	s_addc_u32 s19, s4, 0
	s_add_u32 vcc_lo, s42, 0x100
	s_addc_u32 vcc_hi, s43, 0
	s_add_u32 s42, s40, 0x80080
	s_addc_u32 s43, s41, 0
	v_mov_b32_e32 v2, 0
	v_not_b32_e32 v196, 63
	v_lshl_add_u64 v[130:131], s[42:43], 0, v[164:165]
	v_lshl_add_u64 v[132:133], s[42:43], 0, v[166:167]
	s_mov_b32 s29, -2
	s_mov_b64 s[42:43], 0
	s_waitcnt lgkmcnt(0)
	s_waitcnt vmcnt(0)
	s_add_u32 s20, s40, s42
	s_addc_u32 s21, s41, s43
	s_add_u32 s48, s20, 0x100
	s_addc_u32 s49, s21, 0
	s_add_u32 s44, vcc_lo, s42
	s_addc_u32 s45, vcc_hi, s43
	s_add_u32 s20, s20, 0x180
	s_addc_u32 s21, s21, 0
	s_add_i32 s94, 0, 0x10000
	v_add_u32_e32 v146, s94, v188
	ds_read_b128 v[134:137], v146
	ds_read_b128 v[138:141], v146 offset:1024
	ds_read_b128 v[142:145], v146 offset:2048
	ds_read_b128 v[146:149], v146 offset:3072
	s_cmpk_eq_i32 s42, 0xf00
	s_cselect_b32 s47, s19, s21
	s_cselect_b32 s46, s13, s20
	s_cselect_b32 s45, s7, s45
	s_cselect_b32 s44, s11, s44
	s_cselect_b32 s49, s4, s49
	s_cselect_b32 s48, s6, s48
	v_lshl_add_u64 v[184:185], v[130:131], 0, s[42:43]
	s_add_i32 m0, s23, 0xc000
	ds_read_b128 v[150:153], v189
	ds_read_b128 v[154:157], v189 offset:1024
	ds_read_b128 v[168:171], v189 offset:2048
	ds_read_b128 v[172:175], v189 offset:3072
	ds_read_b128 v[176:179], v189 offset:4096
	ds_read_b128 v[180:183], v189 offset:5120
	ds_read_b128 v[190:193], v189 offset:6144
	ds_read_b128 v[212:215], v189 offset:7168
	global_load_lds_dwordx4 v[184:185], off
	v_lshl_add_u64 v[184:185], v[132:133], 0, s[42:43]
	s_add_i32 m0, s23, 0xe000
	s_nop 0
	global_load_lds_dwordx4 v[184:185], off
	s_waitcnt lgkmcnt(8)
	s_barrier
	s_waitcnt lgkmcnt(0)
	s_setprio 1
	s_waitcnt lgkmcnt(0)
	v_mfma_f32_16x16x32_bf16 v[126:129], v[134:137], v[150:153], 0
	v_mfma_f32_16x16x32_bf16 v[122:125], v[142:145], v[150:153], 0
	v_mfma_f32_16x16x32_bf16 v[110:113], v[134:137], v[168:171], 0
	v_mfma_f32_16x16x32_bf16 v[106:109], v[142:145], v[168:171], 0
	v_mfma_f32_16x16x32_bf16 v[94:97], v[134:137], v[176:179], 0
	v_mfma_f32_16x16x32_bf16 v[90:93], v[142:145], v[176:179], 0
	v_mfma_f32_16x16x32_bf16 v[78:81], v[134:137], v[190:193], 0
	v_mfma_f32_16x16x32_bf16 v[74:77], v[142:145], v[190:193], 0
	v_mfma_f32_16x16x32_bf16 v[126:129], v[138:141], v[154:157], v[126:129]
	v_mfma_f32_16x16x32_bf16 v[122:125], v[146:149], v[154:157], v[122:125]
	v_mfma_f32_16x16x32_bf16 v[110:113], v[138:141], v[172:175], v[110:113]
	v_mfma_f32_16x16x32_bf16 v[106:109], v[146:149], v[172:175], v[106:109]
	v_mfma_f32_16x16x32_bf16 v[94:97], v[138:141], v[180:183], v[94:97]
	v_mfma_f32_16x16x32_bf16 v[90:93], v[146:149], v[180:183], v[90:93]
	v_mfma_f32_16x16x32_bf16 v[78:81], v[138:141], v[212:215], v[78:81]
	v_mfma_f32_16x16x32_bf16 v[74:77], v[146:149], v[212:215], v[74:77]
	s_setprio 0
	s_barrier
	s_add_i32 s8, 0, 0x14000
	v_add_u32_e32 v184, s8, v188
	s_add_i32 s9, s94, s3
	ds_read_b128 v[216:219], v184
	ds_read_b128 v[220:223], v184 offset:1024
	ds_read_b128 v[224:227], v184 offset:2048
	ds_read_b128 v[228:231], v184 offset:3072
	s_mov_b32 m0, s9
	s_nop 0
	global_load_lds_dwordx4 v0, s[44:45]
	s_add_i32 m0, s9, 0x2000
	s_nop 0
	global_load_lds_dwordx4 v162, s[44:45]
	s_barrier
	s_waitcnt lgkmcnt(0)
	s_setprio 1
	s_waitcnt lgkmcnt(0)
	v_mfma_f32_16x16x32_bf16 v[118:121], v[216:219], v[150:153], 0
	v_mfma_f32_16x16x32_bf16 v[114:117], v[224:227], v[150:153], 0
	v_mfma_f32_16x16x32_bf16 v[102:105], v[216:219], v[168:171], 0
	v_mfma_f32_16x16x32_bf16 v[98:101], v[224:227], v[168:171], 0
	v_mfma_f32_16x16x32_bf16 v[86:89], v[216:219], v[176:179], 0
	v_mfma_f32_16x16x32_bf16 v[82:85], v[224:227], v[176:179], 0
	v_mfma_f32_16x16x32_bf16 v[70:73], v[216:219], v[190:193], 0
	v_mfma_f32_16x16x32_bf16 v[66:69], v[224:227], v[190:193], 0
	v_mfma_f32_16x16x32_bf16 v[118:121], v[220:223], v[154:157], v[118:121]
	v_mfma_f32_16x16x32_bf16 v[114:117], v[228:231], v[154:157], v[114:117]
	v_mfma_f32_16x16x32_bf16 v[102:105], v[220:223], v[172:175], v[102:105]
	v_mfma_f32_16x16x32_bf16 v[98:101], v[228:231], v[172:175], v[98:101]
	v_mfma_f32_16x16x32_bf16 v[86:89], v[220:223], v[180:183], v[86:89]
	v_mfma_f32_16x16x32_bf16 v[82:85], v[228:231], v[180:183], v[82:85]
	v_mfma_f32_16x16x32_bf16 v[70:73], v[220:223], v[212:215], v[70:73]
	v_mfma_f32_16x16x32_bf16 v[66:69], v[228:231], v[212:215], v[66:69]
	s_setprio 0
	s_mov_b32 m0, s23
	s_barrier
	ds_read_b128 v[150:153], v189 offset:16384
	ds_read_b128 v[154:157], v189 offset:17408
	ds_read_b128 v[168:171], v189 offset:18432
	ds_read_b128 v[172:175], v189 offset:19456
	ds_read_b128 v[176:179], v189 offset:20480
	ds_read_b128 v[180:183], v189 offset:21504
	ds_read_b128 v[190:193], v189 offset:22528
	ds_read_b128 v[212:215], v189 offset:23552
	global_load_lds_dwordx4 v158, s[48:49]
	s_mov_b32 m0, s51
	s_nop 0
	global_load_lds_dwordx4 v160, s[48:49]
	s_barrier
; #define PG8_STAGE(bufoff, gbase, voff) do { _Pragma("unroll") for (int _i = 0; _i < 2; ++_i) \
;     __builtin_amdgcn_global_load_lds((const unsigned*)((const char*)(gbase) + (voff)[_i]), (LAS unsigned*)(lds + (bufoff) + ldsw + _i * 8192), 16, 0, 0); } while (0)
; #define PG8_LDA(dst, b, h) do { _Pragma("unroll") for (int m = 0; m < 4; ++m) _Pragma("unroll") for (int k = 0; k < 2; ++k) dst[m][k] = *(const LAS bf16x8*)(lds + PG8_SA(b, h) + aoff + m * 2048 + k * 1024); } while (0)
; #define PG8_LDB(dst, b, h) do { _Pragma("unroll") for (int n = 0; n < 2; ++n) _Pragma("unroll") for (int k = 0; k < 2; ++k) dst[n][k] = *(const LAS bf16x8*)(lds + PG8_SB(b, h) + boff + n * 2048 + k * 1024); } while (0)
; #define PG8_MMA(ai, bj, At, Bt) do { __builtin_amdgcn_s_setprio(1); _Pragma("unroll") for (int m = 0; m < 4; ++m) _Pragma("unroll") for (int n = 0; n < 2; ++n) _Pragma("unroll") for (int k = 0; k < 2; ++k) \
;     acc[ai][bj][m][n] = __builtin_amdgcn_mfma_f32_16x16x32_bf16(Bt[n][k], At[m][k], acc[ai][bj][m][n], 0, 0, 0); __builtin_amdgcn_s_setprio(0); } while (0)
; #define PG8_WAIT_V(n) asm volatile("s_waitcnt vmcnt(" #n ")" ::: "memory")
; #define PG8_WAIT_L(n) asm volatile("s_waitcnt lgkmcnt(" #n ")" ::: "memory")
; #define PG8_BAR __builtin_amdgcn_s_barrier()
; #define PG8_SCHED __builtin_amdgcn_sched_barrier(0)
; template <class Epi, bool SPLITA = false>
; __device__ __forceinline__ void gemm_phase(const int tid, LAS unsigned char* lds, const Gemm g, const Order& S, const Epi& E) {
;     ...
;       PG8_BAR; PG8_WAIT_L(0); PG8_MMA(1, 0, At, B0); PG8_BAR; PG8_SCHED;
;       PG8_STAGE(PG8_SB(0, 1), b2 + hstepB, voffB);
;       PG8_WAIT_V(6); PG8_BAR; PG8_MMA(1, 1, At, B1); PG8_BAR;
;       PG8_LDB(B0, 1, 0); PG8_SCHED; PG8_LDA(At, 1, 0); PG8_STAGE(PG8_SA(0, 1), a2 + hstepA, voffA);
;       PG8_WAIT_L(8); PG8_BAR; PG8_WAIT_L(0); PG8_MMA(0, 0, At, B0); PG8_BAR; PG8_SCHED;
;       PG8_LDB(B1, 1, 1); PG8_STAGE(PG8_SB(1, 0), b3, voffB);
;       PG8_BAR; PG8_WAIT_L(0); PG8_MMA(0, 1, At, B1); PG8_BAR;
	s_waitcnt lgkmcnt(0)
	s_setprio 1
	s_waitcnt lgkmcnt(0)
	v_mfma_f32_16x16x32_bf16 v[62:65], v[134:137], v[150:153], 0
	v_mfma_f32_16x16x32_bf16 v[58:61], v[142:145], v[150:153], 0
	v_mfma_f32_16x16x32_bf16 v[46:49], v[134:137], v[168:171], 0
	v_mfma_f32_16x16x32_bf16 v[42:45], v[142:145], v[168:171], 0
	v_mfma_f32_16x16x32_bf16 v[30:33], v[134:137], v[176:179], 0
	v_mfma_f32_16x16x32_bf16 v[26:29], v[142:145], v[176:179], 0
	v_mfma_f32_16x16x32_bf16 v[14:17], v[134:137], v[190:193], 0
	v_mfma_f32_16x16x32_bf16 v[10:13], v[142:145], v[190:193], 0
	v_mfma_f32_16x16x32_bf16 v[62:65], v[138:141], v[154:157], v[62:65]
	v_mfma_f32_16x16x32_bf16 v[58:61], v[146:149], v[154:157], v[58:61]
	v_mfma_f32_16x16x32_bf16 v[46:49], v[138:141], v[172:175], v[46:49]
	v_mfma_f32_16x16x32_bf16 v[42:45], v[146:149], v[172:175], v[42:45]
	v_mfma_f32_16x16x32_bf16 v[30:33], v[138:141], v[180:183], v[30:33]
	v_mfma_f32_16x16x32_bf16 v[26:29], v[146:149], v[180:183], v[26:29]
	v_mfma_f32_16x16x32_bf16 v[14:17], v[138:141], v[212:215], v[14:17]
	v_mfma_f32_16x16x32_bf16 v[10:13], v[146:149], v[212:215], v[10:13]
	s_setprio 0
	s_barrier
	s_add_u32 s20, s44, 0x80000
	s_addc_u32 s21, s45, 0
	s_add_i32 s8, s8, s3
	s_mov_b32 m0, s8
	s_nop 0
	global_load_lds_dwordx4 v0, s[20:21]
	s_add_i32 m0, s8, 0x2000
	s_nop 0
	global_load_lds_dwordx4 v162, s[20:21]
	s_waitcnt vmcnt(6)
	s_barrier
	s_setprio 1
	v_mfma_f32_16x16x32_bf16 v[54:57], v[216:219], v[150:153], 0
	v_mfma_f32_16x16x32_bf16 v[50:53], v[224:227], v[150:153], 0
	v_mfma_f32_16x16x32_bf16 v[38:41], v[216:219], v[168:171], 0
	v_mfma_f32_16x16x32_bf16 v[34:37], v[224:227], v[168:171], 0
	v_mfma_f32_16x16x32_bf16 v[22:25], v[216:219], v[176:179], 0
	v_mfma_f32_16x16x32_bf16 v[18:21], v[224:227], v[176:179], 0
	v_mfma_f32_16x16x32_bf16 v[6:9], v[216:219], v[190:193], 0
	v_mfma_f32_16x16x32_bf16 v[2:5], v[224:227], v[190:193], 0
	v_mfma_f32_16x16x32_bf16 v[54:57], v[220:223], v[154:157], v[54:57]
	v_mfma_f32_16x16x32_bf16 v[50:53], v[228:231], v[154:157], v[50:53]
	v_mfma_f32_16x16x32_bf16 v[38:41], v[220:223], v[172:175], v[38:41]
	v_mfma_f32_16x16x32_bf16 v[34:37], v[228:231], v[172:175], v[34:37]
	v_mfma_f32_16x16x32_bf16 v[22:25], v[220:223], v[180:183], v[22:25]
	v_mfma_f32_16x16x32_bf16 v[18:21], v[228:231], v[180:183], v[18:21]
	v_mfma_f32_16x16x32_bf16 v[6:9], v[220:223], v[212:215], v[6:9]
	v_mfma_f32_16x16x32_bf16 v[2:5], v[228:231], v[212:215], v[2:5]
	s_setprio 0
	s_add_i32 s8, 0, 0x18000
	v_add_u32_e32 v146, s8, v188
	s_barrier
	ds_read_b128 v[134:137], v146
	ds_read_b128 v[138:141], v146 offset:1024
	ds_read_b128 v[142:145], v146 offset:2048
	ds_read_b128 v[146:149], v146 offset:3072
	s_add_u32 s20, s48, 0x80000
	s_addc_u32 s21, s49, 0
	s_mov_b32 m0, s52
	ds_read_b128 v[150:153], v189 offset:32768
	ds_read_b128 v[154:157], v189 offset:33792
	ds_read_b128 v[168:171], v189 offset:34816
	ds_read_b128 v[172:175], v189 offset:35840
	ds_read_b128 v[176:179], v189 offset:36864
	ds_read_b128 v[180:183], v189 offset:37888
	ds_read_b128 v[190:193], v189 offset:38912
	ds_read_b128 v[212:215], v189 offset:39936
	global_load_lds_dwordx4 v158, s[20:21]
	s_mov_b32 m0, s53
	s_nop 0
	global_load_lds_dwordx4 v160, s[20:21]
	s_waitcnt lgkmcnt(8)
	s_barrier
	s_waitcnt lgkmcnt(0)
	s_setprio 1
	s_waitcnt lgkmcnt(0)
	v_mfma_f32_16x16x32_bf16 v[126:129], v[134:137], v[150:153], v[126:129]
	v_mfma_f32_16x16x32_bf16 v[122:125], v[142:145], v[150:153], v[122:125]
	v_mfma_f32_16x16x32_bf16 v[110:113], v[134:137], v[168:171], v[110:113]
	v_mfma_f32_16x16x32_bf16 v[106:109], v[142:145], v[168:171], v[106:109]
	v_mfma_f32_16x16x32_bf16 v[94:97], v[134:137], v[176:179], v[94:97]
	v_mfma_f32_16x16x32_bf16 v[90:93], v[142:145], v[176:179], v[90:93]
	v_mfma_f32_16x16x32_bf16 v[78:81], v[134:137], v[190:193], v[78:81]
	v_mfma_f32_16x16x32_bf16 v[74:77], v[142:145], v[190:193], v[74:77]
	v_mfma_f32_16x16x32_bf16 v[126:129], v[138:141], v[154:157], v[126:129]
	v_mfma_f32_16x16x32_bf16 v[122:125], v[146:149], v[154:157], v[122:125]
	v_mfma_f32_16x16x32_bf16 v[110:113], v[138:141], v[172:175], v[110:113]
	v_mfma_f32_16x16x32_bf16 v[106:109], v[146:149], v[172:175], v[106:109]
	v_mfma_f32_16x16x32_bf16 v[94:97], v[138:141], v[180:183], v[94:97]
	v_mfma_f32_16x16x32_bf16 v[90:93], v[146:149], v[180:183], v[90:93]
	v_mfma_f32_16x16x32_bf16 v[78:81], v[138:141], v[212:215], v[78:81]
	v_mfma_f32_16x16x32_bf16 v[74:77], v[146:149], v[212:215], v[74:77]
	s_setprio 0
	s_barrier
; #define PG8_STAGE(bufoff, gbase, voff) do { _Pragma("unroll") for (int _i = 0; _i < 2; ++_i) \
;     __builtin_amdgcn_global_load_lds((const unsigned*)((const char*)(gbase) + (voff)[_i]), (LAS unsigned*)(lds + (bufoff) + ldsw + _i * 8192), 16, 0, 0); } while (0)
; #define PG8_LDA(dst, b, h) do { _Pragma("unroll") for (int m = 0; m < 4; ++m) _Pragma("unroll") for (int k = 0; k < 2; ++k) dst[m][k] = *(const LAS bf16x8*)(lds + PG8_SA(b, h) + aoff + m * 2048 + k * 1024); } while (0)
; #define PG8_MMA(ai, bj, At, Bt) do { __builtin_amdgcn_s_setprio(1); _Pragma("unroll") for (int m = 0; m < 4; ++m) _Pragma("unroll") for (int n = 0; n < 2; ++n) _Pragma("unroll") for (int k = 0; k < 2; ++k) \
;     acc[ai][bj][m][n] = __builtin_amdgcn_mfma_f32_16x16x32_bf16(Bt[n][k], At[m][k], acc[ai][bj][m][n], 0, 0, 0); __builtin_amdgcn_s_setprio(0); } while (0)
; #define PG8_WAIT_V(n) asm volatile("s_waitcnt vmcnt(" #n ")" ::: "memory")
; #define PG8_WAIT_L(n) asm volatile("s_waitcnt lgkmcnt(" #n ")" ::: "memory")
; #define PG8_BAR __builtin_amdgcn_s_barrier()
; #define PG8_SCHED __builtin_amdgcn_sched_barrier(0)
; template <class Epi, bool SPLITA = false>
; __device__ __forceinline__ void gemm_phase(const int tid, LAS unsigned char* lds, const Gemm g, const Order& S, const Epi& E) {
;     ...
;       PG8_BAR; PG8_WAIT_L(0); PG8_MMA(0, 1, At, B1); PG8_BAR;
;       PG8_LDA(At, 1, 1); PG8_STAGE(PG8_SA(1, 0), a3, voffA);
;       PG8_BAR; PG8_WAIT_L(0); PG8_MMA(1, 0, At, B0); PG8_BAR; PG8_SCHED;
;       PG8_STAGE(PG8_SB(1, 1), b3 + hstepB, voffB);
;       PG8_WAIT_V(6); PG8_BAR; PG8_MMA(1, 1, At, B1); PG8_BAR;
;     }
	s_add_i32 s9, 0, 0x1c000
	s_add_i32 s8, s8, s3
	v_add_u32_e32 v195, s9, v188
	s_add_i32 m0, s8, 0xffffff80
	ds_read_b128 v[216:219], v195
	ds_read_b128 v[220:223], v195 offset:1024
	ds_read_b128 v[224:227], v195 offset:2048
	ds_read_b128 v[228:231], v195 offset:3072
	global_load_lds_dwordx4 v0, s[44:45] offset:128
	s_add_i32 m0, s8, 0x1f80
	s_nop 0
	global_load_lds_dwordx4 v162, s[44:45] offset:128
	s_barrier
	s_waitcnt lgkmcnt(0)
	s_setprio 1
	s_waitcnt lgkmcnt(0)
	v_mfma_f32_16x16x32_bf16 v[118:121], v[216:219], v[150:153], v[118:121]
	v_mfma_f32_16x16x32_bf16 v[114:117], v[224:227], v[150:153], v[114:117]
	v_mfma_f32_16x16x32_bf16 v[102:105], v[216:219], v[168:171], v[102:105]
	v_mfma_f32_16x16x32_bf16 v[98:101], v[224:227], v[168:171], v[98:101]
	v_mfma_f32_16x16x32_bf16 v[86:89], v[216:219], v[176:179], v[86:89]
	v_mfma_f32_16x16x32_bf16 v[82:85], v[224:227], v[176:179], v[82:85]
	v_mfma_f32_16x16x32_bf16 v[70:73], v[216:219], v[190:193], v[70:73]
	v_mfma_f32_16x16x32_bf16 v[66:69], v[224:227], v[190:193], v[66:69]
	v_mfma_f32_16x16x32_bf16 v[118:121], v[220:223], v[154:157], v[118:121]
	v_mfma_f32_16x16x32_bf16 v[114:117], v[228:231], v[154:157], v[114:117]
	v_mfma_f32_16x16x32_bf16 v[102:105], v[220:223], v[172:175], v[102:105]
	v_mfma_f32_16x16x32_bf16 v[98:101], v[228:231], v[172:175], v[98:101]
	v_mfma_f32_16x16x32_bf16 v[86:89], v[220:223], v[180:183], v[86:89]
	v_mfma_f32_16x16x32_bf16 v[82:85], v[228:231], v[180:183], v[82:85]
	v_mfma_f32_16x16x32_bf16 v[70:73], v[220:223], v[212:215], v[70:73]
	v_mfma_f32_16x16x32_bf16 v[66:69], v[228:231], v[212:215], v[66:69]
	s_setprio 0
	s_mov_b32 m0, s91
	s_barrier
	ds_read_b128 v[150:153], v189 offset:49152
	ds_read_b128 v[154:157], v189 offset:50176
	ds_read_b128 v[168:171], v189 offset:51200
	ds_read_b128 v[172:175], v189 offset:52224
	ds_read_b128 v[176:179], v189 offset:53248
	ds_read_b128 v[180:183], v189 offset:54272
	ds_read_b128 v[190:193], v189 offset:55296
	ds_read_b128 v[212:215], v189 offset:56320
	global_load_lds_dwordx4 v158, s[46:47]
	s_mov_b32 m0, s93
	s_nop 0
	global_load_lds_dwordx4 v160, s[46:47]
	s_barrier
	s_waitcnt lgkmcnt(0)
	s_setprio 1
	s_waitcnt lgkmcnt(0)
	v_mfma_f32_16x16x32_bf16 v[62:65], v[134:137], v[150:153], v[62:65]
	v_mfma_f32_16x16x32_bf16 v[58:61], v[142:145], v[150:153], v[58:61]
	v_mfma_f32_16x16x32_bf16 v[46:49], v[134:137], v[168:171], v[46:49]
	v_mfma_f32_16x16x32_bf16 v[42:45], v[142:145], v[168:171], v[42:45]
	v_mfma_f32_16x16x32_bf16 v[30:33], v[134:137], v[176:179], v[30:33]
	v_mfma_f32_16x16x32_bf16 v[26:29], v[142:145], v[176:179], v[26:29]
	v_mfma_f32_16x16x32_bf16 v[14:17], v[134:137], v[190:193], v[14:17]
	v_mfma_f32_16x16x32_bf16 v[10:13], v[142:145], v[190:193], v[10:13]
	v_mfma_f32_16x16x32_bf16 v[62:65], v[138:141], v[154:157], v[62:65]
	v_mfma_f32_16x16x32_bf16 v[58:61], v[146:149], v[154:157], v[58:61]
	v_mfma_f32_16x16x32_bf16 v[46:49], v[138:141], v[172:175], v[46:49]
	v_mfma_f32_16x16x32_bf16 v[42:45], v[146:149], v[172:175], v[42:45]
	v_mfma_f32_16x16x32_bf16 v[30:33], v[138:141], v[180:183], v[30:33]
	v_mfma_f32_16x16x32_bf16 v[26:29], v[146:149], v[180:183], v[26:29]
	v_mfma_f32_16x16x32_bf16 v[14:17], v[138:141], v[212:215], v[14:17]
	v_mfma_f32_16x16x32_bf16 v[10:13], v[146:149], v[212:215], v[10:13]
	s_setprio 0
	s_barrier
	s_add_u32 s20, s44, 0x80080
	s_addc_u32 s21, s45, 0
	s_add_i32 s8, s9, s3
	s_mov_b32 m0, s8
	s_nop 0
	global_load_lds_dwordx4 v0, s[20:21]
	s_add_i32 m0, s8, 0x2000
	s_nop 0
	global_load_lds_dwordx4 v162, s[20:21]
	s_waitcnt vmcnt(6)
	s_barrier
	s_setprio 1
	v_mfma_f32_16x16x32_bf16 v[54:57], v[216:219], v[150:153], v[54:57]
	v_mfma_f32_16x16x32_bf16 v[50:53], v[224:227], v[150:153], v[50:53]
	v_mfma_f32_16x16x32_bf16 v[38:41], v[216:219], v[168:171], v[38:41]
	v_mfma_f32_16x16x32_bf16 v[34:37], v[224:227], v[168:171], v[34:37]
	v_mfma_f32_16x16x32_bf16 v[22:25], v[216:219], v[176:179], v[22:25]
	v_mfma_f32_16x16x32_bf16 v[18:21], v[224:227], v[176:179], v[18:21]
	v_mfma_f32_16x16x32_bf16 v[6:9], v[216:219], v[190:193], v[6:9]
	v_mfma_f32_16x16x32_bf16 v[2:5], v[224:227], v[190:193], v[2:5]
	v_mfma_f32_16x16x32_bf16 v[54:57], v[220:223], v[154:157], v[54:57]
	v_mfma_f32_16x16x32_bf16 v[50:53], v[228:231], v[154:157], v[50:53]
	v_mfma_f32_16x16x32_bf16 v[38:41], v[220:223], v[172:175], v[38:41]
	v_mfma_f32_16x16x32_bf16 v[34:37], v[228:231], v[172:175], v[34:37]
	v_mfma_f32_16x16x32_bf16 v[22:25], v[220:223], v[180:183], v[22:25]
	v_mfma_f32_16x16x32_bf16 v[18:21], v[228:231], v[180:183], v[18:21]
	v_mfma_f32_16x16x32_bf16 v[6:9], v[220:223], v[212:215], v[6:9]
	v_mfma_f32_16x16x32_bf16 v[2:5], v[228:231], v[212:215], v[2:5]
	s_setprio 0
	s_add_i32 s29, s29, 2
	s_add_u32 s42, s42, 0x100
	s_addc_u32 s43, s43, 0
	s_cmp_gt_u32 s29, 29
	s_barrier
	s_cbranch_scc0 .LBB0_192
	s_branch .Lpeel_exit_192

; __device__ __forceinline__ float bflo(unsigned w) { return __uint_as_float(w << 16); }
; __device__ __forceinline__ float bfhi(unsigned w) { return __uint_as_float(w & 0xffff0000u); }
; __device__ __forceinline__ float lane_read(float v, int src) { return __int_as_float(__builtin_amdgcn_ds_bpermute(src << 2, __float_as_int(v))); }
; __device__ __forceinline__ u32x4 pack8(const f32x4 v0, const f32x4 v1) { u32x4 w; w.x = cvtpk(v0[0], v0[1]); w.y = cvtpk(v0[2], v0[3]); w.z = cvtpk(v1[0], v1[1]); w.w = cvtpk(v1[2], v1[3]); return w; }
;   __device__ __forceinline__ void operator()(const Acc& acc, const Unit& u, int wr, int wc, int fr_, int fq_) const {
;     int fr = fr_, fq = fq_; asm volatile("" : "+v"(fr), "+v"(fq));
;     const int lane = fq * 16 + fr;
;     const int row0 = u.pm * BM + wr * 64 + fr, col0 = u.pn * BM + wc * 32 + 8 * fq;
; #pragma unroll
;     for (int ai = 0; ai < 2; ++ai) {
;       u32x4 hv[4][2];
; #pragma unroll
;       for (int m = 0; m < 4; ++m)
; #pragma unroll
;         for (int bj = 0; bj < 2; ++bj) hv[m][bj] = *(const u32x4*)(rin + (size_t)(row0 + ai * HALF + m * 16) * DM + col0 + bj * HALF);
; #pragma unroll
;       for (int m = 0; m < 4; ++m) { const size_t ro = (size_t)(row0 + ai * HALF + m * 16) * DM + col0; float ss = 0.f;
; #pragma unroll
;         for (int bj = 0; bj < 2; ++bj) { const u32x4 h = hv[m][bj];
;           f32x4 v0 = acc[ai][bj][m][0], v1 = acc[ai][bj][m][1];
;           v0[0] += bflo(h.x); v0[1] += bfhi(h.x); v0[2] += bflo(h.y); v0[3] += bfhi(h.y);
;           v1[0] += bflo(h.z); v1[1] += bfhi(h.z); v1[2] += bflo(h.w); v1[3] += bfhi(h.w);
;           if (FINAL) { *(f32x4*)(outf + ro + bj * HALF) = v0; *(f32x4*)(outf + ro + bj * HALF + 4) = v1; }
;           else { ss += v0[0] * v0[0] + v0[1] * v0[1] + v0[2] * v0[2] + v0[3] * v0[3] + v1[0] * v1[0] + v1[1] * v1[1] + v1[2] * v1[2] + v1[3] * v1[3];
;             *(u32x4*)(outb + ro + bj * HALF) = pack8(v0, v1); } }
;         if (!FINAL) { ss += lane_read(ss, lane ^ 16); ss += lane_read(ss, lane ^ 32);
;           if (fq == 0) rss[(size_t)(row0 + ai * HALF + m * 16) * 32 + u.pn * 4 + wc] = ss; } }
.Lpeel_exit_192:
	s_lshl_b32 s4, s22, 8
	v_mov_b32_e32 v130, v187
	v_mov_b32_e32 v131, v186
	s_add_i32 s4, s4, s55
	s_nop 0
	v_add_u32_e32 v170, s4, v130
	s_lshl_b32 s4, s18, 8
	s_or_b32 s4, s4, s90
	v_lshl_add_u32 v168, v131, 3, s4
	v_ashrrev_i32_e32 v169, 31, v168
	v_lshlrev_b32_e32 v130, 2, v130
	v_lshlrev_b64 v[192:193], 1, v[168:169]
	v_ashrrev_i32_e32 v171, 31, v170
	v_lshl_add_u32 v130, v131, 6, v130
	v_lshl_add_u64 v[172:173], s[86:87], 0, v[192:193]
	v_lshlrev_b64 v[198:199], 12, v[170:171]
	v_xor_b32_e32 v191, 64, v130
	v_xor_b32_e32 v190, 0x80, v130
	v_cmp_eq_u32_e32 vcc, 0, v131
	v_lshl_add_u64 v[130:131], v[172:173], 0, v[198:199]
	global_load_dwordx4 v[212:215], v[130:131], off
	global_load_dwordx4 v[154:157], v[130:131], off offset:256
	v_add_u32_e32 v182, 16, v170
	v_ashrrev_i32_e32 v183, 31, v182
	v_add_u32_e32 v178, 32, v170
	v_lshlrev_b64 v[184:185], 12, v[182:183]
	v_ashrrev_i32_e32 v179, 31, v178
	v_add_u32_e32 v174, 48, v170
	v_lshl_add_u64 v[130:131], v[172:173], 0, v[184:185]
	v_lshlrev_b64 v[180:181], 12, v[178:179]
	v_ashrrev_i32_e32 v175, 31, v174
	global_load_dwordx4 v[150:153], v[130:131], off
	global_load_dwordx4 v[146:149], v[130:131], off offset:256
	v_lshl_add_u64 v[130:131], v[172:173], 0, v[180:181]
	v_lshlrev_b64 v[176:177], 12, v[174:175]
	global_load_dwordx4 v[142:145], v[130:131], off
	global_load_dwordx4 v[138:141], v[130:131], off offset:256
	v_lshl_add_u64 v[130:131], v[172:173], 0, v[176:177]
	global_load_dwordx4 v[134:137], v[130:131], off
	s_nop 0
	global_load_dwordx4 v[130:133], v[130:131], off offset:256
	s_lshl_b32 s18, s18, 2
	s_ashr_i32 s19, s18, 31
	s_waitcnt vmcnt(0)
	v_lshlrev_b32_e32 v200, 16, v212
	v_and_b32_e32 v201, 0xffff0000, v212
	v_pk_add_f32 v[126:127], v[126:127], v[200:201]
	v_lshlrev_b32_e32 v200, 16, v213
	v_and_b32_e32 v201, 0xffff0000, v213
	v_pk_add_f32 v[128:129], v[128:129], v[200:201]
	v_lshlrev_b32_e32 v200, 16, v214
	v_and_b32_e32 v201, 0xffff0000, v214
	v_pk_add_f32 v[200:201], v[122:123], v[200:201]
	v_lshlrev_b32_e32 v122, 16, v215
	v_and_b32_e32 v123, 0xffff0000, v215
	v_pk_add_f32 v[202:203], v[124:125], v[122:123]
	v_pk_mul_f32 v[204:205], v[126:127], v[126:127]
	v_cvt_pk_bf16_f32 v122, v126, v127
	v_lshl_add_u64 v[126:127], s[0:1], 0, v[198:199]
	v_cvt_pk_bf16_f32 v123, v128, v129
	v_cvt_pk_bf16_f32 v124, v200, v201
	v_cvt_pk_bf16_f32 v125, v202, v203
	v_lshl_add_u64 v[126:127], v[126:127], 0, v[192:193]
	global_store_dwordx4 v[126:127], v[122:125], off
	v_pk_mul_f32 v[206:207], v[128:129], v[128:129]
	v_pk_mul_f32 v[212:213], v[200:201], v[200:201]
	v_lshlrev_b32_e32 v122, 16, v154
	v_and_b32_e32 v123, 0xffff0000, v154
	v_pk_add_f32 v[118:119], v[118:119], v[122:123]
	v_lshlrev_b32_e32 v122, 16, v155
	v_and_b32_e32 v123, 0xffff0000, v155
	v_pk_add_f32 v[120:121], v[120:121], v[122:123]
	v_lshlrev_b32_e32 v122, 16, v156
	v_and_b32_e32 v123, 0xffff0000, v156
	v_pk_add_f32 v[122:123], v[114:115], v[122:123]
	v_lshlrev_b32_e32 v114, 16, v157
	v_and_b32_e32 v115, 0xffff0000, v157
	v_pk_add_f32 v[124:125], v[116:117], v[114:115]
	v_pk_mul_f32 v[114:115], v[118:119], v[118:119]
	v_pk_mul_f32 v[116:117], v[120:121], v[120:121]
	v_add_f32_e32 v114, v114, v115
	v_add_f32_e32 v115, v204, v205
	v_add_f32_e32 v114, v116, v114
	v_add_f32_e32 v115, v206, v115
	v_pk_mul_f32 v[128:129], v[122:123], v[122:123]
	v_add_f32_e32 v114, v117, v114
	v_add_f32_e32 v115, v207, v115
	v_add_f32_e32 v114, v128, v114
	v_add_f32_e32 v115, v212, v115
	v_pk_mul_f32 v[214:215], v[202:203], v[202:203]
	v_pk_mul_f32 v[154:155], v[124:125], v[124:125]
	v_add_f32_e32 v114, v129, v114
	v_add_f32_e32 v115, v213, v115
	v_add_f32_e32 v114, v154, v114
	v_add_f32_e32 v115, v214, v115
	v_add_f32_e32 v114, v155, v114
	v_add_f32_e32 v115, v215, v115
	v_add_f32_e32 v128, v115, v114
	v_cvt_pk_bf16_f32 v114, v118, v119
	v_cvt_pk_bf16_f32 v115, v120, v121
	v_cvt_pk_bf16_f32 v116, v122, v123
	v_cvt_pk_bf16_f32 v117, v124, v125
	global_store_dwordx4 v[126:127], v[114:117], off offset:256
	ds_bpermute_b32 v114, v191, v128
	s_waitcnt lgkmcnt(0)
	v_add_f32_e32 v114, v128, v114
	ds_bpermute_b32 v115, v190, v114
	s_and_saveexec_b64 s[6:7], vcc
	s_cbranch_execz .LBB0_195
	v_readlane_b32 s8, v255, 1
	v_lshlrev_b64 v[116:117], 7, v[170:171]
	v_readlane_b32 s9, v255, 2
	s_lshl_b32 s4, s54, 2
	s_waitcnt lgkmcnt(0)
	v_add_f32_e32 v114, v114, v115
	v_lshl_add_u64 v[116:117], s[8:9], 0, v[116:117]
	v_lshl_add_u64 v[116:117], s[18:19], 2, v[116:117]
	v_lshl_add_u64 v[116:117], v[116:117], 0, s[4:5]
	global_store_dword v[116:117], v114, off

; #define PG8_STAGE(bufoff, gbase, voff) do { _Pragma("unroll") for (int _i = 0; _i < 2; ++_i) \
;     __builtin_amdgcn_global_load_lds((const unsigned*)((const char*)(gbase) + (voff)[_i]), (LAS unsigned*)(lds + (bufoff) + ldsw + _i * 8192), 16, 0, 0); } while (0)
; #define PG8_LDA(dst, b, h) do { _Pragma("unroll") for (int m = 0; m < 4; ++m) _Pragma("unroll") for (int k = 0; k < 2; ++k) dst[m][k] = *(const LAS bf16x8*)(lds + PG8_SA(b, h) + aoff + m * 2048 + k * 1024); } while (0)
; #define PG8_LDB(dst, b, h) do { _Pragma("unroll") for (int n = 0; n < 2; ++n) _Pragma("unroll") for (int k = 0; k < 2; ++k) dst[n][k] = *(const LAS bf16x8*)(lds + PG8_SB(b, h) + boff + n * 2048 + k * 1024); } while (0)
; #define PG8_WAIT_L(n) asm volatile("s_waitcnt lgkmcnt(" #n ")" ::: "memory")
; #define PG8_BAR __builtin_amdgcn_s_barrier()
; #define PG8_SCHED __builtin_amdgcn_sched_barrier(0)
; template <class Epi, bool SPLITA = false>
; __device__ __forceinline__ void gemm_phase(const int tid, LAS unsigned char* lds, const Gemm g, const Order& S, const Epi& E) {
;     ...
;     const bool has_next = S.next(ui + 1, nxt);
;     const char* nA = has_next ? (const char*)g.A + (size_t)nxt.pm * tstepA + (size_t)nxt.pn * apn : cA; const char* nA2 = (SPLITA && has_next) ? (const char*)g.A2 + (size_t)nxt.pm * tstepA : cA2; const char* nB = has_next ? (const char*)g.Bt + (size_t)nxt.pn * tstepB : cB;
;     for (int t = 0; t < nt; t += 2) {
;       const bool last = (t == nt - 2);
;       if constexpr (SPLITA) { if (t == nt1) E.mid(acc, cur, wr, wc, fr, fq); }
;       const char* a1 = PG8_TA(t + 1);
;       const char* a2 = last ? nA : PG8_TA(t + 2); const char* b2 = last ? nB : cB + (size_t)(t + 2) * kstep;
;       const char* a3 = last ? nA + kstep : PG8_TA(t + 3); const char* b3 = b2 + kstep;
;       PG8_LDB(B0, 0, 0); PG8_SCHED; PG8_LDA(At, 0, 0); PG8_STAGE(PG8_SA(1, 1), a1 + hstepA, voffA);
;       PG8_WAIT_L(8); PG8_BAR; PG8_WAIT_L(0); PG8_MMA(0, 0, At, B0); PG8_BAR; PG8_SCHED;
;       PG8_LDB(B1, 0, 1); PG8_STAGE(PG8_SB(0, 0), b2, voffB);
;       PG8_BAR; PG8_WAIT_L(0); PG8_MMA(0, 1, At, B1); PG8_BAR;
;       PG8_LDA(At, 0, 1); PG8_STAGE(PG8_SA(0, 0), a2, voffA);
;       PG8_BAR; PG8_WAIT_L(0); PG8_MMA(1, 0, At, B0); PG8_BAR; PG8_SCHED;
.LBB0_327:
	s_add_u32 s40, s0, 0x80
	s_addc_u32 s41, s1, 0
	s_add_u32 s55, s10, 0x100
	s_addc_u32 s90, s11, 0
	s_add_u32 s10, s8, 0x88080
	s_addc_u32 s11, s9, 0
	v_mov_b32_e32 v2, 0
	v_lshl_add_u64 v[140:141], s[10:11], 0, v[136:137]
	v_lshl_add_u64 v[142:143], s[10:11], 0, v[138:139]
	s_mov_b32 s91, -2
	s_mov_b64 s[10:11], 0
	s_add_u32 s12, s8, s10
	s_addc_u32 s13, s9, s11
	s_add_u32 s16, s12, 0x100
	s_addc_u32 s17, s13, 0
	s_add_u32 s20, s55, s10
	s_addc_u32 s21, s90, s11
	s_add_u32 s12, s12, 0x180
	s_addc_u32 s13, s13, 0
	s_add_i32 s22, 0, 0x10000
	v_add_u32_e32 v160, s22, v146
	ds_read_b128 v[148:151], v160
	ds_read_b128 v[152:155], v160 offset:1024
	ds_read_b128 v[156:159], v160 offset:2048
	ds_read_b128 v[160:163], v160 offset:3072
	s_cmpk_eq_i32 s10, 0x1000
	s_cselect_b32 s15, s41, s13
	s_cselect_b32 s14, s40, s12
	s_cselect_b32 s13, s7, s21
	s_cselect_b32 s12, s6, s20
	s_cselect_b32 s17, s1, s17
	s_cselect_b32 s16, s0, s16
	v_lshl_add_u64 v[192:193], v[140:141], 0, s[10:11]
	s_add_i32 m0, s30, 0xc000
	ds_read_b128 v[164:167], v147
	ds_read_b128 v[168:171], v147 offset:1024
	ds_read_b128 v[172:175], v147 offset:2048
	ds_read_b128 v[176:179], v147 offset:3072
	ds_read_b128 v[180:183], v147 offset:4096
	ds_read_b128 v[184:187], v147 offset:5120
	ds_read_b128 v[188:191], v147 offset:6144
	ds_read_b128 v[212:215], v147 offset:7168
	global_load_lds_dwordx4 v[192:193], off
	v_lshl_add_u64 v[192:193], v[142:143], 0, s[10:11]
	s_add_i32 m0, s30, 0xe000
	s_nop 0
	global_load_lds_dwordx4 v[192:193], off
	s_waitcnt lgkmcnt(8)
	s_barrier
	s_waitcnt lgkmcnt(0)
	s_setprio 1
	s_waitcnt lgkmcnt(0)
	v_mfma_f32_16x16x32_bf16 v[126:129], v[148:151], v[164:167], 0
	v_mfma_f32_16x16x32_bf16 v[122:125], v[156:159], v[164:167], 0
	v_mfma_f32_16x16x32_bf16 v[110:113], v[148:151], v[172:175], 0
	v_mfma_f32_16x16x32_bf16 v[106:109], v[156:159], v[172:175], 0
	v_mfma_f32_16x16x32_bf16 v[94:97], v[148:151], v[180:183], 0
	v_mfma_f32_16x16x32_bf16 v[90:93], v[156:159], v[180:183], 0
	v_mfma_f32_16x16x32_bf16 v[78:81], v[148:151], v[188:191], 0
	v_mfma_f32_16x16x32_bf16 v[74:77], v[156:159], v[188:191], 0
	v_mfma_f32_16x16x32_bf16 v[126:129], v[152:155], v[168:171], v[126:129]
	v_mfma_f32_16x16x32_bf16 v[122:125], v[160:163], v[168:171], v[122:125]
	v_mfma_f32_16x16x32_bf16 v[110:113], v[152:155], v[176:179], v[110:113]
	v_mfma_f32_16x16x32_bf16 v[106:109], v[160:163], v[176:179], v[106:109]
	v_mfma_f32_16x16x32_bf16 v[94:97], v[152:155], v[184:187], v[94:97]
	v_mfma_f32_16x16x32_bf16 v[90:93], v[160:163], v[184:187], v[90:93]
	v_mfma_f32_16x16x32_bf16 v[78:81], v[152:155], v[212:215], v[78:81]
	v_mfma_f32_16x16x32_bf16 v[74:77], v[160:163], v[212:215], v[74:77]
	s_setprio 0
	s_barrier
	s_add_i32 s20, 0, 0x14000
	v_add_u32_e32 v192, s20, v146
	s_add_i32 s21, s22, s18
	ds_read_b128 v[216:219], v192
	ds_read_b128 v[220:223], v192 offset:1024
	ds_read_b128 v[224:227], v192 offset:2048
	ds_read_b128 v[228:231], v192 offset:3072
	s_mov_b32 m0, s21
	s_nop 0
	global_load_lds_dwordx4 v0, s[12:13]
	s_add_i32 m0, s21, 0x2000
	s_nop 0
	global_load_lds_dwordx4 v134, s[12:13]
	s_barrier
	s_waitcnt lgkmcnt(0)
	s_setprio 1
	s_waitcnt lgkmcnt(0)
	v_mfma_f32_16x16x32_bf16 v[118:121], v[216:219], v[164:167], 0
	v_mfma_f32_16x16x32_bf16 v[114:117], v[224:227], v[164:167], 0
	v_mfma_f32_16x16x32_bf16 v[102:105], v[216:219], v[172:175], 0
	v_mfma_f32_16x16x32_bf16 v[98:101], v[224:227], v[172:175], 0
	v_mfma_f32_16x16x32_bf16 v[86:89], v[216:219], v[180:183], 0
	v_mfma_f32_16x16x32_bf16 v[82:85], v[224:227], v[180:183], 0
	v_mfma_f32_16x16x32_bf16 v[70:73], v[216:219], v[188:191], 0
	v_mfma_f32_16x16x32_bf16 v[66:69], v[224:227], v[188:191], 0
	v_mfma_f32_16x16x32_bf16 v[118:121], v[220:223], v[168:171], v[118:121]
	v_mfma_f32_16x16x32_bf16 v[114:117], v[228:231], v[168:171], v[114:117]
	v_mfma_f32_16x16x32_bf16 v[102:105], v[220:223], v[176:179], v[102:105]
	v_mfma_f32_16x16x32_bf16 v[98:101], v[228:231], v[176:179], v[98:101]
	v_mfma_f32_16x16x32_bf16 v[86:89], v[220:223], v[184:187], v[86:89]
	v_mfma_f32_16x16x32_bf16 v[82:85], v[228:231], v[184:187], v[82:85]
	v_mfma_f32_16x16x32_bf16 v[70:73], v[220:223], v[212:215], v[70:73]
	v_mfma_f32_16x16x32_bf16 v[66:69], v[228:231], v[212:215], v[66:69]
	s_setprio 0
	s_mov_b32 m0, s30
	s_barrier
	ds_read_b128 v[164:167], v147 offset:16384
	ds_read_b128 v[168:171], v147 offset:17408
	ds_read_b128 v[172:175], v147 offset:18432
	ds_read_b128 v[176:179], v147 offset:19456
	ds_read_b128 v[180:183], v147 offset:20480
	ds_read_b128 v[184:187], v147 offset:21504
	ds_read_b128 v[188:191], v147 offset:22528
	ds_read_b128 v[212:215], v147 offset:23552
	global_load_lds_dwordx4 v130, s[16:17]
	s_mov_b32 m0, s31
	s_nop 0
	global_load_lds_dwordx4 v132, s[16:17]
	s_barrier
	s_waitcnt lgkmcnt(0)
	s_setprio 1
	s_waitcnt lgkmcnt(0)
	v_mfma_f32_16x16x32_bf16 v[62:65], v[148:151], v[164:167], 0
	v_mfma_f32_16x16x32_bf16 v[58:61], v[156:159], v[164:167], 0
	v_mfma_f32_16x16x32_bf16 v[46:49], v[148:151], v[172:175], 0
	v_mfma_f32_16x16x32_bf16 v[42:45], v[156:159], v[172:175], 0
	v_mfma_f32_16x16x32_bf16 v[30:33], v[148:151], v[180:183], 0
	v_mfma_f32_16x16x32_bf16 v[26:29], v[156:159], v[180:183], 0
	v_mfma_f32_16x16x32_bf16 v[14:17], v[148:151], v[188:191], 0
	v_mfma_f32_16x16x32_bf16 v[10:13], v[156:159], v[188:191], 0
	v_mfma_f32_16x16x32_bf16 v[62:65], v[152:155], v[168:171], v[62:65]
	v_mfma_f32_16x16x32_bf16 v[58:61], v[160:163], v[168:171], v[58:61]
	v_mfma_f32_16x16x32_bf16 v[46:49], v[152:155], v[176:179], v[46:49]
	v_mfma_f32_16x16x32_bf16 v[42:45], v[160:163], v[176:179], v[42:45]
	v_mfma_f32_16x16x32_bf16 v[30:33], v[152:155], v[184:187], v[30:33]
	v_mfma_f32_16x16x32_bf16 v[26:29], v[160:163], v[184:187], v[26:29]
	v_mfma_f32_16x16x32_bf16 v[14:17], v[152:155], v[212:215], v[14:17]
	v_mfma_f32_16x16x32_bf16 v[10:13], v[160:163], v[212:215], v[10:13]
	s_setprio 0
	s_barrier
; #define PG8_STAGE(bufoff, gbase, voff) do { _Pragma("unroll") for (int _i = 0; _i < 2; ++_i) \
;     __builtin_amdgcn_global_load_lds((const unsigned*)((const char*)(gbase) + (voff)[_i]), (LAS unsigned*)(lds + (bufoff) + ldsw + _i * 8192), 16, 0, 0); } while (0)
; #define PG8_LDA(dst, b, h) do { _Pragma("unroll") for (int m = 0; m < 4; ++m) _Pragma("unroll") for (int k = 0; k < 2; ++k) dst[m][k] = *(const LAS bf16x8*)(lds + PG8_SA(b, h) + aoff + m * 2048 + k * 1024); } while (0)
; #define PG8_LDB(dst, b, h) do { _Pragma("unroll") for (int n = 0; n < 2; ++n) _Pragma("unroll") for (int k = 0; k < 2; ++k) dst[n][k] = *(const LAS bf16x8*)(lds + PG8_SB(b, h) + boff + n * 2048 + k * 1024); } while (0)
; #define PG8_MMA(ai, bj, At, Bt) do { __builtin_amdgcn_s_setprio(1); _Pragma("unroll") for (int m = 0; m < 4; ++m) _Pragma("unroll") for (int n = 0; n < 2; ++n) _Pragma("unroll") for (int k = 0; k < 2; ++k) \
;     acc[ai][bj][m][n] = __builtin_amdgcn_mfma_f32_16x16x32_bf16(Bt[n][k], At[m][k], acc[ai][bj][m][n], 0, 0, 0); __builtin_amdgcn_s_setprio(0); } while (0)
; #define PG8_WAIT_V(n) asm volatile("s_waitcnt vmcnt(" #n ")" ::: "memory")
; #define PG8_WAIT_L(n) asm volatile("s_waitcnt lgkmcnt(" #n ")" ::: "memory")
; #define PG8_BAR __builtin_amdgcn_s_barrier()
; #define PG8_SCHED __builtin_amdgcn_sched_barrier(0)
; template <class Epi, bool SPLITA = false>
; __device__ __forceinline__ void gemm_phase(const int tid, LAS unsigned char* lds, const Gemm g, const Order& S, const Epi& E) {
;     ...
;       PG8_BAR; PG8_WAIT_L(0); PG8_MMA(1, 0, At, B0); PG8_BAR; PG8_SCHED;
;       PG8_STAGE(PG8_SB(0, 1), b2 + hstepB, voffB);
;       PG8_WAIT_V(6); PG8_BAR; PG8_MMA(1, 1, At, B1); PG8_BAR;
;       PG8_LDB(B0, 1, 0); PG8_SCHED; PG8_LDA(At, 1, 0); PG8_STAGE(PG8_SA(0, 1), a2 + hstepA, voffA);
;       PG8_WAIT_L(8); PG8_BAR; PG8_WAIT_L(0); PG8_MMA(0, 0, At, B0); PG8_BAR; PG8_SCHED;
;       PG8_LDB(B1, 1, 1); PG8_STAGE(PG8_SB(1, 0), b3, voffB);
;       PG8_BAR; PG8_WAIT_L(0); PG8_MMA(0, 1, At, B1); PG8_BAR;
	s_add_u32 s22, s12, 0x88000
	s_addc_u32 s23, s13, 0
	s_add_i32 s20, s20, s18
	s_mov_b32 m0, s20
	s_nop 0
	global_load_lds_dwordx4 v0, s[22:23]
	s_add_i32 m0, s20, 0x2000
	s_nop 0
	global_load_lds_dwordx4 v134, s[22:23]
	s_waitcnt vmcnt(6)
	s_barrier
	s_setprio 1
	v_mfma_f32_16x16x32_bf16 v[54:57], v[216:219], v[164:167], 0
	v_mfma_f32_16x16x32_bf16 v[50:53], v[224:227], v[164:167], 0
	v_mfma_f32_16x16x32_bf16 v[38:41], v[216:219], v[172:175], 0
	v_mfma_f32_16x16x32_bf16 v[34:37], v[224:227], v[172:175], 0
	v_mfma_f32_16x16x32_bf16 v[22:25], v[216:219], v[180:183], 0
	v_mfma_f32_16x16x32_bf16 v[18:21], v[224:227], v[180:183], 0
	v_mfma_f32_16x16x32_bf16 v[6:9], v[216:219], v[188:191], 0
	v_mfma_f32_16x16x32_bf16 v[2:5], v[224:227], v[188:191], 0
	v_mfma_f32_16x16x32_bf16 v[54:57], v[220:223], v[168:171], v[54:57]
	v_mfma_f32_16x16x32_bf16 v[50:53], v[228:231], v[168:171], v[50:53]
	v_mfma_f32_16x16x32_bf16 v[38:41], v[220:223], v[176:179], v[38:41]
	v_mfma_f32_16x16x32_bf16 v[34:37], v[228:231], v[176:179], v[34:37]
	v_mfma_f32_16x16x32_bf16 v[22:25], v[220:223], v[184:187], v[22:25]
	v_mfma_f32_16x16x32_bf16 v[18:21], v[228:231], v[184:187], v[18:21]
	v_mfma_f32_16x16x32_bf16 v[6:9], v[220:223], v[212:215], v[6:9]
	v_mfma_f32_16x16x32_bf16 v[2:5], v[228:231], v[212:215], v[2:5]
	s_setprio 0
	s_add_i32 s20, 0, 0x18000
	v_add_u32_e32 v160, s20, v146
	s_barrier
	ds_read_b128 v[148:151], v160
	ds_read_b128 v[152:155], v160 offset:1024
	ds_read_b128 v[156:159], v160 offset:2048
	ds_read_b128 v[160:163], v160 offset:3072
	s_add_u32 s16, s16, 0x88000
	s_addc_u32 s17, s17, 0
	s_mov_b32 m0, s42
	ds_read_b128 v[164:167], v147 offset:32768
	ds_read_b128 v[168:171], v147 offset:33792
	ds_read_b128 v[172:175], v147 offset:34816
	ds_read_b128 v[176:179], v147 offset:35840
	ds_read_b128 v[180:183], v147 offset:36864
	ds_read_b128 v[184:187], v147 offset:37888
	ds_read_b128 v[188:191], v147 offset:38912
	ds_read_b128 v[212:215], v147 offset:39936
	global_load_lds_dwordx4 v130, s[16:17]
	s_mov_b32 m0, s43
	s_nop 0
	global_load_lds_dwordx4 v132, s[16:17]
	s_waitcnt lgkmcnt(8)
	s_barrier
	s_waitcnt lgkmcnt(0)
	s_setprio 1
	s_waitcnt lgkmcnt(0)
	v_mfma_f32_16x16x32_bf16 v[126:129], v[148:151], v[164:167], v[126:129]
	v_mfma_f32_16x16x32_bf16 v[122:125], v[156:159], v[164:167], v[122:125]
	v_mfma_f32_16x16x32_bf16 v[110:113], v[148:151], v[172:175], v[110:113]
	v_mfma_f32_16x16x32_bf16 v[106:109], v[156:159], v[172:175], v[106:109]
	v_mfma_f32_16x16x32_bf16 v[94:97], v[148:151], v[180:183], v[94:97]
	v_mfma_f32_16x16x32_bf16 v[90:93], v[156:159], v[180:183], v[90:93]
	v_mfma_f32_16x16x32_bf16 v[78:81], v[148:151], v[188:191], v[78:81]
	v_mfma_f32_16x16x32_bf16 v[74:77], v[156:159], v[188:191], v[74:77]
	v_mfma_f32_16x16x32_bf16 v[126:129], v[152:155], v[168:171], v[126:129]
	v_mfma_f32_16x16x32_bf16 v[122:125], v[160:163], v[168:171], v[122:125]
	v_mfma_f32_16x16x32_bf16 v[110:113], v[152:155], v[176:179], v[110:113]
	v_mfma_f32_16x16x32_bf16 v[106:109], v[160:163], v[176:179], v[106:109]
	v_mfma_f32_16x16x32_bf16 v[94:97], v[152:155], v[184:187], v[94:97]
	v_mfma_f32_16x16x32_bf16 v[90:93], v[160:163], v[184:187], v[90:93]
	v_mfma_f32_16x16x32_bf16 v[78:81], v[152:155], v[212:215], v[78:81]
	v_mfma_f32_16x16x32_bf16 v[74:77], v[160:163], v[212:215], v[74:77]
	s_setprio 0
	s_barrier
	s_add_i32 s16, 0, 0x1c000
	s_add_i32 s17, s20, s18
	v_add_u32_e32 v195, s16, v146
	s_add_i32 m0, s17, 0xffffff80
	ds_read_b128 v[216:219], v195
	ds_read_b128 v[220:223], v195 offset:1024
	ds_read_b128 v[224:227], v195 offset:2048
	ds_read_b128 v[228:231], v195 offset:3072
	global_load_lds_dwordx4 v0, s[12:13] offset:128
	s_add_i32 m0, s17, 0x1f80
	s_nop 0
	global_load_lds_dwordx4 v134, s[12:13] offset:128
	s_barrier
; #define PG8_STAGE(bufoff, gbase, voff) do { _Pragma("unroll") for (int _i = 0; _i < 2; ++_i) \
;     __builtin_amdgcn_global_load_lds((const unsigned*)((const char*)(gbase) + (voff)[_i]), (LAS unsigned*)(lds + (bufoff) + ldsw + _i * 8192), 16, 0, 0); } while (0)
; #define PG8_LDA(dst, b, h) do { _Pragma("unroll") for (int m = 0; m < 4; ++m) _Pragma("unroll") for (int k = 0; k < 2; ++k) dst[m][k] = *(const LAS bf16x8*)(lds + PG8_SA(b, h) + aoff + m * 2048 + k * 1024); } while (0)
; #define PG8_MMA(ai, bj, At, Bt) do { __builtin_amdgcn_s_setprio(1); _Pragma("unroll") for (int m = 0; m < 4; ++m) _Pragma("unroll") for (int n = 0; n < 2; ++n) _Pragma("unroll") for (int k = 0; k < 2; ++k) \
;     acc[ai][bj][m][n] = __builtin_amdgcn_mfma_f32_16x16x32_bf16(Bt[n][k], At[m][k], acc[ai][bj][m][n], 0, 0, 0); __builtin_amdgcn_s_setprio(0); } while (0)
; #define PG8_WAIT_V(n) asm volatile("s_waitcnt vmcnt(" #n ")" ::: "memory")
; #define PG8_WAIT_L(n) asm volatile("s_waitcnt lgkmcnt(" #n ")" ::: "memory")
; #define PG8_BAR __builtin_amdgcn_s_barrier()
; #define PG8_SCHED __builtin_amdgcn_sched_barrier(0)
; template <class Epi, bool SPLITA = false>
; __device__ __forceinline__ void gemm_phase(const int tid, LAS unsigned char* lds, const Gemm g, const Order& S, const Epi& E) {
;     ...
;       PG8_BAR; PG8_WAIT_L(0); PG8_MMA(0, 1, At, B1); PG8_BAR;
;       PG8_LDA(At, 1, 1); PG8_STAGE(PG8_SA(1, 0), a3, voffA);
;       PG8_BAR; PG8_WAIT_L(0); PG8_MMA(1, 0, At, B0); PG8_BAR; PG8_SCHED;
;       PG8_STAGE(PG8_SB(1, 1), b3 + hstepB, voffB);
;       PG8_WAIT_V(6); PG8_BAR; PG8_MMA(1, 1, At, B1); PG8_BAR;
;     }
	s_waitcnt lgkmcnt(0)
	s_setprio 1
	s_waitcnt lgkmcnt(0)
	v_mfma_f32_16x16x32_bf16 v[118:121], v[216:219], v[164:167], v[118:121]
	v_mfma_f32_16x16x32_bf16 v[114:117], v[224:227], v[164:167], v[114:117]
	v_mfma_f32_16x16x32_bf16 v[102:105], v[216:219], v[172:175], v[102:105]
	v_mfma_f32_16x16x32_bf16 v[98:101], v[224:227], v[172:175], v[98:101]
	v_mfma_f32_16x16x32_bf16 v[86:89], v[216:219], v[180:183], v[86:89]
	v_mfma_f32_16x16x32_bf16 v[82:85], v[224:227], v[180:183], v[82:85]
	v_mfma_f32_16x16x32_bf16 v[70:73], v[216:219], v[188:191], v[70:73]
	v_mfma_f32_16x16x32_bf16 v[66:69], v[224:227], v[188:191], v[66:69]
	v_mfma_f32_16x16x32_bf16 v[118:121], v[220:223], v[168:171], v[118:121]
	v_mfma_f32_16x16x32_bf16 v[114:117], v[228:231], v[168:171], v[114:117]
	v_mfma_f32_16x16x32_bf16 v[102:105], v[220:223], v[176:179], v[102:105]
	v_mfma_f32_16x16x32_bf16 v[98:101], v[228:231], v[176:179], v[98:101]
	v_mfma_f32_16x16x32_bf16 v[86:89], v[220:223], v[184:187], v[86:89]
	v_mfma_f32_16x16x32_bf16 v[82:85], v[228:231], v[184:187], v[82:85]
	v_mfma_f32_16x16x32_bf16 v[70:73], v[220:223], v[212:215], v[70:73]
	v_mfma_f32_16x16x32_bf16 v[66:69], v[228:231], v[212:215], v[66:69]
	s_setprio 0
	s_mov_b32 m0, s46
	s_barrier
	ds_read_b128 v[164:167], v147 offset:49152
	ds_read_b128 v[168:171], v147 offset:50176
	ds_read_b128 v[172:175], v147 offset:51200
	ds_read_b128 v[176:179], v147 offset:52224
	ds_read_b128 v[180:183], v147 offset:53248
	ds_read_b128 v[184:187], v147 offset:54272
	ds_read_b128 v[188:191], v147 offset:55296
	ds_read_b128 v[212:215], v147 offset:56320
	global_load_lds_dwordx4 v130, s[14:15]
	s_mov_b32 m0, s47
	s_nop 0
	global_load_lds_dwordx4 v132, s[14:15]
	s_barrier
	s_waitcnt lgkmcnt(0)
	s_setprio 1
	s_waitcnt lgkmcnt(0)
	v_mfma_f32_16x16x32_bf16 v[62:65], v[148:151], v[164:167], v[62:65]
	v_mfma_f32_16x16x32_bf16 v[58:61], v[156:159], v[164:167], v[58:61]
	v_mfma_f32_16x16x32_bf16 v[46:49], v[148:151], v[172:175], v[46:49]
	v_mfma_f32_16x16x32_bf16 v[42:45], v[156:159], v[172:175], v[42:45]
	v_mfma_f32_16x16x32_bf16 v[30:33], v[148:151], v[180:183], v[30:33]
	v_mfma_f32_16x16x32_bf16 v[26:29], v[156:159], v[180:183], v[26:29]
	v_mfma_f32_16x16x32_bf16 v[14:17], v[148:151], v[188:191], v[14:17]
	v_mfma_f32_16x16x32_bf16 v[10:13], v[156:159], v[188:191], v[10:13]
	v_mfma_f32_16x16x32_bf16 v[62:65], v[152:155], v[168:171], v[62:65]
	v_mfma_f32_16x16x32_bf16 v[58:61], v[160:163], v[168:171], v[58:61]
	v_mfma_f32_16x16x32_bf16 v[46:49], v[152:155], v[176:179], v[46:49]
	v_mfma_f32_16x16x32_bf16 v[42:45], v[160:163], v[176:179], v[42:45]
	v_mfma_f32_16x16x32_bf16 v[30:33], v[152:155], v[184:187], v[30:33]
	v_mfma_f32_16x16x32_bf16 v[26:29], v[160:163], v[184:187], v[26:29]
	v_mfma_f32_16x16x32_bf16 v[14:17], v[152:155], v[212:215], v[14:17]
	v_mfma_f32_16x16x32_bf16 v[10:13], v[160:163], v[212:215], v[10:13]
	s_setprio 0
	s_barrier
	s_add_u32 s12, s12, 0x88080
	s_addc_u32 s13, s13, 0
	s_add_i32 s14, s16, s18
	s_mov_b32 m0, s14
	s_nop 0
	global_load_lds_dwordx4 v0, s[12:13]
	s_add_i32 m0, s14, 0x2000
	s_nop 0
	global_load_lds_dwordx4 v134, s[12:13]
	s_waitcnt vmcnt(6)
	s_barrier
	s_setprio 1
	v_mfma_f32_16x16x32_bf16 v[54:57], v[216:219], v[164:167], v[54:57]
	v_mfma_f32_16x16x32_bf16 v[50:53], v[224:227], v[164:167], v[50:53]
	v_mfma_f32_16x16x32_bf16 v[38:41], v[216:219], v[172:175], v[38:41]
	v_mfma_f32_16x16x32_bf16 v[34:37], v[224:227], v[172:175], v[34:37]
	v_mfma_f32_16x16x32_bf16 v[22:25], v[216:219], v[180:183], v[22:25]
	v_mfma_f32_16x16x32_bf16 v[18:21], v[224:227], v[180:183], v[18:21]
	v_mfma_f32_16x16x32_bf16 v[6:9], v[216:219], v[188:191], v[6:9]
	v_mfma_f32_16x16x32_bf16 v[2:5], v[224:227], v[188:191], v[2:5]
	v_mfma_f32_16x16x32_bf16 v[54:57], v[220:223], v[168:171], v[54:57]
	v_mfma_f32_16x16x32_bf16 v[50:53], v[228:231], v[168:171], v[50:53]
	v_mfma_f32_16x16x32_bf16 v[38:41], v[220:223], v[176:179], v[38:41]
	v_mfma_f32_16x16x32_bf16 v[34:37], v[228:231], v[176:179], v[34:37]
	v_mfma_f32_16x16x32_bf16 v[22:25], v[220:223], v[184:187], v[22:25]
	v_mfma_f32_16x16x32_bf16 v[18:21], v[228:231], v[184:187], v[18:21]
	v_mfma_f32_16x16x32_bf16 v[6:9], v[220:223], v[212:215], v[6:9]
	v_mfma_f32_16x16x32_bf16 v[2:5], v[228:231], v[212:215], v[2:5]
	s_setprio 0
	s_add_i32 s91, s91, 2
	s_add_u32 s10, s10, 0x100
	s_addc_u32 s11, s11, 0
	s_cmp_gt_u32 s91, 31
	s_barrier
	s_cbranch_scc0 .LBB0_328
	s_branch .Lpeel_exit_328

; __device__ __forceinline__ u32x4 pack8(const f32x4 v0, const f32x4 v1) { u32x4 w; w.x = cvtpk(v0[0], v0[1]); w.y = cvtpk(v0[2], v0[3]); w.z = cvtpk(v1[0], v1[1]); w.w = cvtpk(v1[2], v1[3]); return w; }
;   __device__ __forceinline__ void operator()(const Acc& acc, const Unit& u, int wr, int wc, int fr_, int fq_) const {
;     int fr = fr_, fq = fq_; asm volatile("" : "+v"(fr), "+v"(fq));
;     const int z = u.pn >> 2, b = z >> 4, k1 = z & 15, j0 = (u.pn & 3) * 256 + wc * 32 + 8 * fq;
;     const int r0 = u.pm * BM + wr * 64 + fr;
; #pragma unroll
;     for (int ai = 0; ai < 2; ++ai)
; #pragma unroll
;       for (int m = 0; m < 4; ++m) { const int k2 = r0 + ai * HALF + m * 16;
;         if (k2 < FN2) { bf16_t* rowp = F + (size_t)row_of(b, k1 + 16 * k2) * 1024 + j0;
; #pragma unroll
;           for (int bj = 0; bj < 2; ++bj) *(u32x4*)(rowp + bj * HALF) = pack8(acc[ai][bj][m][0], acc[ai][bj][m][1]); } }
.Lpeel_exit_328:
	s_lshl_b32 s10, s51, 8
	v_mov_b32_e32 v141, v145
	v_mov_b32_e32 v140, v144
	s_and_b32 s10, s10, 0x300
	s_or_b32 s10, s10, s45
	v_lshl_add_u32 v140, v140, 3, s10
	s_lshl_b32 s10, s52, 8
	s_ashr_i32 s8, s51, 6
	s_add_i32 s10, s10, s44
	s_bfe_u32 s9, s51, 0x40002
	v_add_u32_e32 v142, s10, v141
	s_lshl_b32 s10, s8, 14
	s_lshl_b32 s11, s8, 4
	s_movk_i32 s8, 0x401
	s_add_i32 s10, s10, -16
	s_add_i32 s11, s11, 0x8000
	v_ashrrev_i32_e32 v141, 31, v140
	v_cmp_gt_i32_e32 vcc, s8, v142
	v_lshl_or_b32 v143, v142, 4, s9
	s_and_saveexec_b64 s[8:9], vcc
	s_cbranch_execz .LBB0_331
	v_mov_b32_e32 v148, s10
	v_mov_b32_e32 v149, s11
	v_cmp_gt_i32_e32 vcc, 16, v143
	v_readlane_b32 s12, v255, 1
	v_readlane_b32 s13, v255, 2
	v_cndmask_b32_e32 v148, v148, v149, vcc
	v_add_u32_e32 v148, v148, v143
	v_ashrrev_i32_e32 v149, 31, v148
	v_lshlrev_b64 v[148:149], 11, v[148:149]
	v_lshl_add_u64 v[148:149], s[12:13], 0, v[148:149]
	v_lshl_add_u64 v[148:149], v[140:141], 1, v[148:149]
	v_cvt_pk_bf16_f32 v126, v126, v127
	v_cvt_pk_bf16_f32 v127, v128, v129
	v_cvt_pk_bf16_f32 v128, v122, v123
	v_cvt_pk_bf16_f32 v129, v124, v125
	v_cvt_pk_bf16_f32 v118, v118, v119
	v_cvt_pk_bf16_f32 v119, v120, v121
	v_cvt_pk_bf16_f32 v120, v114, v115
	v_cvt_pk_bf16_f32 v121, v116, v117
	global_store_dwordx4 v[148:149], v[126:129], off
	global_store_dwordx4 v[148:149], v[118:121], off offset:256

; #define PG8_STAGE(bufoff, gbase, voff) do { _Pragma("unroll") for (int _i = 0; _i < 2; ++_i) \
;     __builtin_amdgcn_global_load_lds((const unsigned*)((const char*)(gbase) + (voff)[_i]), (LAS unsigned*)(lds + (bufoff) + ldsw + _i * 8192), 16, 0, 0); } while (0)
; #define PG8_LDA(dst, b, h) do { _Pragma("unroll") for (int m = 0; m < 4; ++m) _Pragma("unroll") for (int k = 0; k < 2; ++k) dst[m][k] = *(const LAS bf16x8*)(lds + PG8_SA(b, h) + aoff + m * 2048 + k * 1024); } while (0)
; #define PG8_LDB(dst, b, h) do { _Pragma("unroll") for (int n = 0; n < 2; ++n) _Pragma("unroll") for (int k = 0; k < 2; ++k) dst[n][k] = *(const LAS bf16x8*)(lds + PG8_SB(b, h) + boff + n * 2048 + k * 1024); } while (0)
; #define PG8_MMA(ai, bj, At, Bt) do { __builtin_amdgcn_s_setprio(1); _Pragma("unroll") for (int m = 0; m < 4; ++m) _Pragma("unroll") for (int n = 0; n < 2; ++n) _Pragma("unroll") for (int k = 0; k < 2; ++k) \
;     acc[ai][bj][m][n] = __builtin_amdgcn_mfma_f32_16x16x32_bf16(Bt[n][k], At[m][k], acc[ai][bj][m][n], 0, 0, 0); __builtin_amdgcn_s_setprio(0); } while (0)
; template <class Epi, bool SPLITA = false>
; __device__ __forceinline__ void gemm_phase(const int tid, LAS unsigned char* lds, const Gemm g, const Order& S, const Epi& E) {
;     ...
;   Acc acc;
; #pragma unroll
;   for (int a = 0; a < 2; ++a)
; #pragma unroll
;     for (int b = 0; b < 2; ++b)
; #pragma unroll
;       for (int m = 0; m < 4; ++m)
; #pragma unroll
;         for (int n = 0; n < 2; ++n) acc[a][b][m][n] = (f32x4){0.f, 0.f, 0.f, 0.f};
;     ...
;     for (int t = 0; t < nt; t += 2) {
;       const bool last = (t == nt - 2);
;       if constexpr (SPLITA) { if (t == nt1) E.mid(acc, cur, wr, wc, fr, fq); }
;       const char* a1 = PG8_TA(t + 1);
;       const char* a2 = last ? nA : PG8_TA(t + 2); const char* b2 = last ? nB : cB + (size_t)(t + 2) * kstep;
;       const char* a3 = last ? nA + kstep : PG8_TA(t + 3); const char* b3 = b2 + kstep;
;       PG8_LDB(B0, 0, 0); PG8_SCHED; PG8_LDA(At, 0, 0); PG8_STAGE(PG8_SA(1, 1), a1 + hstepA, voffA);
;       PG8_WAIT_L(8); PG8_BAR; PG8_WAIT_L(0); PG8_MMA(0, 0, At, B0); PG8_BAR; PG8_SCHED;
;       PG8_LDB(B1, 0, 1); PG8_STAGE(PG8_SB(0, 0), b2, voffB);
;       PG8_BAR; PG8_WAIT_L(0); PG8_MMA(0, 1, At, B1); PG8_BAR;
;       PG8_LDA(At, 0, 1); PG8_STAGE(PG8_SA(0, 0), a2, voffA);
;       PG8_BAR; PG8_WAIT_L(0); PG8_MMA(1, 0, At, B0); PG8_BAR; PG8_SCHED;
.LBB0_398:
	v_mov_b32_e32 v125, 0
	s_andn2_b64 vcc, exec, s[2:3]
	v_mov_b32_e32 v124, v125
	v_mov_b32_e32 v123, v125
	v_mov_b32_e32 v122, v125
	v_mov_b32_e32 v129, v125
	v_mov_b32_e32 v128, v125
	v_mov_b32_e32 v127, v125
	v_mov_b32_e32 v126, v125
	v_mov_b32_e32 v113, v125
	v_mov_b32_e32 v112, v125
	v_mov_b32_e32 v111, v125
	v_mov_b32_e32 v110, v125
	v_mov_b32_e32 v109, v125
	v_mov_b32_e32 v108, v125
	v_mov_b32_e32 v107, v125
	v_mov_b32_e32 v106, v125
	v_mov_b32_e32 v97, v125
	v_mov_b32_e32 v96, v125
	v_mov_b32_e32 v95, v125
	v_mov_b32_e32 v94, v125
	v_mov_b32_e32 v93, v125
	v_mov_b32_e32 v92, v125
	v_mov_b32_e32 v91, v125
	v_mov_b32_e32 v90, v125
	v_mov_b32_e32 v81, v125
	v_mov_b32_e32 v80, v125
	v_mov_b32_e32 v79, v125
	v_mov_b32_e32 v78, v125
	v_mov_b32_e32 v77, v125
	v_mov_b32_e32 v76, v125
	v_mov_b32_e32 v75, v125
	v_mov_b32_e32 v74, v125
	v_mov_b32_e32 v121, v125
	v_mov_b32_e32 v120, v125
	v_mov_b32_e32 v119, v125
	v_mov_b32_e32 v118, v125
	v_mov_b32_e32 v117, v125
	v_mov_b32_e32 v116, v125
	v_mov_b32_e32 v115, v125
	v_mov_b32_e32 v114, v125
	v_mov_b32_e32 v105, v125
	v_mov_b32_e32 v104, v125
	v_mov_b32_e32 v103, v125
	v_mov_b32_e32 v102, v125
	v_mov_b32_e32 v101, v125
	v_mov_b32_e32 v100, v125
	v_mov_b32_e32 v99, v125
	v_mov_b32_e32 v98, v125
	v_mov_b32_e32 v89, v125
	v_mov_b32_e32 v88, v125
	v_mov_b32_e32 v87, v125
	v_mov_b32_e32 v86, v125
	v_mov_b32_e32 v85, v125
	v_mov_b32_e32 v84, v125
	v_mov_b32_e32 v83, v125
	v_mov_b32_e32 v82, v125
	v_mov_b32_e32 v73, v125
	v_mov_b32_e32 v72, v125
	v_mov_b32_e32 v71, v125
	v_mov_b32_e32 v70, v125
	v_mov_b32_e32 v69, v125
	v_mov_b32_e32 v68, v125
	v_mov_b32_e32 v67, v125
	v_mov_b32_e32 v66, v125
	v_mov_b32_e32 v65, v125
	v_mov_b32_e32 v64, v125
	v_mov_b32_e32 v63, v125
	v_mov_b32_e32 v62, v125
	v_mov_b32_e32 v61, v125
	v_mov_b32_e32 v60, v125
	v_mov_b32_e32 v59, v125
	v_mov_b32_e32 v58, v125
	v_mov_b32_e32 v49, v125
	v_mov_b32_e32 v48, v125
	v_mov_b32_e32 v47, v125
	v_mov_b32_e32 v46, v125
	v_mov_b32_e32 v45, v125
	v_mov_b32_e32 v44, v125
	v_mov_b32_e32 v43, v125
	v_mov_b32_e32 v42, v125
	v_mov_b32_e32 v33, v125
	v_mov_b32_e32 v32, v125
	v_mov_b32_e32 v31, v125
	v_mov_b32_e32 v30, v125
	v_mov_b32_e32 v29, v125
	v_mov_b32_e32 v28, v125
	v_mov_b32_e32 v27, v125
	v_mov_b32_e32 v26, v125
	v_mov_b32_e32 v17, v125
	v_mov_b32_e32 v16, v125
	v_mov_b32_e32 v15, v125
	v_mov_b32_e32 v14, v125
	v_mov_b32_e32 v13, v125
	v_mov_b32_e32 v12, v125
	v_mov_b32_e32 v11, v125
	v_mov_b32_e32 v10, v125
	v_mov_b32_e32 v57, v125
	v_mov_b32_e32 v56, v125
	v_mov_b32_e32 v55, v125
	v_mov_b32_e32 v54, v125
	v_mov_b32_e32 v53, v125
	v_mov_b32_e32 v52, v125
	v_mov_b32_e32 v51, v125
	v_mov_b32_e32 v50, v125
	v_mov_b32_e32 v41, v125
	v_mov_b32_e32 v40, v125
	v_mov_b32_e32 v39, v125
	v_mov_b32_e32 v38, v125
	v_mov_b32_e32 v37, v125
	v_mov_b32_e32 v36, v125
	v_mov_b32_e32 v35, v125
	v_mov_b32_e32 v34, v125
	v_mov_b32_e32 v25, v125
	v_mov_b32_e32 v24, v125
	v_mov_b32_e32 v23, v125
	v_mov_b32_e32 v22, v125
	v_mov_b32_e32 v21, v125
	v_mov_b32_e32 v20, v125
	v_mov_b32_e32 v19, v125
	v_mov_b32_e32 v18, v125
	v_mov_b32_e32 v9, v125
	v_mov_b32_e32 v8, v125
	v_mov_b32_e32 v7, v125
	v_mov_b32_e32 v6, v125
	v_mov_b32_e32 v5, v125
	v_mov_b32_e32 v4, v125
	v_mov_b32_e32 v3, v125
	v_mov_b32_e32 v2, v125
	s_cbranch_vccnz .LBB0_389
	s_add_u32 s9, s0, 0x80
	v_mov_b32_e32 v2, 0
	v_not_b32_e32 v196, 63
	s_addc_u32 s11, s1, 0
	v_lshl_add_u64 v[140:141], s[12:13], 0, v[136:137]
	v_lshl_add_u64 v[142:143], s[12:13], 0, v[138:139]
	s_mov_b32 s18, 0
	s_mov_b64 s[14:15], 0
	s_add_i32 s29, s18, 2
	s_add_u32 s16, s14, 0x100
	s_addc_u32 s17, s15, 0
	s_add_u32 s19, s12, s14
	s_addc_u32 s20, s13, s15
	s_add_u32 s21, s19, 0x100
	s_addc_u32 s22, s20, 0
	s_add_u32 s19, s19, 0x180
	s_addc_u32 s20, s20, 0
	s_add_i32 s23, 0, 0x10000
	v_add_u32_e32 v160, s23, v146
	ds_read_b128 v[148:151], v160
	ds_read_b128 v[152:155], v160 offset:1024
	ds_read_b128 v[156:159], v160 offset:2048
	ds_read_b128 v[160:163], v160 offset:3072
	s_cmp_eq_u32 s52, s18
	s_cselect_b32 s18, 0, s16
	s_cselect_b32 s41, s11, s20
	s_cselect_b32 s40, s9, s19
	s_cselect_b32 s19, 0, s17
	s_cselect_b32 s42, s0, s21
	s_cselect_b32 s43, s1, s22
	s_add_u32 s18, s6, s18
	s_addc_u32 s19, s7, s19
	v_lshl_add_u64 v[192:193], v[140:141], 0, s[14:15]
	s_add_i32 m0, s30, 0xc000
	ds_read_b128 v[164:167], v147
	ds_read_b128 v[168:171], v147 offset:1024
	ds_read_b128 v[172:175], v147 offset:2048
	ds_read_b128 v[176:179], v147 offset:3072
	ds_read_b128 v[180:183], v147 offset:4096
	ds_read_b128 v[184:187], v147 offset:5120
	ds_read_b128 v[188:191], v147 offset:6144
	ds_read_b128 v[212:215], v147 offset:7168
	global_load_lds_dwordx4 v[192:193], off
	v_lshl_add_u64 v[192:193], v[142:143], 0, s[14:15]
	s_add_i32 m0, s30, 0xe000
	s_nop 0
	global_load_lds_dwordx4 v[192:193], off
	s_waitcnt lgkmcnt(8)
	s_barrier
	s_waitcnt lgkmcnt(0)
	s_setprio 1
	s_waitcnt lgkmcnt(0)
	v_mfma_f32_16x16x32_bf16 v[122:125], v[148:151], v[164:167], 0
	v_mfma_f32_16x16x32_bf16 v[126:129], v[156:159], v[164:167], 0
	v_mfma_f32_16x16x32_bf16 v[110:113], v[148:151], v[172:175], 0
	v_mfma_f32_16x16x32_bf16 v[106:109], v[156:159], v[172:175], 0
	v_mfma_f32_16x16x32_bf16 v[94:97], v[148:151], v[180:183], 0
	v_mfma_f32_16x16x32_bf16 v[90:93], v[156:159], v[180:183], 0
	v_mfma_f32_16x16x32_bf16 v[78:81], v[148:151], v[188:191], 0
	v_mfma_f32_16x16x32_bf16 v[74:77], v[156:159], v[188:191], 0
	v_mfma_f32_16x16x32_bf16 v[122:125], v[152:155], v[168:171], v[122:125]
	v_mfma_f32_16x16x32_bf16 v[126:129], v[160:163], v[168:171], v[126:129]
	v_mfma_f32_16x16x32_bf16 v[110:113], v[152:155], v[176:179], v[110:113]
	v_mfma_f32_16x16x32_bf16 v[106:109], v[160:163], v[176:179], v[106:109]
	v_mfma_f32_16x16x32_bf16 v[94:97], v[152:155], v[184:187], v[94:97]
	v_mfma_f32_16x16x32_bf16 v[90:93], v[160:163], v[184:187], v[90:93]
	v_mfma_f32_16x16x32_bf16 v[78:81], v[152:155], v[212:215], v[78:81]
	v_mfma_f32_16x16x32_bf16 v[74:77], v[160:163], v[212:215], v[74:77]
	s_setprio 0
	s_barrier
; #define PG8_STAGE(bufoff, gbase, voff) do { _Pragma("unroll") for (int _i = 0; _i < 2; ++_i) \
;     __builtin_amdgcn_global_load_lds((const unsigned*)((const char*)(gbase) + (voff)[_i]), (LAS unsigned*)(lds + (bufoff) + ldsw + _i * 8192), 16, 0, 0); } while (0)
; #define PG8_LDA(dst, b, h) do { _Pragma("unroll") for (int m = 0; m < 4; ++m) _Pragma("unroll") for (int k = 0; k < 2; ++k) dst[m][k] = *(const LAS bf16x8*)(lds + PG8_SA(b, h) + aoff + m * 2048 + k * 1024); } while (0)
; #define PG8_LDB(dst, b, h) do { _Pragma("unroll") for (int n = 0; n < 2; ++n) _Pragma("unroll") for (int k = 0; k < 2; ++k) dst[n][k] = *(const LAS bf16x8*)(lds + PG8_SB(b, h) + boff + n * 2048 + k * 1024); } while (0)
; #define PG8_MMA(ai, bj, At, Bt) do { __builtin_amdgcn_s_setprio(1); _Pragma("unroll") for (int m = 0; m < 4; ++m) _Pragma("unroll") for (int n = 0; n < 2; ++n) _Pragma("unroll") for (int k = 0; k < 2; ++k) \
;     acc[ai][bj][m][n] = __builtin_amdgcn_mfma_f32_16x16x32_bf16(Bt[n][k], At[m][k], acc[ai][bj][m][n], 0, 0, 0); __builtin_amdgcn_s_setprio(0); } while (0)
; #define PG8_WAIT_V(n) asm volatile("s_waitcnt vmcnt(" #n ")" ::: "memory")
; #define PG8_WAIT_L(n) asm volatile("s_waitcnt lgkmcnt(" #n ")" ::: "memory")
; #define PG8_BAR __builtin_amdgcn_s_barrier()
; #define PG8_SCHED __builtin_amdgcn_sched_barrier(0)
; template <class Epi, bool SPLITA = false>
; __device__ __forceinline__ void gemm_phase(const int tid, LAS unsigned char* lds, const Gemm g, const Order& S, const Epi& E) {
;     ...
;       PG8_BAR; PG8_WAIT_L(0); PG8_MMA(0, 1, At, B1); PG8_BAR;
;       PG8_LDA(At, 0, 1); PG8_STAGE(PG8_SA(0, 0), a2, voffA);
;       PG8_BAR; PG8_WAIT_L(0); PG8_MMA(1, 0, At, B0); PG8_BAR; PG8_SCHED;
;       PG8_STAGE(PG8_SB(0, 1), b2 + hstepB, voffB);
;       PG8_WAIT_V(6); PG8_BAR; PG8_MMA(1, 1, At, B1); PG8_BAR;
;       PG8_LDB(B0, 1, 0); PG8_SCHED; PG8_LDA(At, 1, 0); PG8_STAGE(PG8_SA(0, 1), a2 + hstepA, voffA);
;       PG8_WAIT_L(8); PG8_BAR; PG8_WAIT_L(0); PG8_MMA(0, 0, At, B0); PG8_BAR; PG8_SCHED;
;       PG8_LDB(B1, 1, 1); PG8_STAGE(PG8_SB(1, 0), b3, voffB);
;       PG8_BAR; PG8_WAIT_L(0); PG8_MMA(0, 1, At, B1); PG8_BAR;
	s_add_i32 s20, 0, 0x14000
	v_add_u32_e32 v192, s20, v146
	s_add_i32 s14, s23, s28
	ds_read_b128 v[216:219], v192
	ds_read_b128 v[220:223], v192 offset:1024
	ds_read_b128 v[224:227], v192 offset:2048
	ds_read_b128 v[228:231], v192 offset:3072
	s_mov_b32 m0, s14
	s_nop 0
	global_load_lds_dwordx4 v134, s[18:19]
	s_add_i32 m0, s14, 0x2000
	s_nop 0
	global_load_lds_dwordx4 v130, s[18:19]
	s_barrier
	s_waitcnt lgkmcnt(0)
	s_setprio 1
	s_waitcnt lgkmcnt(0)
	v_mfma_f32_16x16x32_bf16 v[118:121], v[216:219], v[164:167], 0
	v_mfma_f32_16x16x32_bf16 v[114:117], v[224:227], v[164:167], 0
	v_mfma_f32_16x16x32_bf16 v[102:105], v[216:219], v[172:175], 0
	v_mfma_f32_16x16x32_bf16 v[98:101], v[224:227], v[172:175], 0
	v_mfma_f32_16x16x32_bf16 v[86:89], v[216:219], v[180:183], 0
	v_mfma_f32_16x16x32_bf16 v[82:85], v[224:227], v[180:183], 0
	v_mfma_f32_16x16x32_bf16 v[70:73], v[216:219], v[188:191], 0
	v_mfma_f32_16x16x32_bf16 v[66:69], v[224:227], v[188:191], 0
	v_mfma_f32_16x16x32_bf16 v[118:121], v[220:223], v[168:171], v[118:121]
	v_mfma_f32_16x16x32_bf16 v[114:117], v[228:231], v[168:171], v[114:117]
	v_mfma_f32_16x16x32_bf16 v[102:105], v[220:223], v[176:179], v[102:105]
	v_mfma_f32_16x16x32_bf16 v[98:101], v[228:231], v[176:179], v[98:101]
	v_mfma_f32_16x16x32_bf16 v[86:89], v[220:223], v[184:187], v[86:89]
	v_mfma_f32_16x16x32_bf16 v[82:85], v[228:231], v[184:187], v[82:85]
	v_mfma_f32_16x16x32_bf16 v[70:73], v[220:223], v[212:215], v[70:73]
	v_mfma_f32_16x16x32_bf16 v[66:69], v[228:231], v[212:215], v[66:69]
	s_setprio 0
	s_mov_b32 m0, s30
	s_barrier
	ds_read_b128 v[164:167], v147 offset:16384
	ds_read_b128 v[168:171], v147 offset:17408
	ds_read_b128 v[172:175], v147 offset:18432
	ds_read_b128 v[176:179], v147 offset:19456
	ds_read_b128 v[180:183], v147 offset:20480
	ds_read_b128 v[184:187], v147 offset:21504
	ds_read_b128 v[188:191], v147 offset:22528
	ds_read_b128 v[212:215], v147 offset:23552
	global_load_lds_dwordx4 v0, s[42:43]
	s_mov_b32 m0, s31
	s_nop 0
	global_load_lds_dwordx4 v132, s[42:43]
	s_barrier
	s_waitcnt lgkmcnt(0)
	s_setprio 1
	s_waitcnt lgkmcnt(0)
	v_mfma_f32_16x16x32_bf16 v[62:65], v[148:151], v[164:167], 0
	v_mfma_f32_16x16x32_bf16 v[58:61], v[156:159], v[164:167], 0
	v_mfma_f32_16x16x32_bf16 v[46:49], v[148:151], v[172:175], 0
	v_mfma_f32_16x16x32_bf16 v[42:45], v[156:159], v[172:175], 0
	v_mfma_f32_16x16x32_bf16 v[30:33], v[148:151], v[180:183], 0
	v_mfma_f32_16x16x32_bf16 v[26:29], v[156:159], v[180:183], 0
	v_mfma_f32_16x16x32_bf16 v[14:17], v[148:151], v[188:191], 0
	v_mfma_f32_16x16x32_bf16 v[10:13], v[156:159], v[188:191], 0
	v_mfma_f32_16x16x32_bf16 v[62:65], v[152:155], v[168:171], v[62:65]
	v_mfma_f32_16x16x32_bf16 v[58:61], v[160:163], v[168:171], v[58:61]
	v_mfma_f32_16x16x32_bf16 v[46:49], v[152:155], v[176:179], v[46:49]
	v_mfma_f32_16x16x32_bf16 v[42:45], v[160:163], v[176:179], v[42:45]
	v_mfma_f32_16x16x32_bf16 v[30:33], v[152:155], v[184:187], v[30:33]
	v_mfma_f32_16x16x32_bf16 v[26:29], v[160:163], v[184:187], v[26:29]
	v_mfma_f32_16x16x32_bf16 v[14:17], v[152:155], v[212:215], v[14:17]
	v_mfma_f32_16x16x32_bf16 v[10:13], v[160:163], v[212:215], v[10:13]
	s_setprio 0
	s_barrier
	s_add_u32 s14, s18, 0x8000
	s_addc_u32 s15, s19, 0
	s_add_i32 s20, s20, s28
	s_mov_b32 m0, s20
	s_nop 0
	global_load_lds_dwordx4 v134, s[14:15]
	s_add_i32 m0, s20, 0x2000
	s_nop 0
	global_load_lds_dwordx4 v130, s[14:15]
	s_waitcnt vmcnt(6)
	s_barrier
	s_setprio 1
	v_mfma_f32_16x16x32_bf16 v[54:57], v[216:219], v[164:167], 0
	v_mfma_f32_16x16x32_bf16 v[50:53], v[224:227], v[164:167], 0
	v_mfma_f32_16x16x32_bf16 v[38:41], v[216:219], v[172:175], 0
	v_mfma_f32_16x16x32_bf16 v[34:37], v[224:227], v[172:175], 0
	v_mfma_f32_16x16x32_bf16 v[22:25], v[216:219], v[180:183], 0
	v_mfma_f32_16x16x32_bf16 v[18:21], v[224:227], v[180:183], 0
	v_mfma_f32_16x16x32_bf16 v[6:9], v[216:219], v[188:191], 0
	v_mfma_f32_16x16x32_bf16 v[2:5], v[224:227], v[188:191], 0
	v_mfma_f32_16x16x32_bf16 v[54:57], v[220:223], v[168:171], v[54:57]
	v_mfma_f32_16x16x32_bf16 v[50:53], v[228:231], v[168:171], v[50:53]
	v_mfma_f32_16x16x32_bf16 v[38:41], v[220:223], v[176:179], v[38:41]
	v_mfma_f32_16x16x32_bf16 v[34:37], v[228:231], v[176:179], v[34:37]
	v_mfma_f32_16x16x32_bf16 v[22:25], v[220:223], v[184:187], v[22:25]
	v_mfma_f32_16x16x32_bf16 v[18:21], v[228:231], v[184:187], v[18:21]
	v_mfma_f32_16x16x32_bf16 v[6:9], v[220:223], v[212:215], v[6:9]
	v_mfma_f32_16x16x32_bf16 v[2:5], v[228:231], v[212:215], v[2:5]
	s_setprio 0
	s_add_i32 s20, 0, 0x18000
	v_add_u32_e32 v160, s20, v146
	s_barrier
	ds_read_b128 v[148:151], v160
	ds_read_b128 v[152:155], v160 offset:1024
	ds_read_b128 v[156:159], v160 offset:2048
	ds_read_b128 v[160:163], v160 offset:3072
	s_add_u32 s14, s42, 0x40000
	s_addc_u32 s15, s43, 0
	s_mov_b32 m0, s44
	ds_read_b128 v[164:167], v147 offset:32768
	ds_read_b128 v[168:171], v147 offset:33792
	ds_read_b128 v[172:175], v147 offset:34816
	ds_read_b128 v[176:179], v147 offset:35840
	ds_read_b128 v[180:183], v147 offset:36864
	ds_read_b128 v[184:187], v147 offset:37888
	ds_read_b128 v[188:191], v147 offset:38912
	ds_read_b128 v[212:215], v147 offset:39936
	global_load_lds_dwordx4 v0, s[14:15]
	s_mov_b32 m0, s45
	s_nop 0
	global_load_lds_dwordx4 v132, s[14:15]
	s_waitcnt lgkmcnt(8)
	s_barrier
; #define PG8_STAGE(bufoff, gbase, voff) do { _Pragma("unroll") for (int _i = 0; _i < 2; ++_i) \
;     __builtin_amdgcn_global_load_lds((const unsigned*)((const char*)(gbase) + (voff)[_i]), (LAS unsigned*)(lds + (bufoff) + ldsw + _i * 8192), 16, 0, 0); } while (0)
; #define PG8_LDA(dst, b, h) do { _Pragma("unroll") for (int m = 0; m < 4; ++m) _Pragma("unroll") for (int k = 0; k < 2; ++k) dst[m][k] = *(const LAS bf16x8*)(lds + PG8_SA(b, h) + aoff + m * 2048 + k * 1024); } while (0)
; #define PG8_MMA(ai, bj, At, Bt) do { __builtin_amdgcn_s_setprio(1); _Pragma("unroll") for (int m = 0; m < 4; ++m) _Pragma("unroll") for (int n = 0; n < 2; ++n) _Pragma("unroll") for (int k = 0; k < 2; ++k) \
;     acc[ai][bj][m][n] = __builtin_amdgcn_mfma_f32_16x16x32_bf16(Bt[n][k], At[m][k], acc[ai][bj][m][n], 0, 0, 0); __builtin_amdgcn_s_setprio(0); } while (0)
; #define PG8_WAIT_V(n) asm volatile("s_waitcnt vmcnt(" #n ")" ::: "memory")
; #define PG8_WAIT_L(n) asm volatile("s_waitcnt lgkmcnt(" #n ")" ::: "memory")
; #define PG8_BAR __builtin_amdgcn_s_barrier()
; #define PG8_SCHED __builtin_amdgcn_sched_barrier(0)
; template <class Epi, bool SPLITA = false>
; __device__ __forceinline__ void gemm_phase(const int tid, LAS unsigned char* lds, const Gemm g, const Order& S, const Epi& E) {
;     ...
;       PG8_BAR; PG8_WAIT_L(0); PG8_MMA(0, 1, At, B1); PG8_BAR;
;       PG8_LDA(At, 1, 1); PG8_STAGE(PG8_SA(1, 0), a3, voffA);
;       PG8_BAR; PG8_WAIT_L(0); PG8_MMA(1, 0, At, B0); PG8_BAR; PG8_SCHED;
;       PG8_STAGE(PG8_SB(1, 1), b3 + hstepB, voffB);
;       PG8_WAIT_V(6); PG8_BAR; PG8_MMA(1, 1, At, B1); PG8_BAR;
;     }
	s_waitcnt lgkmcnt(0)
	s_setprio 1
	s_waitcnt lgkmcnt(0)
	v_mfma_f32_16x16x32_bf16 v[122:125], v[148:151], v[164:167], v[122:125]
	v_mfma_f32_16x16x32_bf16 v[126:129], v[156:159], v[164:167], v[126:129]
	v_mfma_f32_16x16x32_bf16 v[110:113], v[148:151], v[172:175], v[110:113]
	v_mfma_f32_16x16x32_bf16 v[106:109], v[156:159], v[172:175], v[106:109]
	v_mfma_f32_16x16x32_bf16 v[94:97], v[148:151], v[180:183], v[94:97]
	v_mfma_f32_16x16x32_bf16 v[90:93], v[156:159], v[180:183], v[90:93]
	v_mfma_f32_16x16x32_bf16 v[78:81], v[148:151], v[188:191], v[78:81]
	v_mfma_f32_16x16x32_bf16 v[74:77], v[156:159], v[188:191], v[74:77]
	v_mfma_f32_16x16x32_bf16 v[122:125], v[152:155], v[168:171], v[122:125]
	v_mfma_f32_16x16x32_bf16 v[126:129], v[160:163], v[168:171], v[126:129]
	v_mfma_f32_16x16x32_bf16 v[110:113], v[152:155], v[176:179], v[110:113]
	v_mfma_f32_16x16x32_bf16 v[106:109], v[160:163], v[176:179], v[106:109]
	v_mfma_f32_16x16x32_bf16 v[94:97], v[152:155], v[184:187], v[94:97]
	v_mfma_f32_16x16x32_bf16 v[90:93], v[160:163], v[184:187], v[90:93]
	v_mfma_f32_16x16x32_bf16 v[78:81], v[152:155], v[212:215], v[78:81]
	v_mfma_f32_16x16x32_bf16 v[74:77], v[160:163], v[212:215], v[74:77]
	s_setprio 0
	s_barrier
	s_add_i32 s21, 0, 0x1c000
	s_add_i32 s14, s20, s28
	v_add_u32_e32 v195, s21, v146
	s_add_i32 m0, s14, 0xffffff80
	ds_read_b128 v[216:219], v195
	ds_read_b128 v[220:223], v195 offset:1024
	ds_read_b128 v[224:227], v195 offset:2048
	ds_read_b128 v[228:231], v195 offset:3072
	global_load_lds_dwordx4 v134, s[18:19] offset:128
	s_add_i32 m0, s14, 0x1f80
	s_nop 0
	global_load_lds_dwordx4 v130, s[18:19] offset:128
	s_barrier
	s_waitcnt lgkmcnt(0)
	s_setprio 1
	s_waitcnt lgkmcnt(0)
	v_mfma_f32_16x16x32_bf16 v[118:121], v[216:219], v[164:167], v[118:121]
	v_mfma_f32_16x16x32_bf16 v[114:117], v[224:227], v[164:167], v[114:117]
	v_mfma_f32_16x16x32_bf16 v[102:105], v[216:219], v[172:175], v[102:105]
	v_mfma_f32_16x16x32_bf16 v[98:101], v[224:227], v[172:175], v[98:101]
	v_mfma_f32_16x16x32_bf16 v[86:89], v[216:219], v[180:183], v[86:89]
	v_mfma_f32_16x16x32_bf16 v[82:85], v[224:227], v[180:183], v[82:85]
	v_mfma_f32_16x16x32_bf16 v[70:73], v[216:219], v[188:191], v[70:73]
	v_mfma_f32_16x16x32_bf16 v[66:69], v[224:227], v[188:191], v[66:69]
	v_mfma_f32_16x16x32_bf16 v[118:121], v[220:223], v[168:171], v[118:121]
	v_mfma_f32_16x16x32_bf16 v[114:117], v[228:231], v[168:171], v[114:117]
	v_mfma_f32_16x16x32_bf16 v[102:105], v[220:223], v[176:179], v[102:105]
	v_mfma_f32_16x16x32_bf16 v[98:101], v[228:231], v[176:179], v[98:101]
	v_mfma_f32_16x16x32_bf16 v[86:89], v[220:223], v[184:187], v[86:89]
	v_mfma_f32_16x16x32_bf16 v[82:85], v[228:231], v[184:187], v[82:85]
	v_mfma_f32_16x16x32_bf16 v[70:73], v[220:223], v[212:215], v[70:73]
	v_mfma_f32_16x16x32_bf16 v[66:69], v[228:231], v[212:215], v[66:69]
	s_setprio 0
	s_mov_b32 m0, s49
	s_barrier
	ds_read_b128 v[164:167], v147 offset:49152
	ds_read_b128 v[168:171], v147 offset:50176
	ds_read_b128 v[172:175], v147 offset:51200
	ds_read_b128 v[176:179], v147 offset:52224
	ds_read_b128 v[180:183], v147 offset:53248
	ds_read_b128 v[184:187], v147 offset:54272
	ds_read_b128 v[188:191], v147 offset:55296
	ds_read_b128 v[212:215], v147 offset:56320
	global_load_lds_dwordx4 v0, s[40:41]
	s_mov_b32 m0, s51
	s_nop 0
	global_load_lds_dwordx4 v132, s[40:41]
	s_barrier
	s_waitcnt lgkmcnt(0)
	s_setprio 1
	s_waitcnt lgkmcnt(0)
	v_mfma_f32_16x16x32_bf16 v[62:65], v[148:151], v[164:167], v[62:65]
	v_mfma_f32_16x16x32_bf16 v[58:61], v[156:159], v[164:167], v[58:61]
	v_mfma_f32_16x16x32_bf16 v[46:49], v[148:151], v[172:175], v[46:49]
	v_mfma_f32_16x16x32_bf16 v[42:45], v[156:159], v[172:175], v[42:45]
	v_mfma_f32_16x16x32_bf16 v[30:33], v[148:151], v[180:183], v[30:33]
	v_mfma_f32_16x16x32_bf16 v[26:29], v[156:159], v[180:183], v[26:29]
	v_mfma_f32_16x16x32_bf16 v[14:17], v[148:151], v[188:191], v[14:17]
	v_mfma_f32_16x16x32_bf16 v[10:13], v[156:159], v[188:191], v[10:13]
	v_mfma_f32_16x16x32_bf16 v[62:65], v[152:155], v[168:171], v[62:65]
	v_mfma_f32_16x16x32_bf16 v[58:61], v[160:163], v[168:171], v[58:61]
	v_mfma_f32_16x16x32_bf16 v[46:49], v[152:155], v[176:179], v[46:49]
	v_mfma_f32_16x16x32_bf16 v[42:45], v[160:163], v[176:179], v[42:45]
	v_mfma_f32_16x16x32_bf16 v[30:33], v[152:155], v[184:187], v[30:33]
	v_mfma_f32_16x16x32_bf16 v[26:29], v[160:163], v[184:187], v[26:29]
	v_mfma_f32_16x16x32_bf16 v[14:17], v[152:155], v[212:215], v[14:17]
	v_mfma_f32_16x16x32_bf16 v[10:13], v[160:163], v[212:215], v[10:13]
	s_setprio 0
	s_barrier
	s_add_u32 s14, s18, 0x8080
	s_addc_u32 s15, s19, 0
	s_add_i32 s18, s21, s28
	s_mov_b32 m0, s18
	s_nop 0
	global_load_lds_dwordx4 v134, s[14:15]
	s_add_i32 m0, s18, 0x2000
	s_nop 0
	global_load_lds_dwordx4 v130, s[14:15]
	s_waitcnt vmcnt(6)
	s_barrier
	s_setprio 1
	v_mfma_f32_16x16x32_bf16 v[54:57], v[216:219], v[164:167], v[54:57]
	v_mfma_f32_16x16x32_bf16 v[50:53], v[224:227], v[164:167], v[50:53]
	v_mfma_f32_16x16x32_bf16 v[38:41], v[216:219], v[172:175], v[38:41]
	v_mfma_f32_16x16x32_bf16 v[34:37], v[224:227], v[172:175], v[34:37]
	v_mfma_f32_16x16x32_bf16 v[22:25], v[216:219], v[180:183], v[22:25]
	v_mfma_f32_16x16x32_bf16 v[18:21], v[224:227], v[180:183], v[18:21]
	v_mfma_f32_16x16x32_bf16 v[6:9], v[216:219], v[188:191], v[6:9]
	v_mfma_f32_16x16x32_bf16 v[2:5], v[224:227], v[188:191], v[2:5]
	v_mfma_f32_16x16x32_bf16 v[54:57], v[220:223], v[168:171], v[54:57]
	v_mfma_f32_16x16x32_bf16 v[50:53], v[228:231], v[168:171], v[50:53]
	v_mfma_f32_16x16x32_bf16 v[38:41], v[220:223], v[176:179], v[38:41]
	v_mfma_f32_16x16x32_bf16 v[34:37], v[228:231], v[176:179], v[34:37]
	v_mfma_f32_16x16x32_bf16 v[22:25], v[220:223], v[184:187], v[22:25]
	v_mfma_f32_16x16x32_bf16 v[18:21], v[228:231], v[184:187], v[18:21]
	v_mfma_f32_16x16x32_bf16 v[6:9], v[220:223], v[212:215], v[6:9]
	v_mfma_f32_16x16x32_bf16 v[2:5], v[228:231], v[212:215], v[2:5]
	s_setprio 0
	s_cmp_ge_i32 s29, s46
	s_mov_b64 s[14:15], s[16:17]
	s_mov_b32 s18, s29
	s_barrier
	s_cbranch_scc0 .LBB0_400
	s_branch .Lpeel_exit_400

; template <class Epi, bool SPLITA = false>
; __device__ __forceinline__ void gemm_phase(const int tid, LAS unsigned char* lds, const Gemm g, const Order& S, const Epi& E) {
;     ...
;     }
;     E(acc, cur, wr, wc, fr, fq);
;     if (!has_next) break;
.Lpeel_exit_400:
	s_mov_b64 s[20:21], s[34:35]
	v_mov_b32_e32 v219, v196
	s_branch .LBB0_389

; #define PG8_STAGE(bufoff, gbase, voff) do { _Pragma("unroll") for (int _i = 0; _i < 2; ++_i) \
;     __builtin_amdgcn_global_load_lds((const unsigned*)((const char*)(gbase) + (voff)[_i]), (LAS unsigned*)(lds + (bufoff) + ldsw + _i * 8192), 16, 0, 0); } while (0)
; #define PG8_LDA(dst, b, h) do { _Pragma("unroll") for (int m = 0; m < 4; ++m) _Pragma("unroll") for (int k = 0; k < 2; ++k) dst[m][k] = *(const LAS bf16x8*)(lds + PG8_SA(b, h) + aoff + m * 2048 + k * 1024); } while (0)
; #define PG8_LDB(dst, b, h) do { _Pragma("unroll") for (int n = 0; n < 2; ++n) _Pragma("unroll") for (int k = 0; k < 2; ++k) dst[n][k] = *(const LAS bf16x8*)(lds + PG8_SB(b, h) + boff + n * 2048 + k * 1024); } while (0)
; #define PG8_WAIT_L(n) asm volatile("s_waitcnt lgkmcnt(" #n ")" ::: "memory")
; #define PG8_BAR __builtin_amdgcn_s_barrier()
; #define PG8_SCHED __builtin_amdgcn_sched_barrier(0)
; template <class Epi, bool SPLITA = false>
; __device__ __forceinline__ void gemm_phase(const int tid, LAS unsigned char* lds, const Gemm g, const Order& S, const Epi& E) {
;     ...
;     const bool has_next = S.next(ui + 1, nxt);
;     const char* nA = has_next ? (const char*)g.A + (size_t)nxt.pm * tstepA + (size_t)nxt.pn * apn : cA; const char* nA2 = (SPLITA && has_next) ? (const char*)g.A2 + (size_t)nxt.pm * tstepA : cA2; const char* nB = has_next ? (const char*)g.Bt + (size_t)nxt.pn * tstepB : cB;
;     for (int t = 0; t < nt; t += 2) {
;       const bool last = (t == nt - 2);
;       if constexpr (SPLITA) { if (t == nt1) E.mid(acc, cur, wr, wc, fr, fq); }
;       const char* a1 = PG8_TA(t + 1);
;       const char* a2 = last ? nA : PG8_TA(t + 2); const char* b2 = last ? nB : cB + (size_t)(t + 2) * kstep;
;       const char* a3 = last ? nA + kstep : PG8_TA(t + 3); const char* b3 = b2 + kstep;
;       PG8_LDB(B0, 0, 0); PG8_SCHED; PG8_LDA(At, 0, 0); PG8_STAGE(PG8_SA(1, 1), a1 + hstepA, voffA);
;       PG8_WAIT_L(8); PG8_BAR; PG8_WAIT_L(0); PG8_MMA(0, 0, At, B0); PG8_BAR; PG8_SCHED;
;       PG8_LDB(B1, 0, 1); PG8_STAGE(PG8_SB(0, 0), b2, voffB);
;       PG8_BAR; PG8_WAIT_L(0); PG8_MMA(0, 1, At, B1); PG8_BAR;
;       PG8_LDA(At, 0, 1); PG8_STAGE(PG8_SA(0, 0), a2, voffA);
;       PG8_BAR; PG8_WAIT_L(0); PG8_MMA(1, 0, At, B0); PG8_BAR; PG8_SCHED;
.LBB0_462:
	v_mov_b64_e32 v[2:3], 0xd00
	s_ashr_i32 s11, s10, 31
	v_cmp_lt_i64_e32 vcc, s[12:13], v[2:3]
	s_lshl_b64 s[12:13], s[10:11], 20
	s_add_u32 s12, s86, s12
	s_addc_u32 s13, s87, s13
	s_and_b64 s[14:15], vcc, exec
	s_cselect_b32 s1, s13, s17
	s_cselect_b32 s11, s12, s16
	s_ashr_i32 s9, s8, 31
	s_lshl_b64 s[14:15], s[8:9], 20
	v_readlane_b32 s20, v255, 20
	v_readlane_b32 s21, v255, 21
	s_add_u32 s14, s20, s14
	s_addc_u32 s15, s21, s15
	s_and_b64 s[28:29], vcc, exec
	s_cselect_b32 s9, s15, s41
	s_cselect_b32 s28, s14, s40
	s_add_u32 s91, s11, 0x80
	s_addc_u32 s93, s1, 0
	s_add_u32 vcc_lo, s40, 0x100
	s_addc_u32 vcc_hi, s41, 0
	s_add_u32 s40, s16, 0x80080
	s_addc_u32 s41, s17, 0
	v_mov_b32_e32 v2, 0
	v_lshl_add_u64 v[58:59], s[40:41], 0, v[152:153]
	v_lshl_add_u64 v[60:61], s[40:41], 0, v[154:155]
	s_mov_b32 s4, -2
	s_mov_b64 s[40:41], 0
	s_waitcnt vmcnt(0)
	s_add_u32 s20, s16, s40
	s_addc_u32 s21, s17, s41
	s_add_u32 s22, s20, 0x100
	s_addc_u32 s23, s21, 0
	s_add_u32 s29, vcc_lo, s40
	s_addc_u32 s42, vcc_hi, s41
	s_add_u32 s20, s20, 0x180
	s_addc_u32 s21, s21, 0
	s_add_i32 s94, 0, 0x10000
	v_add_u32_e32 v156, s94, v182
	ds_read_b128 v[62:65], v156
	ds_read_b128 v[74:77], v156 offset:1024
	ds_read_b128 v[78:81], v156 offset:2048
	ds_read_b128 v[156:159], v156 offset:3072
	s_cmpk_eq_i32 s40, 0xf00
	s_cselect_b32 s49, s93, s21
	s_cselect_b32 s48, s91, s20
	s_cselect_b32 s43, s9, s42
	s_cselect_b32 s42, s28, s29
	s_cselect_b32 s55, s1, s23
	s_cselect_b32 s54, s11, s22
	v_lshl_add_u64 v[192:193], v[58:59], 0, s[40:41]
	s_add_i32 m0, s19, 0xc000
	ds_read_b128 v[160:163], v183
	ds_read_b128 v[164:167], v183 offset:1024
	ds_read_b128 v[168:171], v183 offset:2048
	ds_read_b128 v[172:175], v183 offset:3072
	ds_read_b128 v[176:179], v183 offset:4096
	ds_read_b128 v[184:187], v183 offset:5120
	ds_read_b128 v[188:191], v183 offset:6144
	ds_read_b128 v[212:215], v183 offset:7168
	global_load_lds_dwordx4 v[192:193], off
	v_lshl_add_u64 v[192:193], v[60:61], 0, s[40:41]
	s_add_i32 m0, s19, 0xe000
	s_nop 0
	global_load_lds_dwordx4 v[192:193], off
	s_waitcnt lgkmcnt(8)
	s_barrier
	s_waitcnt lgkmcnt(0)
	s_setprio 1
	s_waitcnt lgkmcnt(0)
	v_mfma_f32_16x16x32_bf16 v[142:145], v[62:65], v[160:163], 0
	v_mfma_f32_16x16x32_bf16 v[138:141], v[78:81], v[160:163], 0
	v_mfma_f32_16x16x32_bf16 v[126:129], v[62:65], v[168:171], 0
	v_mfma_f32_16x16x32_bf16 v[122:125], v[78:81], v[168:171], 0
	v_mfma_f32_16x16x32_bf16 v[110:113], v[62:65], v[176:179], 0
	v_mfma_f32_16x16x32_bf16 v[106:109], v[78:81], v[176:179], 0
	v_mfma_f32_16x16x32_bf16 v[94:97], v[62:65], v[188:191], 0
	v_mfma_f32_16x16x32_bf16 v[90:93], v[78:81], v[188:191], 0
	v_mfma_f32_16x16x32_bf16 v[142:145], v[74:77], v[164:167], v[142:145]
	v_mfma_f32_16x16x32_bf16 v[138:141], v[156:159], v[164:167], v[138:141]
	v_mfma_f32_16x16x32_bf16 v[126:129], v[74:77], v[172:175], v[126:129]
	v_mfma_f32_16x16x32_bf16 v[122:125], v[156:159], v[172:175], v[122:125]
	v_mfma_f32_16x16x32_bf16 v[110:113], v[74:77], v[184:187], v[110:113]
	v_mfma_f32_16x16x32_bf16 v[106:109], v[156:159], v[184:187], v[106:109]
	v_mfma_f32_16x16x32_bf16 v[94:97], v[74:77], v[212:215], v[94:97]
	v_mfma_f32_16x16x32_bf16 v[90:93], v[156:159], v[212:215], v[90:93]
	s_setprio 0
	s_barrier
	s_add_i32 s20, 0, 0x14000
	v_add_u32_e32 v192, s20, v182
	s_add_i32 s21, s94, s30
	ds_read_b128 v[216:219], v192
	ds_read_b128 v[220:223], v192 offset:1024
	ds_read_b128 v[224:227], v192 offset:2048
	ds_read_b128 v[228:231], v192 offset:3072
	s_mov_b32 m0, s21
	s_nop 0
	global_load_lds_dwordx4 v0, s[42:43]
	s_add_i32 m0, s21, 0x2000
	s_nop 0
	global_load_lds_dwordx4 v150, s[42:43]
	s_barrier
	s_waitcnt lgkmcnt(0)
	s_setprio 1
	s_waitcnt lgkmcnt(0)
	v_mfma_f32_16x16x32_bf16 v[134:137], v[216:219], v[160:163], 0
	v_mfma_f32_16x16x32_bf16 v[130:133], v[224:227], v[160:163], 0
	v_mfma_f32_16x16x32_bf16 v[118:121], v[216:219], v[168:171], 0
	v_mfma_f32_16x16x32_bf16 v[114:117], v[224:227], v[168:171], 0
	v_mfma_f32_16x16x32_bf16 v[102:105], v[216:219], v[176:179], 0
	v_mfma_f32_16x16x32_bf16 v[98:101], v[224:227], v[176:179], 0
	v_mfma_f32_16x16x32_bf16 v[86:89], v[216:219], v[188:191], 0
	v_mfma_f32_16x16x32_bf16 v[82:85], v[224:227], v[188:191], 0
	v_mfma_f32_16x16x32_bf16 v[134:137], v[220:223], v[164:167], v[134:137]
	v_mfma_f32_16x16x32_bf16 v[130:133], v[228:231], v[164:167], v[130:133]
	v_mfma_f32_16x16x32_bf16 v[118:121], v[220:223], v[172:175], v[118:121]
	v_mfma_f32_16x16x32_bf16 v[114:117], v[228:231], v[172:175], v[114:117]
	v_mfma_f32_16x16x32_bf16 v[102:105], v[220:223], v[184:187], v[102:105]
	v_mfma_f32_16x16x32_bf16 v[98:101], v[228:231], v[184:187], v[98:101]
	v_mfma_f32_16x16x32_bf16 v[86:89], v[220:223], v[212:215], v[86:89]
	v_mfma_f32_16x16x32_bf16 v[82:85], v[228:231], v[212:215], v[82:85]
	s_setprio 0
	s_mov_b32 m0, s19
	s_barrier
	ds_read_b128 v[160:163], v183 offset:16384
	ds_read_b128 v[164:167], v183 offset:17408
	ds_read_b128 v[168:171], v183 offset:18432
	ds_read_b128 v[172:175], v183 offset:19456
	ds_read_b128 v[176:179], v183 offset:20480
	ds_read_b128 v[184:187], v183 offset:21504
	ds_read_b128 v[188:191], v183 offset:22528
	ds_read_b128 v[212:215], v183 offset:23552
	global_load_lds_dwordx4 v146, s[54:55]
	s_mov_b32 m0, s31
	s_nop 0
	global_load_lds_dwordx4 v148, s[54:55]
	s_barrier
; #define PG8_STAGE(bufoff, gbase, voff) do { _Pragma("unroll") for (int _i = 0; _i < 2; ++_i) \
;     __builtin_amdgcn_global_load_lds((const unsigned*)((const char*)(gbase) + (voff)[_i]), (LAS unsigned*)(lds + (bufoff) + ldsw + _i * 8192), 16, 0, 0); } while (0)
; #define PG8_LDA(dst, b, h) do { _Pragma("unroll") for (int m = 0; m < 4; ++m) _Pragma("unroll") for (int k = 0; k < 2; ++k) dst[m][k] = *(const LAS bf16x8*)(lds + PG8_SA(b, h) + aoff + m * 2048 + k * 1024); } while (0)
; #define PG8_LDB(dst, b, h) do { _Pragma("unroll") for (int n = 0; n < 2; ++n) _Pragma("unroll") for (int k = 0; k < 2; ++k) dst[n][k] = *(const LAS bf16x8*)(lds + PG8_SB(b, h) + boff + n * 2048 + k * 1024); } while (0)
; #define PG8_MMA(ai, bj, At, Bt) do { __builtin_amdgcn_s_setprio(1); _Pragma("unroll") for (int m = 0; m < 4; ++m) _Pragma("unroll") for (int n = 0; n < 2; ++n) _Pragma("unroll") for (int k = 0; k < 2; ++k) \
;     acc[ai][bj][m][n] = __builtin_amdgcn_mfma_f32_16x16x32_bf16(Bt[n][k], At[m][k], acc[ai][bj][m][n], 0, 0, 0); __builtin_amdgcn_s_setprio(0); } while (0)
; #define PG8_WAIT_V(n) asm volatile("s_waitcnt vmcnt(" #n ")" ::: "memory")
; #define PG8_WAIT_L(n) asm volatile("s_waitcnt lgkmcnt(" #n ")" ::: "memory")
; #define PG8_BAR __builtin_amdgcn_s_barrier()
; #define PG8_SCHED __builtin_amdgcn_sched_barrier(0)
; template <class Epi, bool SPLITA = false>
; __device__ __forceinline__ void gemm_phase(const int tid, LAS unsigned char* lds, const Gemm g, const Order& S, const Epi& E) {
;     ...
;       PG8_BAR; PG8_WAIT_L(0); PG8_MMA(1, 0, At, B0); PG8_BAR; PG8_SCHED;
;       PG8_STAGE(PG8_SB(0, 1), b2 + hstepB, voffB);
;       PG8_WAIT_V(6); PG8_BAR; PG8_MMA(1, 1, At, B1); PG8_BAR;
;       PG8_LDB(B0, 1, 0); PG8_SCHED; PG8_LDA(At, 1, 0); PG8_STAGE(PG8_SA(0, 1), a2 + hstepA, voffA);
;       PG8_WAIT_L(8); PG8_BAR; PG8_WAIT_L(0); PG8_MMA(0, 0, At, B0); PG8_BAR; PG8_SCHED;
;       PG8_LDB(B1, 1, 1); PG8_STAGE(PG8_SB(1, 0), b3, voffB);
;       PG8_BAR; PG8_WAIT_L(0); PG8_MMA(0, 1, At, B1); PG8_BAR;
	s_waitcnt lgkmcnt(0)
	s_setprio 1
	s_waitcnt lgkmcnt(0)
	v_mfma_f32_16x16x32_bf16 v[70:73], v[62:65], v[160:163], 0
	v_mfma_f32_16x16x32_bf16 v[66:69], v[78:81], v[160:163], 0
	v_mfma_f32_16x16x32_bf16 v[46:49], v[62:65], v[168:171], 0
	v_mfma_f32_16x16x32_bf16 v[42:45], v[78:81], v[168:171], 0
	v_mfma_f32_16x16x32_bf16 v[30:33], v[62:65], v[176:179], 0
	v_mfma_f32_16x16x32_bf16 v[26:29], v[78:81], v[176:179], 0
	v_mfma_f32_16x16x32_bf16 v[14:17], v[62:65], v[188:191], 0
	v_mfma_f32_16x16x32_bf16 v[10:13], v[78:81], v[188:191], 0
	v_mfma_f32_16x16x32_bf16 v[70:73], v[74:77], v[164:167], v[70:73]
	v_mfma_f32_16x16x32_bf16 v[66:69], v[156:159], v[164:167], v[66:69]
	v_mfma_f32_16x16x32_bf16 v[46:49], v[74:77], v[172:175], v[46:49]
	v_mfma_f32_16x16x32_bf16 v[42:45], v[156:159], v[172:175], v[42:45]
	v_mfma_f32_16x16x32_bf16 v[30:33], v[74:77], v[184:187], v[30:33]
	v_mfma_f32_16x16x32_bf16 v[26:29], v[156:159], v[184:187], v[26:29]
	v_mfma_f32_16x16x32_bf16 v[14:17], v[74:77], v[212:215], v[14:17]
	v_mfma_f32_16x16x32_bf16 v[10:13], v[156:159], v[212:215], v[10:13]
	s_setprio 0
	s_barrier
	s_add_u32 s22, s42, 0x80000
	s_addc_u32 s23, s43, 0
	s_add_i32 s20, s20, s30
	s_mov_b32 m0, s20
	s_nop 0
	global_load_lds_dwordx4 v0, s[22:23]
	s_add_i32 m0, s20, 0x2000
	s_nop 0
	global_load_lds_dwordx4 v150, s[22:23]
	s_waitcnt vmcnt(6)
	s_barrier
	s_setprio 1
	v_mfma_f32_16x16x32_bf16 v[54:57], v[216:219], v[160:163], 0
	v_mfma_f32_16x16x32_bf16 v[50:53], v[224:227], v[160:163], 0
	v_mfma_f32_16x16x32_bf16 v[38:41], v[216:219], v[168:171], 0
	v_mfma_f32_16x16x32_bf16 v[34:37], v[224:227], v[168:171], 0
	v_mfma_f32_16x16x32_bf16 v[22:25], v[216:219], v[176:179], 0
	v_mfma_f32_16x16x32_bf16 v[18:21], v[224:227], v[176:179], 0
	v_mfma_f32_16x16x32_bf16 v[6:9], v[216:219], v[188:191], 0
	v_mfma_f32_16x16x32_bf16 v[2:5], v[224:227], v[188:191], 0
	v_mfma_f32_16x16x32_bf16 v[54:57], v[220:223], v[164:167], v[54:57]
	v_mfma_f32_16x16x32_bf16 v[50:53], v[228:231], v[164:167], v[50:53]
	v_mfma_f32_16x16x32_bf16 v[38:41], v[220:223], v[172:175], v[38:41]
	v_mfma_f32_16x16x32_bf16 v[34:37], v[228:231], v[172:175], v[34:37]
	v_mfma_f32_16x16x32_bf16 v[22:25], v[220:223], v[184:187], v[22:25]
	v_mfma_f32_16x16x32_bf16 v[18:21], v[228:231], v[184:187], v[18:21]
	v_mfma_f32_16x16x32_bf16 v[6:9], v[220:223], v[212:215], v[6:9]
	v_mfma_f32_16x16x32_bf16 v[2:5], v[228:231], v[212:215], v[2:5]
	s_setprio 0
	s_add_i32 s20, 0, 0x18000
	v_add_u32_e32 v156, s20, v182
	s_barrier
	ds_read_b128 v[62:65], v156
	ds_read_b128 v[74:77], v156 offset:1024
	ds_read_b128 v[78:81], v156 offset:2048
	ds_read_b128 v[156:159], v156 offset:3072
	s_add_u32 s22, s54, 0x80000
	s_addc_u32 s23, s55, 0
	s_mov_b32 m0, s44
	ds_read_b128 v[160:163], v183 offset:32768
	ds_read_b128 v[164:167], v183 offset:33792
	ds_read_b128 v[168:171], v183 offset:34816
	ds_read_b128 v[172:175], v183 offset:35840
	ds_read_b128 v[176:179], v183 offset:36864
	ds_read_b128 v[184:187], v183 offset:37888
	ds_read_b128 v[188:191], v183 offset:38912
	ds_read_b128 v[212:215], v183 offset:39936
	global_load_lds_dwordx4 v146, s[22:23]
	s_mov_b32 m0, s45
	s_nop 0
	global_load_lds_dwordx4 v148, s[22:23]
	s_waitcnt lgkmcnt(8)
	s_barrier
	s_waitcnt lgkmcnt(0)
	s_setprio 1
	s_waitcnt lgkmcnt(0)
	v_mfma_f32_16x16x32_bf16 v[142:145], v[62:65], v[160:163], v[142:145]
	v_mfma_f32_16x16x32_bf16 v[138:141], v[78:81], v[160:163], v[138:141]
	v_mfma_f32_16x16x32_bf16 v[126:129], v[62:65], v[168:171], v[126:129]
	v_mfma_f32_16x16x32_bf16 v[122:125], v[78:81], v[168:171], v[122:125]
	v_mfma_f32_16x16x32_bf16 v[110:113], v[62:65], v[176:179], v[110:113]
	v_mfma_f32_16x16x32_bf16 v[106:109], v[78:81], v[176:179], v[106:109]
	v_mfma_f32_16x16x32_bf16 v[94:97], v[62:65], v[188:191], v[94:97]
	v_mfma_f32_16x16x32_bf16 v[90:93], v[78:81], v[188:191], v[90:93]
	v_mfma_f32_16x16x32_bf16 v[142:145], v[74:77], v[164:167], v[142:145]
	v_mfma_f32_16x16x32_bf16 v[138:141], v[156:159], v[164:167], v[138:141]
	v_mfma_f32_16x16x32_bf16 v[126:129], v[74:77], v[172:175], v[126:129]
	v_mfma_f32_16x16x32_bf16 v[122:125], v[156:159], v[172:175], v[122:125]
	v_mfma_f32_16x16x32_bf16 v[110:113], v[74:77], v[184:187], v[110:113]
	v_mfma_f32_16x16x32_bf16 v[106:109], v[156:159], v[184:187], v[106:109]
	v_mfma_f32_16x16x32_bf16 v[94:97], v[74:77], v[212:215], v[94:97]
	v_mfma_f32_16x16x32_bf16 v[90:93], v[156:159], v[212:215], v[90:93]
	s_setprio 0
	s_barrier
; #define PG8_STAGE(bufoff, gbase, voff) do { _Pragma("unroll") for (int _i = 0; _i < 2; ++_i) \
;     __builtin_amdgcn_global_load_lds((const unsigned*)((const char*)(gbase) + (voff)[_i]), (LAS unsigned*)(lds + (bufoff) + ldsw + _i * 8192), 16, 0, 0); } while (0)
; #define PG8_LDA(dst, b, h) do { _Pragma("unroll") for (int m = 0; m < 4; ++m) _Pragma("unroll") for (int k = 0; k < 2; ++k) dst[m][k] = *(const LAS bf16x8*)(lds + PG8_SA(b, h) + aoff + m * 2048 + k * 1024); } while (0)
; #define PG8_MMA(ai, bj, At, Bt) do { __builtin_amdgcn_s_setprio(1); _Pragma("unroll") for (int m = 0; m < 4; ++m) _Pragma("unroll") for (int n = 0; n < 2; ++n) _Pragma("unroll") for (int k = 0; k < 2; ++k) \
;     acc[ai][bj][m][n] = __builtin_amdgcn_mfma_f32_16x16x32_bf16(Bt[n][k], At[m][k], acc[ai][bj][m][n], 0, 0, 0); __builtin_amdgcn_s_setprio(0); } while (0)
; #define PG8_WAIT_V(n) asm volatile("s_waitcnt vmcnt(" #n ")" ::: "memory")
; #define PG8_WAIT_L(n) asm volatile("s_waitcnt lgkmcnt(" #n ")" ::: "memory")
; #define PG8_BAR __builtin_amdgcn_s_barrier()
; #define PG8_SCHED __builtin_amdgcn_sched_barrier(0)
; template <class Epi, bool SPLITA = false>
; __device__ __forceinline__ void gemm_phase(const int tid, LAS unsigned char* lds, const Gemm g, const Order& S, const Epi& E) {
;     ...
;       PG8_BAR; PG8_WAIT_L(0); PG8_MMA(0, 1, At, B1); PG8_BAR;
;       PG8_LDA(At, 1, 1); PG8_STAGE(PG8_SA(1, 0), a3, voffA);
;       PG8_BAR; PG8_WAIT_L(0); PG8_MMA(1, 0, At, B0); PG8_BAR; PG8_SCHED;
;       PG8_STAGE(PG8_SB(1, 1), b3 + hstepB, voffB);
;       PG8_WAIT_V(6); PG8_BAR; PG8_MMA(1, 1, At, B1); PG8_BAR;
;     }
	s_add_i32 s21, 0, 0x1c000
	s_add_i32 s20, s20, s30
	v_add_u32_e32 v195, s21, v182
	s_add_i32 m0, s20, 0xffffff80
	ds_read_b128 v[216:219], v195
	ds_read_b128 v[220:223], v195 offset:1024
	ds_read_b128 v[224:227], v195 offset:2048
	ds_read_b128 v[228:231], v195 offset:3072
	global_load_lds_dwordx4 v0, s[42:43] offset:128
	s_add_i32 m0, s20, 0x1f80
	s_nop 0
	global_load_lds_dwordx4 v150, s[42:43] offset:128
	s_barrier
	s_waitcnt lgkmcnt(0)
	s_setprio 1
	s_waitcnt lgkmcnt(0)
	v_mfma_f32_16x16x32_bf16 v[134:137], v[216:219], v[160:163], v[134:137]
	v_mfma_f32_16x16x32_bf16 v[130:133], v[224:227], v[160:163], v[130:133]
	v_mfma_f32_16x16x32_bf16 v[118:121], v[216:219], v[168:171], v[118:121]
	v_mfma_f32_16x16x32_bf16 v[114:117], v[224:227], v[168:171], v[114:117]
	v_mfma_f32_16x16x32_bf16 v[102:105], v[216:219], v[176:179], v[102:105]
	v_mfma_f32_16x16x32_bf16 v[98:101], v[224:227], v[176:179], v[98:101]
	v_mfma_f32_16x16x32_bf16 v[86:89], v[216:219], v[188:191], v[86:89]
	v_mfma_f32_16x16x32_bf16 v[82:85], v[224:227], v[188:191], v[82:85]
	v_mfma_f32_16x16x32_bf16 v[134:137], v[220:223], v[164:167], v[134:137]
	v_mfma_f32_16x16x32_bf16 v[130:133], v[228:231], v[164:167], v[130:133]
	v_mfma_f32_16x16x32_bf16 v[118:121], v[220:223], v[172:175], v[118:121]
	v_mfma_f32_16x16x32_bf16 v[114:117], v[228:231], v[172:175], v[114:117]
	v_mfma_f32_16x16x32_bf16 v[102:105], v[220:223], v[184:187], v[102:105]
	v_mfma_f32_16x16x32_bf16 v[98:101], v[228:231], v[184:187], v[98:101]
	v_mfma_f32_16x16x32_bf16 v[86:89], v[220:223], v[212:215], v[86:89]
	v_mfma_f32_16x16x32_bf16 v[82:85], v[228:231], v[212:215], v[82:85]
	s_setprio 0
	s_mov_b32 m0, s51
	s_barrier
	ds_read_b128 v[160:163], v183 offset:49152
	ds_read_b128 v[164:167], v183 offset:50176
	ds_read_b128 v[168:171], v183 offset:51200
	ds_read_b128 v[172:175], v183 offset:52224
	ds_read_b128 v[176:179], v183 offset:53248
	ds_read_b128 v[184:187], v183 offset:54272
	ds_read_b128 v[188:191], v183 offset:55296
	ds_read_b128 v[212:215], v183 offset:56320
	global_load_lds_dwordx4 v146, s[48:49]
	s_mov_b32 m0, s52
	s_nop 0
	global_load_lds_dwordx4 v148, s[48:49]
	s_barrier
	s_waitcnt lgkmcnt(0)
	s_setprio 1
	s_waitcnt lgkmcnt(0)
	v_mfma_f32_16x16x32_bf16 v[70:73], v[62:65], v[160:163], v[70:73]
	v_mfma_f32_16x16x32_bf16 v[66:69], v[78:81], v[160:163], v[66:69]
	v_mfma_f32_16x16x32_bf16 v[46:49], v[62:65], v[168:171], v[46:49]
	v_mfma_f32_16x16x32_bf16 v[42:45], v[78:81], v[168:171], v[42:45]
	v_mfma_f32_16x16x32_bf16 v[30:33], v[62:65], v[176:179], v[30:33]
	v_mfma_f32_16x16x32_bf16 v[26:29], v[78:81], v[176:179], v[26:29]
	v_mfma_f32_16x16x32_bf16 v[14:17], v[62:65], v[188:191], v[14:17]
	v_mfma_f32_16x16x32_bf16 v[10:13], v[78:81], v[188:191], v[10:13]
	v_mfma_f32_16x16x32_bf16 v[70:73], v[74:77], v[164:167], v[70:73]
	v_mfma_f32_16x16x32_bf16 v[66:69], v[156:159], v[164:167], v[66:69]
	v_mfma_f32_16x16x32_bf16 v[46:49], v[74:77], v[172:175], v[46:49]
	v_mfma_f32_16x16x32_bf16 v[42:45], v[156:159], v[172:175], v[42:45]
	v_mfma_f32_16x16x32_bf16 v[30:33], v[74:77], v[184:187], v[30:33]
	v_mfma_f32_16x16x32_bf16 v[26:29], v[156:159], v[184:187], v[26:29]
	v_mfma_f32_16x16x32_bf16 v[14:17], v[74:77], v[212:215], v[14:17]
	v_mfma_f32_16x16x32_bf16 v[10:13], v[156:159], v[212:215], v[10:13]
	s_setprio 0
	s_barrier
	s_add_u32 s22, s42, 0x80080
	s_addc_u32 s23, s43, 0
	s_add_i32 s20, s21, s30
	s_mov_b32 m0, s20
	s_nop 0
	global_load_lds_dwordx4 v0, s[22:23]
	s_add_i32 m0, s20, 0x2000
	s_nop 0
	global_load_lds_dwordx4 v150, s[22:23]
	s_waitcnt vmcnt(6)
	s_barrier
	s_setprio 1
	v_mfma_f32_16x16x32_bf16 v[54:57], v[216:219], v[160:163], v[54:57]
	v_mfma_f32_16x16x32_bf16 v[50:53], v[224:227], v[160:163], v[50:53]
	v_mfma_f32_16x16x32_bf16 v[38:41], v[216:219], v[168:171], v[38:41]
	v_mfma_f32_16x16x32_bf16 v[34:37], v[224:227], v[168:171], v[34:37]
	v_mfma_f32_16x16x32_bf16 v[22:25], v[216:219], v[176:179], v[22:25]
	v_mfma_f32_16x16x32_bf16 v[18:21], v[224:227], v[176:179], v[18:21]
	v_mfma_f32_16x16x32_bf16 v[6:9], v[216:219], v[188:191], v[6:9]
	v_mfma_f32_16x16x32_bf16 v[2:5], v[224:227], v[188:191], v[2:5]
	v_mfma_f32_16x16x32_bf16 v[54:57], v[220:223], v[164:167], v[54:57]
	v_mfma_f32_16x16x32_bf16 v[50:53], v[228:231], v[164:167], v[50:53]
	v_mfma_f32_16x16x32_bf16 v[38:41], v[220:223], v[172:175], v[38:41]
	v_mfma_f32_16x16x32_bf16 v[34:37], v[228:231], v[172:175], v[34:37]
	v_mfma_f32_16x16x32_bf16 v[22:25], v[220:223], v[184:187], v[22:25]
	v_mfma_f32_16x16x32_bf16 v[18:21], v[228:231], v[184:187], v[18:21]
	v_mfma_f32_16x16x32_bf16 v[6:9], v[220:223], v[212:215], v[6:9]
	v_mfma_f32_16x16x32_bf16 v[2:5], v[228:231], v[212:215], v[2:5]
	s_setprio 0
	s_add_i32 s4, s4, 2
	s_add_u32 s40, s40, 0x100
	s_addc_u32 s41, s41, 0
	s_cmp_gt_u32 s4, 29
	s_barrier
	s_cbranch_scc0 .LBB0_463
	s_branch .Lpeel_exit_463

;   __device__ __forceinline__ void operator()(const Acc& acc, const Unit& u, int wr, int wc, int fr_, int fq_) const {
;     int fr = fr_, fq = fq_; asm volatile("" : "+v"(fr), "+v"(fq));
;     bf16_t* base; int ld, c0; bool gate = false;
;     if (u.pn < 4) { base = Q; ld = 1024; c0 = u.pn * 256; }
;     else if (u.pn == 4) { base = Kb; ld = 256; c0 = 0; }
;     else if (u.pn == 5) { base = Vb; ld = 256; c0 = 0; }
;     else if (u.pn < 10) { base = F; ld = 1024; c0 = (u.pn - 6) * 256; }
;     else { base = Gt; ld = 4096; c0 = (u.pn - 10) * 256; gate = true; }
;     const int row0 = u.pm * BM + wr * 64 + fr, col0 = c0 + wc * 32 + 8 * fq;
.Lpeel_exit_463:
	v_mov_b32_e32 v158, v181
	v_mov_b32_e32 v58, v180
	s_cmp_gt_i32 s0, 3
	s_mov_b64 s[48:49], -1
	s_mov_b64 s[20:21], s[34:35]
	s_cbranch_scc0 .LBB0_475
	s_cmp_lt_i32 s0, 5
	s_mov_b64 s[48:49], 0
	s_cbranch_scc1 .LBB0_474
	s_cmp_lg_u32 s0, 5
	s_mov_b64 s[54:55], -1
	s_cbranch_scc0 .LBB0_472
	s_lshl_b32 s4, s0, 8
	s_cmp_gt_u32 s0, 9
	s_mov_b64 s[40:41], -1
	s_mov_b64 s[42:43], -1
	s_cbranch_scc0 .LBB0_469
	s_add_i32 s1, s4, 0xfffff600
	s_mov_b64 s[42:43], 0
